# v30 + resid_norm_row loops (P6,P9,P15,P18): whole-row x/Y loads hoisted to row top (SGPR-base form), gains kept in LDS, vmcnt counted per chunk; bit-identical
# speedup vs baseline: 1.0079x; 1.0069x over previous
.LBB0_1688:
	s_cmp_gt_i32 s78, 6
	s_cselect_b64 s[2:3], -1, 0
	s_cmp_lt_i32 s79, 7
	s_cselect_b64 s[4:5], -1, 0
	s_or_b64 s[2:3], s[2:3], s[4:5]
	s_and_b64 vcc, exec, s[2:3]
	s_cbranch_vccnz .LBB0_1748
	s_mov_b64 s[2:3], s[0:1]
	s_getreg_b32 s4, hwreg(HW_REG_HW_ID, 0, 6)
	s_lshl_b32 s4, s4, 2
	s_and_b32 s4, s4, 0xfc
	s_add_i32 s4, s4, 0
	s_add_i32 s4, s4, 0x20200
	s_waitcnt vmcnt(0)
	v_mov_b32_e32 v0, s4
	ds_read_b32 v0, v0
	v_mbcnt_lo_u32_b32 v1, -1, 0
	v_mbcnt_hi_u32_b32 v1, -1, v1
	s_mov_b32 s4, s64
	s_waitcnt lgkmcnt(0)
	v_readfirstlane_b32 s5, v0
	s_nop 1
	v_lshl_add_u32 v0, s5, 6, v1
	s_load_dword s22, s[0:1], 0xa0
	v_readfirstlane_b32 s5, v0
	s_ashr_i32 s5, s5, 6
	s_add_u32 s8, s0, 0xa0
	s_addc_u32 s9, s1, 0
	s_lshl_b32 s4, s4, 3
	s_add_i32 s10, s4, s5
	s_cmpk_lt_i32 s10, 0x4000
	s_cbranch_scc0 .LBB0_1694
	s_load_dwordx2 s[12:13], s[2:3], 0x0
	s_load_dwordx4 s[4:7], s[2:3], 0x58
	v_and_b32_e32 v4, 63, v0
	v_lshlrev_b32_e32 v0, 4, v4
	v_mov_b32_e32 v1, 0
	v_or_b32_e32 v2, 0x1000, v0
	v_mov_b32_e32 v3, v1
	s_waitcnt lgkmcnt(0)
	v_lshl_add_u64 v[18:19], s[4:5], 0, v[2:3]
	v_or_b32_e32 v2, 0x1400, v0
	v_lshl_add_u64 v[20:21], s[4:5], 0, v[2:3]
	v_or_b32_e32 v2, 0x1800, v0
	v_lshl_add_u64 v[22:23], s[4:5], 0, v[2:3]
	v_or_b32_e32 v2, 0x1c00, v0
	v_lshl_add_u64 v[24:25], s[4:5], 0, v[2:3]
	v_or_b32_e32 v2, 0x2000, v0
	v_lshl_add_u64 v[26:27], s[4:5], 0, v[2:3]
	v_or_b32_e32 v2, 0x2400, v0
	v_lshl_add_u64 v[28:29], s[4:5], 0, v[2:3]
	v_or_b32_e32 v2, 0x2800, v0
	v_lshl_add_u64 v[30:31], s[4:5], 0, v[2:3]
	v_or_b32_e32 v2, 0x2c00, v0
	v_lshl_add_u64 v[32:33], s[4:5], 0, v[2:3]
	v_or_b32_e32 v2, 0x3000, v0
	v_lshl_add_u64 v[34:35], s[4:5], 0, v[2:3]
	v_or_b32_e32 v2, 0x3400, v0
	v_lshl_add_u64 v[16:17], s[4:5], 0, v[0:1]
	v_lshl_add_u64 v[36:37], s[4:5], 0, v[2:3]
	v_or_b32_e32 v2, 0x3800, v0
	v_lshl_add_u64 v[42:43], s[6:7], 0, v[0:1]
	v_mbcnt_lo_u32_b32 v1, -1, 0
	v_lshl_add_u64 v[38:39], s[4:5], 0, v[2:3]
	v_or_b32_e32 v2, 0x3c00, v0
	v_mbcnt_hi_u32_b32 v1, -1, v1
	v_lshl_add_u64 v[40:41], s[4:5], 0, v[2:3]
	v_and_b32_e32 v2, 64, v1
	v_add_u32_e32 v2, 64, v2
	v_xor_b32_e32 v3, 1, v1
	v_cmp_lt_i32_e32 vcc, v3, v2
	s_load_dwordx2 s[16:17], s[2:3], 0x90
	s_mov_b64 s[2:3], 0x1000
	v_cndmask_b32_e32 v3, v1, v3, vcc
	v_lshlrev_b32_e32 v126, 2, v3
	v_xor_b32_e32 v3, 2, v1
	v_cmp_lt_i32_e32 vcc, v3, v2
	v_lshl_add_u64 v[44:45], v[42:43], 0, s[2:3]
	s_mov_b64 s[2:3], 0x1400
	v_cndmask_b32_e32 v3, v1, v3, vcc
	v_lshl_add_u64 v[46:47], v[42:43], 0, s[2:3]
	s_mov_b64 s[2:3], 0x1800
	v_lshlrev_b32_e32 v127, 2, v3
	v_xor_b32_e32 v3, 4, v1
	v_lshl_add_u64 v[48:49], v[42:43], 0, s[2:3]
	s_mov_b64 s[2:3], 0x1c00
	v_cmp_lt_i32_e32 vcc, v3, v2
	v_lshl_add_u64 v[50:51], v[42:43], 0, s[2:3]
	s_mov_b64 s[2:3], 0x2000
	v_cndmask_b32_e32 v3, v1, v3, vcc
	v_lshl_add_u64 v[52:53], v[42:43], 0, s[2:3]
	s_mov_b64 s[2:3], 0x2400
	v_lshlrev_b32_e32 v128, 2, v3
	v_xor_b32_e32 v3, 8, v1
	v_lshl_add_u64 v[54:55], v[42:43], 0, s[2:3]
	s_mov_b64 s[2:3], 0x2800
	v_cmp_lt_i32_e32 vcc, v3, v2
	v_lshl_add_u64 v[56:57], v[42:43], 0, s[2:3]
	s_mov_b64 s[2:3], 0x2c00
	v_cndmask_b32_e32 v3, v1, v3, vcc
	v_lshl_add_u64 v[58:59], v[42:43], 0, s[2:3]
	s_mov_b64 s[2:3], 0x3000
	v_lshlrev_b32_e32 v129, 2, v3
	v_xor_b32_e32 v3, 16, v1
	s_lshl_b32 s14, s22, 3
	v_lshl_add_u64 v[60:61], v[42:43], 0, s[2:3]
	s_mov_b64 s[2:3], 0x3400
	v_cmp_lt_i32_e32 vcc, v3, v2
	s_cmp_lg_u64 s[6:7], 0
	v_lshl_add_u64 v[62:63], v[42:43], 0, s[2:3]
	s_mov_b64 s[2:3], 0x3800
	v_cndmask_b32_e32 v3, v1, v3, vcc
	s_cselect_b64 s[4:5], -1, 0
	v_lshl_add_u64 v[64:65], v[42:43], 0, s[2:3]
	s_mov_b64 s[2:3], 0x3c00
	v_lshlrev_b32_e32 v130, 2, v3
	v_xor_b32_e32 v3, 32, v1
	s_ashr_i32 s11, s10, 31
	v_lshl_add_u64 v[66:67], v[42:43], 0, s[2:3]
	v_cmp_lt_i32_e32 vcc, v3, v2
	s_lshl_b64 s[2:3], s[10:11], 8
	v_lshl_or_b32 v2, v4, 2, s2
	v_cndmask_b32_e32 v1, v1, v3, vcc
	v_mov_b32_e32 v3, s3
	s_mov_b64 s[2:3], 0x5dc00000
	v_lshl_add_u64 v[68:69], v[2:3], 0, s[2:3]
	s_lshl_b64 s[2:3], s[10:11], 13
	s_ashr_i32 s15, s14, 31
	v_lshl_or_b32 v70, v4, 3, s2
	v_mov_b32_e32 v71, s3
	s_lshl_b64 s[2:3], s[10:11], 14
	s_movk_i32 s23, 0x1000
	s_movk_i32 s24, 0x2000
	s_movk_i32 s25, 0x3000
	v_lshlrev_b32_e32 v131, 2, v1
	s_lshl_b64 s[6:7], s[14:15], 8
	s_lshl_b64 s[18:19], s[14:15], 13
	v_or_b32_e32 v72, s2, v0
	v_mov_b32_e32 v73, s3
	s_lshl_b64 s[20:21], s[14:15], 14
	v_mov_b32_e32 v132, 0x358637bd
	s_mov_b32 s11, 0xf800000
	v_mov_b32_e32 v133, 0x260
	s_mov_b32 s15, 0x2a000000
	s_mov_b32 s26, 0x32000000
	s_mov_b32 s27, 0x32001000
	s_mov_b32 s28, 0x2a001000
	s_mov_b32 s29, 0x32002000
	s_mov_b32 s30, 0x32003000
	s_movk_i32 s31, 0x7fff
	s_mov_b32 s33, 0x1a000000
	s_mov_b32 s34, 0x1a001000
	v_mov_b32_e32 v134, 1
	s_add_u32 s80, s12, 0x0
	s_addc_u32 s81, s13, 0
	s_add_u32 s82, s12, 0x1000
	s_addc_u32 s83, s13, 0
	s_add_u32 s84, s12, 0x2000
	s_addc_u32 s85, s13, 0
	s_add_u32 s86, s12, 0x3000
	s_addc_u32 s87, s13, 0
	s_add_u32 s88, s16, 0x2a000000
	s_addc_u32 s89, s17, 0
	s_add_u32 s90, s16, 0x2a001000
	s_addc_u32 s91, s17, 0
	v_mbcnt_lo_u32_b32 v150, -1, 0
	v_mbcnt_hi_u32_b32 v150, -1, v150
	v_lshlrev_b32_e32 v150, 4, v150
	global_load_dwordx4 v[160:163], v[16:17], off
	global_load_dwordx4 v[164:167], v[16:17], off offset:1024
	global_load_dwordx4 v[168:171], v[16:17], off offset:2048
	global_load_dwordx4 v[172:175], v[16:17], off offset:3072
	global_load_dwordx4 v[176:179], v[18:19], off
	global_load_dwordx4 v[180:183], v[20:21], off
	global_load_dwordx4 v[184:187], v[22:23], off
	global_load_dwordx4 v[188:191], v[24:25], off
	s_waitcnt vmcnt(0)
	ds_write_b128 v150, v[160:163] offset:0
	ds_write_b128 v150, v[164:167] offset:1024
	ds_write_b128 v150, v[168:171] offset:2048
	ds_write_b128 v150, v[172:175] offset:3072
	ds_write_b128 v150, v[176:179] offset:4096
	ds_write_b128 v150, v[180:183] offset:5120
	ds_write_b128 v150, v[184:187] offset:6144
	ds_write_b128 v150, v[188:191] offset:7168
	global_load_dwordx4 v[160:163], v[26:27], off
	global_load_dwordx4 v[164:167], v[28:29], off
	global_load_dwordx4 v[168:171], v[30:31], off
	global_load_dwordx4 v[172:175], v[32:33], off
	global_load_dwordx4 v[176:179], v[34:35], off
	global_load_dwordx4 v[180:183], v[36:37], off
	global_load_dwordx4 v[184:187], v[38:39], off
	global_load_dwordx4 v[188:191], v[40:41], off
	s_waitcnt vmcnt(0)
	ds_write_b128 v150, v[160:163] offset:8192
	ds_write_b128 v150, v[164:167] offset:9216
	ds_write_b128 v150, v[168:171] offset:10240
	ds_write_b128 v150, v[172:175] offset:11264
	ds_write_b128 v150, v[176:179] offset:12288
	ds_write_b128 v150, v[180:183] offset:13312
	ds_write_b128 v150, v[184:187] offset:14336
	ds_write_b128 v150, v[188:191] offset:15360
	global_load_dwordx4 v[160:163], v[42:43], off
	global_load_dwordx4 v[164:167], v[42:43], off offset:1024
	global_load_dwordx4 v[168:171], v[42:43], off offset:2048
	global_load_dwordx4 v[172:175], v[42:43], off offset:3072
	global_load_dwordx4 v[176:179], v[44:45], off
	global_load_dwordx4 v[180:183], v[46:47], off
	global_load_dwordx4 v[184:187], v[48:49], off
	global_load_dwordx4 v[188:191], v[50:51], off
	s_waitcnt vmcnt(0)
	ds_write_b128 v150, v[160:163] offset:16384
	ds_write_b128 v150, v[164:167] offset:17408
	ds_write_b128 v150, v[168:171] offset:18432
	ds_write_b128 v150, v[172:175] offset:19456
	ds_write_b128 v150, v[176:179] offset:20480
	ds_write_b128 v150, v[180:183] offset:21504
	ds_write_b128 v150, v[184:187] offset:22528
	ds_write_b128 v150, v[188:191] offset:23552
	global_load_dwordx4 v[160:163], v[52:53], off
	global_load_dwordx4 v[164:167], v[54:55], off
	global_load_dwordx4 v[168:171], v[56:57], off
	global_load_dwordx4 v[172:175], v[58:59], off
	global_load_dwordx4 v[176:179], v[60:61], off
	global_load_dwordx4 v[180:183], v[62:63], off
	global_load_dwordx4 v[184:187], v[64:65], off
	global_load_dwordx4 v[188:191], v[66:67], off
	s_waitcnt vmcnt(0)
	ds_write_b128 v150, v[160:163] offset:24576
	ds_write_b128 v150, v[164:167] offset:25600
	ds_write_b128 v150, v[168:171] offset:26624
	ds_write_b128 v150, v[172:175] offset:27648
	ds_write_b128 v150, v[176:179] offset:28672
	ds_write_b128 v150, v[180:183] offset:29696
	ds_write_b128 v150, v[184:187] offset:30720
	ds_write_b128 v150, v[188:191] offset:31744
	s_waitcnt lgkmcnt(0)
	s_branch .LBB0_1692

.LBB0_1692:
	s_waitcnt lgkmcnt(0)
	v_lshl_add_u64 v[4:5], s[16:17], 0, v[68:69]
	global_load_dword v8, v[4:5], off
	global_load_dwordx4 v[160:163], v72, s[80:81] offset:0
	global_load_dwordx2 v[224:225], v70, s[88:89] offset:0
	global_load_dwordx4 v[164:167], v72, s[80:81] offset:1024
	global_load_dwordx2 v[226:227], v70, s[88:89] offset:512
	global_load_dwordx4 v[168:171], v72, s[80:81] offset:2048
	global_load_dwordx2 v[228:229], v70, s[88:89] offset:1024
	global_load_dwordx4 v[172:175], v72, s[80:81] offset:3072
	global_load_dwordx2 v[230:231], v70, s[88:89] offset:1536
	global_load_dwordx4 v[176:179], v72, s[82:83] offset:0
	global_load_dwordx2 v[232:233], v70, s[88:89] offset:2048
	global_load_dwordx4 v[180:183], v72, s[82:83] offset:1024
	global_load_dwordx2 v[234:235], v70, s[88:89] offset:2560
	global_load_dwordx4 v[184:187], v72, s[82:83] offset:2048
	global_load_dwordx2 v[236:237], v70, s[88:89] offset:3072
	global_load_dwordx4 v[188:191], v72, s[82:83] offset:3072
	global_load_dwordx2 v[238:239], v70, s[88:89] offset:3584
	global_load_dwordx4 v[192:195], v72, s[84:85] offset:0
	global_load_dwordx2 v[240:241], v70, s[90:91] offset:0
	global_load_dwordx4 v[196:199], v72, s[84:85] offset:1024
	global_load_dwordx2 v[242:243], v70, s[90:91] offset:512
	global_load_dwordx4 v[200:203], v72, s[84:85] offset:2048
	global_load_dwordx2 v[244:245], v70, s[90:91] offset:1024
	global_load_dwordx4 v[204:207], v72, s[84:85] offset:3072
	global_load_dwordx2 v[246:247], v70, s[90:91] offset:1536
	global_load_dwordx4 v[208:211], v72, s[86:87] offset:0
	global_load_dwordx2 v[248:249], v70, s[90:91] offset:2048
	global_load_dwordx4 v[212:215], v72, s[86:87] offset:1024
	global_load_dwordx2 v[250:251], v70, s[90:91] offset:2560
	global_load_dwordx4 v[216:219], v72, s[86:87] offset:2048
	global_load_dwordx2 v[252:253], v70, s[90:91] offset:3072
	global_load_dwordx4 v[220:223], v72, s[86:87] offset:3072
	global_load_dwordx2 v[254:255], v70, s[90:91] offset:3584
	ds_read_b128 v[0:3], v150 offset:0
	v_lshl_add_u64 v[12:13], s[12:13], 0, v[72:73]
	s_waitcnt vmcnt(31)
	s_nop 1
	v_mov_b32_e32 v4, v160
	v_mov_b32_e32 v5, v161
	v_mov_b32_e32 v6, v162
	v_mov_b32_e32 v7, v163
	v_lshl_add_u64 v[74:75], s[16:17], 0, v[70:71]
	v_add_co_u32_e32 v120, vcc, s28, v74
	s_waitcnt vmcnt(32) lgkmcnt(0)
	ds_bpermute_b32 v9, v126, v8
	v_addc_co_u32_e32 v121, vcc, 0, v75, vcc
	s_waitcnt vmcnt(30)
	s_nop 1
	v_mov_b32_e32 v76, v224
	v_mov_b32_e32 v77, v225
	v_add_co_u32_e32 v14, vcc, s15, v74
	s_waitcnt lgkmcnt(0)
	v_add_f32_e32 v8, v8, v9
	ds_bpermute_b32 v9, v127, v8
	v_addc_co_u32_e32 v15, vcc, 0, v75, vcc
	s_waitcnt lgkmcnt(0)
	v_mov_b32_e32 v78, v0
	s_waitcnt lgkmcnt(0)
	v_mov_b32_e32 v0, v4
	s_waitcnt lgkmcnt(0)
	v_add_f32_e32 v10, v8, v9
	ds_bpermute_b32 v11, v128, v10
	v_lshl_add_u64 v[8:9], s[16:17], 0, v[72:73]
	v_mov_b32_e32 v79, v2
	v_mov_b32_e32 v2, v1
	v_mov_b32_e32 v1, v6
	s_waitcnt lgkmcnt(0)
	v_add_f32_e32 v10, v10, v11
	ds_bpermute_b32 v11, v129, v10
	v_mov_b32_e32 v6, v5
	s_waitcnt lgkmcnt(0)
	v_add_f32_e32 v80, v10, v11
	ds_bpermute_b32 v81, v130, v80
	v_add_co_u32_e32 v10, vcc, s27, v8
	s_waitcnt lgkmcnt(0)
	v_add_f32_e32 v80, v80, v81
	ds_bpermute_b32 v81, v131, v80
	v_addc_co_u32_e32 v11, vcc, 0, v9, vcc
	s_waitcnt lgkmcnt(0)
	v_add_f32_e32 v4, v80, v81
	v_fmamk_f32 v4, v4, 0x39800000, v132
	v_mul_f32_e32 v5, 0x4f800000, v4
	v_cmp_gt_f32_e32 vcc, s11, v4
	s_nop 1
	v_cndmask_b32_e32 v80, v4, v5, vcc
	v_sqrt_f32_e32 v81, v80
	s_waitcnt lgkmcnt(0)
	v_lshlrev_b32_e32 v4, 16, v76
	v_add_u32_e32 v82, -1, v81
	v_add_u32_e32 v83, 1, v81
	v_fma_f32 v84, -v82, v81, v80
	v_fma_f32 v85, -v83, v81, v80
	v_cmp_ge_f32_e64 s[2:3], 0, v84
	v_and_b32_e32 v76, 0xffff0000, v76
	v_lshlrev_b32_e32 v5, 16, v77
	v_cndmask_b32_e64 v81, v81, v82, s[2:3]
	v_cmp_lt_f32_e64 s[2:3], 0, v85
	v_and_b32_e32 v77, 0xffff0000, v77
	s_nop 0
	v_cndmask_b32_e64 v81, v81, v83, s[2:3]
	v_mul_f32_e32 v82, 0x37800000, v81
	v_cndmask_b32_e32 v81, v81, v82, vcc
	v_cmp_class_f32_e32 vcc, v80, v133
	s_nop 1
	v_cndmask_b32_e32 v80, v81, v80, vcc
	v_div_scale_f32 v81, s[2:3], v80, v80, 1.0
	v_rcp_f32_e32 v82, v81
	v_div_scale_f32 v83, vcc, 1.0, v80, 1.0
	v_fma_f32 v84, -v81, v82, 1.0
	v_fmac_f32_e32 v82, v84, v82
	v_mul_f32_e32 v84, v83, v82
	v_fma_f32 v85, -v81, v84, v83
	v_fmac_f32_e32 v84, v85, v82
	v_fma_f32 v81, -v81, v84, v83
	v_div_fmas_f32 v81, v81, v82, v84
	v_div_fixup_f32 v122, v81, v80, 1.0
	v_pk_mul_f32 v[4:5], v[122:123], v[4:5] op_sel_hi:[0,1]
	v_pk_mul_f32 v[76:77], v[122:123], v[76:77] op_sel_hi:[0,1]
	v_pk_fma_f32 v[82:83], v[78:79], v[4:5], v[0:1]
	v_pk_fma_f32 v[76:77], v[2:3], v[76:77], v[6:7]
	v_mov_b32_e32 v0, v82
	v_mov_b32_e32 v1, v76
	v_mov_b32_e32 v2, v83
	v_mov_b32_e32 v3, v77
	global_store_dwordx4 v[10:11], v[0:3], off offset:-4096
	s_waitcnt vmcnt(29)
	s_nop 1
	v_mov_b32_e32 v78, v226
	v_mov_b32_e32 v79, v227
	s_nop 0
	ds_read_b128 v[0:3], v150 offset:1024
	s_waitcnt vmcnt(30)
	s_nop 1
	v_mov_b32_e32 v4, v164
	v_mov_b32_e32 v5, v165
	v_mov_b32_e32 v6, v166
	v_mov_b32_e32 v7, v167
	v_add_co_u32_e32 v92, vcc, s26, v8
	s_waitcnt lgkmcnt(0)
	v_lshlrev_b32_e32 v81, 16, v79
	v_lshlrev_b32_e32 v80, 16, v78
	v_and_b32_e32 v79, 0xffff0000, v79
	v_and_b32_e32 v78, 0xffff0000, v78
	s_waitcnt lgkmcnt(0)
	v_mov_b32_e32 v84, v0
	v_mov_b32_e32 v85, v2
	s_waitcnt lgkmcnt(0)
	v_mov_b32_e32 v86, v4
	v_mov_b32_e32 v87, v6
	v_mov_b32_e32 v2, v1
	v_mov_b32_e32 v6, v5
	v_pk_mul_f32 v[0:1], v[122:123], v[80:81] op_sel_hi:[0,1]
	v_pk_mul_f32 v[4:5], v[122:123], v[78:79] op_sel_hi:[0,1]
	v_pk_fma_f32 v[86:87], v[84:85], v[0:1], v[86:87]
	v_pk_fma_f32 v[84:85], v[2:3], v[4:5], v[6:7]
	v_addc_co_u32_e32 v93, vcc, 0, v9, vcc
	v_mov_b32_e32 v0, v86
	v_mov_b32_e32 v1, v84
	v_mov_b32_e32 v2, v87
	v_mov_b32_e32 v3, v85
	global_store_dwordx4 v[92:93], v[0:3], off offset:1024
	s_waitcnt vmcnt(28)
	s_nop 1
	v_mov_b32_e32 v78, v228
	v_mov_b32_e32 v79, v229
	s_nop 0
	s_waitcnt vmcnt(29)
	s_nop 1
	v_mov_b32_e32 v0, v168
	v_mov_b32_e32 v1, v169
	v_mov_b32_e32 v2, v170
	v_mov_b32_e32 v3, v171
	ds_read_b128 v[4:7], v150 offset:2048
	v_add_co_u32_e32 v104, vcc, s24, v12
	s_waitcnt lgkmcnt(0)
	v_lshlrev_b32_e32 v80, 16, v78
	v_and_b32_e32 v81, 0xffff0000, v78
	v_lshlrev_b32_e32 v78, 16, v79
	v_and_b32_e32 v79, 0xffff0000, v79
	v_pk_mul_f32 v[80:81], v[122:123], v[80:81] op_sel_hi:[0,1]
	v_pk_mul_f32 v[78:79], v[122:123], v[78:79] op_sel_hi:[0,1]
	s_waitcnt lgkmcnt(0)
	v_pk_fma_f32 v[0:1], v[4:5], v[80:81], v[0:1]
	v_pk_fma_f32 v[2:3], v[6:7], v[78:79], v[2:3]
	global_store_dwordx4 v[92:93], v[0:3], off offset:2048
	s_waitcnt vmcnt(27)
	s_nop 1
	v_mov_b32_e32 v78, v230
	v_mov_b32_e32 v79, v231
	ds_read_b128 v[4:7], v150 offset:3072
	s_waitcnt vmcnt(28)
	s_nop 1
	v_mov_b32_e32 v88, v172
	v_mov_b32_e32 v89, v173
	v_mov_b32_e32 v90, v174
	v_mov_b32_e32 v91, v175
	v_addc_co_u32_e32 v105, vcc, 0, v13, vcc
	v_add_co_u32_e32 v110, vcc, s23, v12
	s_waitcnt lgkmcnt(0)
	v_lshlrev_b32_e32 v80, 16, v78
	v_and_b32_e32 v78, 0xffff0000, v78
	v_lshlrev_b32_e32 v81, 16, v79
	v_and_b32_e32 v79, 0xffff0000, v79
	s_waitcnt lgkmcnt(0)
	v_mov_b32_e32 v94, v4
	v_mov_b32_e32 v95, v6
	s_waitcnt lgkmcnt(0)
	v_mov_b32_e32 v96, v88
	v_mov_b32_e32 v97, v90
	v_mov_b32_e32 v6, v5
	v_mov_b32_e32 v90, v89
	v_pk_mul_f32 v[4:5], v[122:123], v[80:81] op_sel_hi:[0,1]
	v_pk_mul_f32 v[78:79], v[122:123], v[78:79] op_sel_hi:[0,1]
	v_pk_fma_f32 v[80:81], v[94:95], v[4:5], v[96:97]
	v_pk_fma_f32 v[78:79], v[6:7], v[78:79], v[90:91]
	v_mov_b32_e32 v4, v80
	v_mov_b32_e32 v5, v78
	v_mov_b32_e32 v6, v81
	v_mov_b32_e32 v7, v79
	global_store_dwordx4 v[92:93], v[4:7], off offset:3072
	s_waitcnt vmcnt(26)
	s_nop 1
	v_mov_b32_e32 v88, v232
	v_mov_b32_e32 v89, v233
	s_nop 0
	ds_read_b128 v[4:7], v150 offset:4096
	s_waitcnt vmcnt(27)
	s_nop 1
	v_mov_b32_e32 v90, v176
	v_mov_b32_e32 v91, v177
	v_mov_b32_e32 v92, v178
	v_mov_b32_e32 v93, v179
	v_addc_co_u32_e32 v111, vcc, 0, v13, vcc
	v_add_co_u32_e32 v124, vcc, s30, v8
	s_waitcnt lgkmcnt(0)
	v_lshlrev_b32_e32 v95, 16, v89
	v_lshlrev_b32_e32 v94, 16, v88
	v_and_b32_e32 v89, 0xffff0000, v89
	v_and_b32_e32 v88, 0xffff0000, v88
	s_waitcnt lgkmcnt(0)
	v_mov_b32_e32 v96, v4
	v_mov_b32_e32 v97, v6
	s_waitcnt lgkmcnt(0)
	v_mov_b32_e32 v98, v90
	v_mov_b32_e32 v99, v92
	v_mov_b32_e32 v6, v5
	v_mov_b32_e32 v92, v91
	v_pk_mul_f32 v[4:5], v[122:123], v[94:95] op_sel_hi:[0,1]
	v_pk_mul_f32 v[88:89], v[122:123], v[88:89] op_sel_hi:[0,1]
	v_pk_fma_f32 v[90:91], v[96:97], v[4:5], v[98:99]
	v_pk_fma_f32 v[88:89], v[6:7], v[88:89], v[92:93]
	v_mov_b32_e32 v4, v90
	v_mov_b32_e32 v5, v88
	v_mov_b32_e32 v6, v91
	v_mov_b32_e32 v7, v89
	global_store_dwordx4 v[10:11], v[4:7], off
	s_waitcnt vmcnt(25)
	s_nop 1
	v_mov_b32_e32 v96, v234
	v_mov_b32_e32 v97, v235
	s_nop 0
	ds_read_b128 v[4:7], v150 offset:5120
	s_waitcnt vmcnt(26)
	s_nop 1
	v_mov_b32_e32 v92, v180
	v_mov_b32_e32 v93, v181
	v_mov_b32_e32 v94, v182
	v_mov_b32_e32 v95, v183
	v_addc_co_u32_e32 v125, vcc, 0, v9, vcc
	s_waitcnt lgkmcnt(0)
	v_lshlrev_b32_e32 v99, 16, v97
	v_lshlrev_b32_e32 v98, 16, v96
	v_and_b32_e32 v97, 0xffff0000, v97
	v_and_b32_e32 v96, 0xffff0000, v96
	s_waitcnt lgkmcnt(0)
	v_mov_b32_e32 v100, v4
	v_mov_b32_e32 v101, v6
	s_waitcnt lgkmcnt(0)
	v_mov_b32_e32 v102, v92
	v_mov_b32_e32 v103, v94
	v_mov_b32_e32 v6, v5
	v_mov_b32_e32 v94, v93
	v_pk_mul_f32 v[4:5], v[122:123], v[98:99] op_sel_hi:[0,1]
	v_pk_mul_f32 v[92:93], v[122:123], v[96:97] op_sel_hi:[0,1]
	v_pk_fma_f32 v[98:99], v[100:101], v[4:5], v[102:103]
	v_pk_fma_f32 v[94:95], v[6:7], v[92:93], v[94:95]
	v_mov_b32_e32 v4, v98
	v_mov_b32_e32 v5, v94
	v_mov_b32_e32 v6, v99
	v_mov_b32_e32 v7, v95
	global_store_dwordx4 v[10:11], v[4:7], off offset:1024
	s_waitcnt vmcnt(24)
	s_nop 1
	v_mov_b32_e32 v92, v236
	v_mov_b32_e32 v93, v237
	s_nop 0
	s_waitcnt vmcnt(25)
	s_nop 1
	v_mov_b32_e32 v4, v184
	v_mov_b32_e32 v5, v185
	v_mov_b32_e32 v6, v186
	v_mov_b32_e32 v7, v187
	ds_read_b128 v[100:103], v150 offset:6144
	s_waitcnt lgkmcnt(0)
	v_lshlrev_b32_e32 v96, 16, v92
	v_and_b32_e32 v97, 0xffff0000, v92
	v_lshlrev_b32_e32 v92, 16, v93
	v_and_b32_e32 v93, 0xffff0000, v93
	v_pk_mul_f32 v[96:97], v[122:123], v[96:97] op_sel_hi:[0,1]
	v_pk_mul_f32 v[92:93], v[122:123], v[92:93] op_sel_hi:[0,1]
	s_waitcnt lgkmcnt(0)
	v_pk_fma_f32 v[4:5], v[100:101], v[96:97], v[4:5]
	v_pk_fma_f32 v[6:7], v[102:103], v[92:93], v[6:7]
	global_store_dwordx4 v[10:11], v[4:7], off offset:2048
	s_waitcnt vmcnt(23)
	s_nop 1
	v_mov_b32_e32 v92, v238
	v_mov_b32_e32 v93, v239
	ds_read_b128 v[100:103], v150 offset:7168
	s_waitcnt vmcnt(24)
	s_nop 1
	v_mov_b32_e32 v106, v188
	v_mov_b32_e32 v107, v189
	v_mov_b32_e32 v108, v190
	v_mov_b32_e32 v109, v191
	s_waitcnt lgkmcnt(0)
	v_lshlrev_b32_e32 v14, 16, v92
	v_and_b32_e32 v92, 0xffff0000, v92
	v_lshlrev_b32_e32 v15, 16, v93
	v_and_b32_e32 v93, 0xffff0000, v93
	s_waitcnt lgkmcnt(0)
	v_mov_b32_e32 v96, v100
	v_mov_b32_e32 v97, v102
	s_waitcnt lgkmcnt(0)
	v_mov_b32_e32 v110, v106
	v_mov_b32_e32 v111, v108
	v_mov_b32_e32 v102, v101
	v_mov_b32_e32 v108, v107
	v_pk_mul_f32 v[14:15], v[122:123], v[14:15] op_sel_hi:[0,1]
	v_pk_mul_f32 v[92:93], v[122:123], v[92:93] op_sel_hi:[0,1]
	v_pk_fma_f32 v[96:97], v[96:97], v[14:15], v[110:111]
	v_pk_fma_f32 v[92:93], v[102:103], v[92:93], v[108:109]
	v_mov_b32_e32 v100, v96
	v_mov_b32_e32 v101, v92
	v_mov_b32_e32 v102, v97
	v_mov_b32_e32 v103, v93
	global_store_dwordx4 v[10:11], v[100:103], off offset:3072
	s_waitcnt vmcnt(22)
	s_nop 1
	v_mov_b32_e32 v10, v240
	v_mov_b32_e32 v11, v241
	s_nop 0
	ds_read_b128 v[106:109], v150 offset:8192
	s_waitcnt vmcnt(23)
	s_nop 1
	v_mov_b32_e32 v110, v192
	v_mov_b32_e32 v111, v193
	v_mov_b32_e32 v112, v194
	v_mov_b32_e32 v113, v195
	s_waitcnt lgkmcnt(0)
	v_lshlrev_b32_e32 v15, 16, v11
	v_lshlrev_b32_e32 v14, 16, v10
	v_and_b32_e32 v11, 0xffff0000, v11
	v_and_b32_e32 v10, 0xffff0000, v10
	s_waitcnt lgkmcnt(0)
	v_mov_b32_e32 v100, v106
	v_mov_b32_e32 v101, v108
	s_waitcnt lgkmcnt(0)
	v_mov_b32_e32 v102, v110
	v_mov_b32_e32 v103, v112
	v_mov_b32_e32 v108, v107
	v_mov_b32_e32 v112, v111
	v_pk_mul_f32 v[14:15], v[122:123], v[14:15] op_sel_hi:[0,1]
	v_pk_mul_f32 v[10:11], v[122:123], v[10:11] op_sel_hi:[0,1]
	v_pk_fma_f32 v[102:103], v[100:101], v[14:15], v[102:103]
	v_pk_fma_f32 v[100:101], v[108:109], v[10:11], v[112:113]
	v_mov_b32_e32 v106, v102
	v_mov_b32_e32 v107, v100
	v_mov_b32_e32 v108, v103
	v_mov_b32_e32 v109, v101
	global_store_dwordx4 v[124:125], v[106:109], off offset:-4096
	s_waitcnt vmcnt(21)
	s_nop 1
	v_mov_b32_e32 v10, v242
	v_mov_b32_e32 v11, v243
	s_nop 0
	ds_read_b128 v[106:109], v150 offset:9216
	s_waitcnt vmcnt(22)
	s_nop 1
	v_mov_b32_e32 v110, v196
	v_mov_b32_e32 v111, v197
	v_mov_b32_e32 v112, v198
	v_mov_b32_e32 v113, v199
	v_add_co_u32_e32 v14, vcc, s29, v8
	s_waitcnt lgkmcnt(0)
	v_lshlrev_b32_e32 v8, 16, v10
	v_addc_co_u32_e32 v15, vcc, 0, v9, vcc
	v_lshlrev_b32_e32 v9, 16, v11
	v_and_b32_e32 v11, 0xffff0000, v11
	v_and_b32_e32 v10, 0xffff0000, v10
	s_waitcnt lgkmcnt(0)
	v_mov_b32_e32 v114, v106
	v_mov_b32_e32 v115, v108
	s_waitcnt lgkmcnt(0)
	v_mov_b32_e32 v116, v110
	v_mov_b32_e32 v117, v112
	v_mov_b32_e32 v108, v107
	v_mov_b32_e32 v112, v111
	v_pk_mul_f32 v[8:9], v[122:123], v[8:9] op_sel_hi:[0,1]
	v_pk_mul_f32 v[10:11], v[122:123], v[10:11] op_sel_hi:[0,1]
	v_pk_fma_f32 v[110:111], v[114:115], v[8:9], v[116:117]
	v_pk_fma_f32 v[108:109], v[108:109], v[10:11], v[112:113]
	v_mov_b32_e32 v8, v110
	v_mov_b32_e32 v9, v108
	v_mov_b32_e32 v10, v111
	v_mov_b32_e32 v11, v109
	global_store_dwordx4 v[14:15], v[8:11], off offset:1024
	s_waitcnt vmcnt(20)
	s_nop 1
	v_mov_b32_e32 v106, v244
	v_mov_b32_e32 v107, v245
	s_nop 0
	s_waitcnt vmcnt(21)
	s_nop 1
	v_mov_b32_e32 v8, v200
	v_mov_b32_e32 v9, v201
	v_mov_b32_e32 v10, v202
	v_mov_b32_e32 v11, v203
	ds_read_b128 v[112:115], v150 offset:10240
	v_add_co_u32_e32 v140, vcc, s25, v12
	s_waitcnt lgkmcnt(0)
	v_lshlrev_b32_e32 v116, 16, v106
	v_and_b32_e32 v117, 0xffff0000, v106
	v_lshlrev_b32_e32 v106, 16, v107
	v_and_b32_e32 v107, 0xffff0000, v107
	v_pk_mul_f32 v[116:117], v[122:123], v[116:117] op_sel_hi:[0,1]
	v_pk_mul_f32 v[106:107], v[122:123], v[106:107] op_sel_hi:[0,1]
	s_waitcnt lgkmcnt(0)
	v_pk_fma_f32 v[8:9], v[112:113], v[116:117], v[8:9]
	v_pk_fma_f32 v[10:11], v[114:115], v[106:107], v[10:11]
	global_store_dwordx4 v[14:15], v[8:11], off offset:2048
	s_waitcnt vmcnt(19)
	s_nop 1
	v_mov_b32_e32 v106, v246
	v_mov_b32_e32 v107, v247
	ds_read_b128 v[112:115], v150 offset:11264
	s_waitcnt vmcnt(20)
	s_nop 1
	v_mov_b32_e32 v116, v204
	v_mov_b32_e32 v117, v205
	v_mov_b32_e32 v118, v206
	v_mov_b32_e32 v119, v207
	v_addc_co_u32_e32 v141, vcc, 0, v13, vcc
	s_andn2_b64 vcc, exec, s[4:5]
	s_waitcnt lgkmcnt(0)
	v_lshlrev_b32_e32 v104, 16, v106
	v_and_b32_e32 v106, 0xffff0000, v106
	v_lshlrev_b32_e32 v105, 16, v107
	v_and_b32_e32 v107, 0xffff0000, v107
	s_waitcnt lgkmcnt(0)
	v_mov_b32_e32 v136, v112
	v_mov_b32_e32 v137, v114
	s_waitcnt lgkmcnt(0)
	v_mov_b32_e32 v138, v116
	v_mov_b32_e32 v139, v118
	v_mov_b32_e32 v114, v113
	v_mov_b32_e32 v118, v117
	v_pk_mul_f32 v[104:105], v[122:123], v[104:105] op_sel_hi:[0,1]
	v_pk_mul_f32 v[112:113], v[122:123], v[106:107] op_sel_hi:[0,1]
	v_pk_fma_f32 v[106:107], v[136:137], v[104:105], v[138:139]
	v_pk_fma_f32 v[104:105], v[114:115], v[112:113], v[118:119]
	v_mov_b32_e32 v112, v106
	v_mov_b32_e32 v113, v104
	v_mov_b32_e32 v114, v107
	v_mov_b32_e32 v115, v105
	global_store_dwordx4 v[14:15], v[112:115], off offset:3072
	s_waitcnt vmcnt(18)
	s_nop 1
	v_mov_b32_e32 v112, v248
	v_mov_b32_e32 v113, v249
	s_nop 0
	ds_read_b128 v[114:117], v150 offset:12288
	s_waitcnt vmcnt(19)
	s_nop 1
	v_mov_b32_e32 v12, v208
	v_mov_b32_e32 v13, v209
	v_mov_b32_e32 v14, v210
	v_mov_b32_e32 v15, v211
	s_waitcnt lgkmcnt(0)
	v_lshlrev_b32_e32 v119, 16, v113
	v_lshlrev_b32_e32 v118, 16, v112
	v_and_b32_e32 v113, 0xffff0000, v113
	v_and_b32_e32 v112, 0xffff0000, v112
	s_waitcnt lgkmcnt(0)
	v_mov_b32_e32 v136, v114
	v_mov_b32_e32 v137, v116
	s_waitcnt lgkmcnt(0)
	v_mov_b32_e32 v138, v12
	v_mov_b32_e32 v139, v14
	v_mov_b32_e32 v116, v115
	v_mov_b32_e32 v14, v13
	v_pk_mul_f32 v[12:13], v[122:123], v[118:119] op_sel_hi:[0,1]
	v_pk_mul_f32 v[112:113], v[122:123], v[112:113] op_sel_hi:[0,1]
	v_pk_fma_f32 v[114:115], v[136:137], v[12:13], v[138:139]
	v_pk_fma_f32 v[112:113], v[116:117], v[112:113], v[14:15]
	v_mov_b32_e32 v12, v114
	v_mov_b32_e32 v13, v112
	v_mov_b32_e32 v14, v115
	v_mov_b32_e32 v15, v113
	global_store_dwordx4 v[124:125], v[12:15], off
	s_waitcnt vmcnt(17)
	s_nop 1
	v_mov_b32_e32 v116, v250
	v_mov_b32_e32 v117, v251
	s_nop 0
	ds_read_b128 v[12:15], v150 offset:13312
	s_waitcnt vmcnt(18)
	s_nop 1
	v_mov_b32_e32 v136, v212
	v_mov_b32_e32 v137, v213
	v_mov_b32_e32 v138, v214
	v_mov_b32_e32 v139, v215
	s_waitcnt lgkmcnt(0)
	v_lshlrev_b32_e32 v119, 16, v117
	v_lshlrev_b32_e32 v118, 16, v116
	v_and_b32_e32 v117, 0xffff0000, v117
	v_and_b32_e32 v116, 0xffff0000, v116
	s_waitcnt lgkmcnt(0)
	v_mov_b32_e32 v142, v12
	v_mov_b32_e32 v143, v14
	s_waitcnt lgkmcnt(0)
	v_mov_b32_e32 v144, v136
	v_mov_b32_e32 v145, v138
	v_mov_b32_e32 v14, v13
	v_mov_b32_e32 v138, v137
	v_pk_mul_f32 v[12:13], v[122:123], v[118:119] op_sel_hi:[0,1]
	v_pk_mul_f32 v[116:117], v[122:123], v[116:117] op_sel_hi:[0,1]
	v_pk_fma_f32 v[118:119], v[142:143], v[12:13], v[144:145]
	v_pk_fma_f32 v[116:117], v[14:15], v[116:117], v[138:139]
	v_mov_b32_e32 v12, v118
	v_mov_b32_e32 v13, v116
	v_mov_b32_e32 v14, v119
	v_mov_b32_e32 v15, v117
	global_store_dwordx4 v[124:125], v[12:15], off offset:1024
	s_waitcnt vmcnt(16)
	s_nop 1
	v_mov_b32_e32 v142, v252
	v_mov_b32_e32 v143, v253
	s_nop 0
	s_waitcnt vmcnt(17)
	s_nop 1
	v_mov_b32_e32 v12, v216
	v_mov_b32_e32 v13, v217
	v_mov_b32_e32 v14, v218
	v_mov_b32_e32 v15, v219
	ds_read_b128 v[136:139], v150 offset:14336
	s_waitcnt lgkmcnt(0)
	v_lshlrev_b32_e32 v144, 16, v142
	v_and_b32_e32 v145, 0xffff0000, v142
	v_lshlrev_b32_e32 v142, 16, v143
	v_and_b32_e32 v143, 0xffff0000, v143
	v_pk_mul_f32 v[144:145], v[122:123], v[144:145] op_sel_hi:[0,1]
	v_pk_mul_f32 v[142:143], v[122:123], v[142:143] op_sel_hi:[0,1]
	s_waitcnt lgkmcnt(0)
	v_pk_fma_f32 v[12:13], v[136:137], v[144:145], v[12:13]
	v_pk_fma_f32 v[14:15], v[138:139], v[142:143], v[14:15]
	global_store_dwordx4 v[124:125], v[12:15], off offset:2048
	s_waitcnt vmcnt(15)
	s_nop 1
	v_mov_b32_e32 v120, v254
	v_mov_b32_e32 v121, v255
	s_nop 0
	ds_read_b128 v[136:139], v150 offset:15360
	s_nop 0
	s_waitcnt vmcnt(16)
	s_nop 1
	v_mov_b32_e32 v140, v220
	v_mov_b32_e32 v141, v221
	v_mov_b32_e32 v142, v222
	v_mov_b32_e32 v143, v223
	s_waitcnt lgkmcnt(0)
	v_lshlrev_b32_e32 v144, 16, v120
	v_and_b32_e32 v120, 0xffff0000, v120
	v_lshlrev_b32_e32 v145, 16, v121
	v_and_b32_e32 v121, 0xffff0000, v121
	s_waitcnt lgkmcnt(0)
	v_mov_b32_e32 v146, v136
	v_mov_b32_e32 v147, v138
	s_waitcnt lgkmcnt(0)
	v_mov_b32_e32 v148, v140
	v_mov_b32_e32 v149, v142
	v_mov_b32_e32 v138, v137
	v_mov_b32_e32 v142, v141
	v_pk_mul_f32 v[136:137], v[122:123], v[144:145] op_sel_hi:[0,1]
	v_pk_mul_f32 v[120:121], v[122:123], v[120:121] op_sel_hi:[0,1]
	v_pk_fma_f32 v[122:123], v[146:147], v[136:137], v[148:149]
	v_pk_fma_f32 v[120:121], v[138:139], v[120:121], v[142:143]
	v_mov_b32_e32 v136, v122
	v_mov_b32_e32 v137, v120
	v_mov_b32_e32 v138, v123
	v_mov_b32_e32 v139, v121
	global_store_dwordx4 v[124:125], v[136:139], off offset:3072
	s_cbranch_vccnz .LBB0_1691
	v_mov_b32_e32 v124, v82
	v_mov_b32_e32 v125, v76
	v_mul_f32_e32 v136, v76, v76
	v_pk_fma_f32 v[124:125], v[124:125], v[124:125], v[136:137] op_sel_hi:[1,1,0]
	v_mov_b32_e32 v136, v83
	v_mov_b32_e32 v137, v77
	v_mul_f32_e32 v138, v77, v77
	v_pk_fma_f32 v[136:137], v[136:137], v[136:137], v[138:139] op_sel_hi:[1,1,0]
	v_pk_mul_f32 v[138:139], v[84:85], v[84:85]
	v_mul_f32_e32 v140, v1, v1
	v_pk_fma_f32 v[138:139], v[86:87], v[86:87], v[138:139]
	v_mul_f32_e32 v142, v3, v3
	v_pk_add_f32 v[138:139], v[138:139], v[138:139] op_sel:[0,1] op_sel_hi:[1,0]
	v_pk_fma_f32 v[140:141], v[0:1], v[0:1], v[140:141] op_sel_hi:[1,1,0]
	v_pk_fma_f32 v[142:143], v[2:3], v[2:3], v[142:143] op_sel_hi:[1,1,0]
	v_pk_mul_f32 v[144:145], v[78:79], v[78:79]
	v_pk_mul_f32 v[146:147], v[80:81], v[80:81]
	v_pk_add_f32 v[124:125], v[124:125], v[136:137]
	v_mov_b32_e32 v139, v144
	v_mov_b32_e32 v125, v146
	v_mov_b32_e32 v141, v147
	v_mov_b32_e32 v143, v145
	v_pk_add_f32 v[124:125], v[124:125], v[138:139]
	v_pk_add_f32 v[136:137], v[140:141], v[142:143]
	v_pk_mul_f32 v[138:139], v[94:95], v[94:95]
	v_pk_add_f32 v[124:125], v[124:125], v[136:137]
	v_pk_mul_f32 v[136:137], v[88:89], v[88:89]
	v_pk_add_f32 v[124:125], v[124:125], v[124:125] op_sel:[0,1] op_sel_hi:[1,0]
	v_pk_fma_f32 v[136:137], v[90:91], v[90:91], v[136:137]
	v_pk_fma_f32 v[138:139], v[98:99], v[98:99], v[138:139]
	v_pk_add_f32 v[136:137], v[136:137], v[136:137] op_sel:[0,1] op_sel_hi:[1,0]
	v_mul_f32_e32 v140, v5, v5
	v_mul_f32_e32 v142, v7, v7
	v_pk_add_f32 v[138:139], v[138:139], v[138:139] op_sel:[0,1] op_sel_hi:[1,0]
	v_pk_fma_f32 v[140:141], v[4:5], v[4:5], v[140:141] op_sel_hi:[1,1,0]
	v_pk_fma_f32 v[142:143], v[6:7], v[6:7], v[142:143] op_sel_hi:[1,1,0]
	v_pk_mul_f32 v[144:145], v[92:93], v[92:93]
	v_pk_mul_f32 v[146:147], v[96:97], v[96:97]
	v_pk_add_f32 v[124:125], v[124:125], v[136:137]
	v_mov_b32_e32 v139, v144
	v_mov_b32_e32 v125, v146
	v_mov_b32_e32 v141, v147
	v_mov_b32_e32 v143, v145
	v_pk_add_f32 v[124:125], v[124:125], v[138:139]
	v_pk_add_f32 v[136:137], v[140:141], v[142:143]
	v_pk_mul_f32 v[138:139], v[108:109], v[108:109]
	v_pk_add_f32 v[124:125], v[124:125], v[136:137]
	v_pk_mul_f32 v[136:137], v[100:101], v[100:101]
	v_pk_add_f32 v[124:125], v[124:125], v[124:125] op_sel:[0,1] op_sel_hi:[1,0]
	v_pk_fma_f32 v[136:137], v[102:103], v[102:103], v[136:137]
	v_pk_fma_f32 v[138:139], v[110:111], v[110:111], v[138:139]
	v_pk_add_f32 v[136:137], v[136:137], v[136:137] op_sel:[0,1] op_sel_hi:[1,0]
	v_mul_f32_e32 v140, v9, v9
	v_mul_f32_e32 v142, v11, v11
	v_pk_add_f32 v[138:139], v[138:139], v[138:139] op_sel:[0,1] op_sel_hi:[1,0]
	v_pk_fma_f32 v[140:141], v[8:9], v[8:9], v[140:141] op_sel_hi:[1,1,0]
	v_pk_fma_f32 v[142:143], v[10:11], v[10:11], v[142:143] op_sel_hi:[1,1,0]
	v_pk_mul_f32 v[144:145], v[104:105], v[104:105]
	v_pk_mul_f32 v[146:147], v[106:107], v[106:107]
	v_pk_add_f32 v[124:125], v[124:125], v[136:137]
	v_mov_b32_e32 v139, v144
	v_mov_b32_e32 v125, v146
	v_mov_b32_e32 v141, v147
	v_mov_b32_e32 v143, v145
	v_pk_add_f32 v[124:125], v[124:125], v[138:139]
	v_pk_add_f32 v[136:137], v[140:141], v[142:143]
	v_pk_mul_f32 v[138:139], v[116:117], v[116:117]
	v_pk_add_f32 v[124:125], v[124:125], v[136:137]
	v_pk_mul_f32 v[136:137], v[112:113], v[112:113]
	v_pk_add_f32 v[124:125], v[124:125], v[124:125] op_sel:[0,1] op_sel_hi:[1,0]
	v_pk_fma_f32 v[136:137], v[114:115], v[114:115], v[136:137]
	v_pk_fma_f32 v[138:139], v[118:119], v[118:119], v[138:139]
	v_pk_add_f32 v[136:137], v[136:137], v[136:137] op_sel:[0,1] op_sel_hi:[1,0]
	v_pk_add_f32 v[138:139], v[138:139], v[138:139] op_sel:[0,1] op_sel_hi:[1,0]
	v_pk_mul_f32 v[144:145], v[120:121], v[120:121]
	v_pk_mul_f32 v[146:147], v[122:123], v[122:123]
	v_pk_add_f32 v[124:125], v[124:125], v[136:137]
	v_mov_b32_e32 v139, v144
	v_mov_b32_e32 v125, v146
	v_pk_add_f32 v[124:125], v[124:125], v[138:139]
	ds_read_b128 v[136:139], v150 offset:16384
	v_mul_f32_e32 v140, v13, v13
	v_mul_f32_e32 v142, v15, v15
	v_pk_fma_f32 v[140:141], v[12:13], v[12:13], v[140:141] op_sel_hi:[1,1,0]
	v_pk_fma_f32 v[142:143], v[14:15], v[14:15], v[142:143] op_sel_hi:[1,1,0]
	v_mov_b32_e32 v141, v147
	v_mov_b32_e32 v143, v145
	v_pk_add_f32 v[140:141], v[140:141], v[142:143]
	s_nop 0
	v_pk_add_f32 v[124:125], v[124:125], v[140:141]
	s_nop 0
	v_add_f32_e32 v124, v124, v125
	ds_bpermute_b32 v125, v126, v124
	s_waitcnt lgkmcnt(0)
	v_add_f32_e32 v124, v124, v125
	ds_bpermute_b32 v125, v127, v124
	s_waitcnt lgkmcnt(0)
	v_add_f32_e32 v124, v124, v125
	ds_bpermute_b32 v125, v128, v124
	s_waitcnt lgkmcnt(0)
	v_add_f32_e32 v124, v124, v125
	ds_bpermute_b32 v125, v129, v124
	s_waitcnt lgkmcnt(0)
	v_add_f32_e32 v124, v124, v125
	ds_bpermute_b32 v125, v130, v124
	s_waitcnt lgkmcnt(0)
	v_add_f32_e32 v124, v124, v125
	ds_bpermute_b32 v125, v131, v124
	s_waitcnt lgkmcnt(0)
	v_add_f32_e32 v124, v124, v125
	v_fmamk_f32 v124, v124, 0x39800000, v132
	v_mul_f32_e32 v125, 0x4f800000, v124
	v_cmp_gt_f32_e32 vcc, s11, v124
	s_nop 1
	v_cndmask_b32_e32 v124, v124, v125, vcc
	v_sqrt_f32_e32 v125, v124
	s_nop 0
	v_add_u32_e32 v135, -1, v125
	v_fma_f32 v140, -v135, v125, v124
	v_cmp_ge_f32_e64 s[2:3], 0, v140
	v_add_u32_e32 v140, 1, v125
	s_nop 0
	v_cndmask_b32_e64 v135, v125, v135, s[2:3]
	v_fma_f32 v125, -v140, v125, v124
	v_cmp_lt_f32_e64 s[2:3], 0, v125
	s_nop 1
	v_cndmask_b32_e64 v125, v135, v140, s[2:3]
	v_mul_f32_e32 v135, 0x37800000, v125
	v_cndmask_b32_e32 v125, v125, v135, vcc
	v_cmp_class_f32_e32 vcc, v124, v133
	s_nop 1
	v_cndmask_b32_e32 v124, v125, v124, vcc
	v_div_scale_f32 v125, s[2:3], v124, v124, 1.0
	v_rcp_f32_e32 v135, v125
	s_nop 0
	v_fma_f32 v140, -v125, v135, 1.0
	v_fmac_f32_e32 v135, v140, v135
	v_div_scale_f32 v140, vcc, 1.0, v124, 1.0
	v_mul_f32_e32 v141, v140, v135
	v_fma_f32 v142, -v125, v141, v140
	v_fmac_f32_e32 v141, v142, v135
	v_fma_f32 v125, -v125, v141, v140
	v_div_fmas_f32 v125, v125, v135, v141
	v_div_fixup_f32 v124, v125, v124, 1.0
	v_pk_mul_f32 v[82:83], v[82:83], v[124:125] op_sel_hi:[1,0]
	s_waitcnt lgkmcnt(0)
	v_mov_b32_e32 v140, v136
	v_mov_b32_e32 v141, v138
	v_pk_mul_f32 v[82:83], v[140:141], v[82:83]
	v_pk_mul_f32 v[76:77], v[76:77], v[124:125] op_sel_hi:[1,0]
	v_mov_b32_e32 v138, v137
	v_pk_mul_f32 v[76:77], v[138:139], v[76:77]
	v_and_b32_sdwa v135, v82, v134 dst_sel:DWORD dst_unused:UNUSED_PAD src0_sel:WORD_1 src1_sel:DWORD
	v_and_b32_sdwa v125, v83, v134 dst_sel:DWORD dst_unused:UNUSED_PAD src0_sel:WORD_1 src1_sel:DWORD
	v_add3_u32 v82, v82, v135, s31
	v_and_b32_sdwa v135, v76, v134 dst_sel:DWORD dst_unused:UNUSED_PAD src0_sel:WORD_1 src1_sel:DWORD
	v_add3_u32 v83, v83, v125, s31
	v_and_b32_sdwa v125, v77, v134 dst_sel:DWORD dst_unused:UNUSED_PAD src0_sel:WORD_1 src1_sel:DWORD
	v_add3_u32 v76, v76, v135, s31
	v_add3_u32 v77, v77, v125, s31
	v_and_b32_e32 v76, 0xffff0000, v76
	v_and_b32_e32 v77, 0xffff0000, v77
	v_or_b32_sdwa v82, v76, v82 dst_sel:DWORD dst_unused:UNUSED_PAD src0_sel:DWORD src1_sel:WORD_1
	v_add_co_u32_e32 v76, vcc, s34, v74
	v_or_b32_sdwa v83, v77, v83 dst_sel:DWORD dst_unused:UNUSED_PAD src0_sel:DWORD src1_sel:WORD_1
	s_nop 0
	v_addc_co_u32_e32 v77, vcc, 0, v75, vcc
	global_store_dwordx2 v[76:77], v[82:83], off offset:-4096
	ds_read_b128 v[136:139], v150 offset:17408
	v_pk_mul_f32 v[82:83], v[86:87], v[124:125] op_sel_hi:[1,0]
	v_pk_mul_f32 v[84:85], v[84:85], v[124:125] op_sel_hi:[1,0]
	v_add_co_u32_e32 v74, vcc, s33, v74
	s_waitcnt lgkmcnt(0)
	v_mov_b32_e32 v87, v138
	v_mov_b32_e32 v138, v137
	v_mov_b32_e32 v86, v136
	v_pk_mul_f32 v[84:85], v[138:139], v[84:85]
	v_pk_mul_f32 v[82:83], v[86:87], v[82:83]
	v_and_b32_sdwa v125, v85, v134 dst_sel:DWORD dst_unused:UNUSED_PAD src0_sel:WORD_1 src1_sel:DWORD
	v_and_b32_sdwa v135, v84, v134 dst_sel:DWORD dst_unused:UNUSED_PAD src0_sel:WORD_1 src1_sel:DWORD
	v_and_b32_sdwa v86, v83, v134 dst_sel:DWORD dst_unused:UNUSED_PAD src0_sel:WORD_1 src1_sel:DWORD
	v_and_b32_sdwa v87, v82, v134 dst_sel:DWORD dst_unused:UNUSED_PAD src0_sel:WORD_1 src1_sel:DWORD
	v_add3_u32 v85, v85, v125, s31
	v_add3_u32 v84, v84, v135, s31
	v_add3_u32 v82, v82, v87, s31
	v_add3_u32 v83, v83, v86, s31
	v_and_b32_e32 v85, 0xffff0000, v85
	v_and_b32_e32 v84, 0xffff0000, v84
	v_addc_co_u32_e32 v75, vcc, 0, v75, vcc
	v_or_b32_sdwa v83, v85, v83 dst_sel:DWORD dst_unused:UNUSED_PAD src0_sel:DWORD src1_sel:WORD_1
	v_or_b32_sdwa v82, v84, v82 dst_sel:DWORD dst_unused:UNUSED_PAD src0_sel:DWORD src1_sel:WORD_1
	global_store_dwordx2 v[74:75], v[82:83], off offset:512
	ds_read_b128 v[82:85], v150 offset:18432
	v_mov_b32_e32 v86, v0
	v_mov_b32_e32 v87, v2
	v_mov_b32_e32 v2, v1
	v_pk_mul_f32 v[0:1], v[86:87], v[124:125] op_sel_hi:[1,0]
	v_pk_mul_f32 v[2:3], v[2:3], v[124:125] op_sel_hi:[1,0]
	v_pk_mul_f32 v[78:79], v[78:79], v[124:125] op_sel_hi:[1,0]
	v_pk_mul_f32 v[80:81], v[80:81], v[124:125] op_sel_hi:[1,0]
	s_waitcnt lgkmcnt(0)
	v_mov_b32_e32 v87, v84
	v_mov_b32_e32 v84, v83
	v_mov_b32_e32 v86, v82
	v_pk_mul_f32 v[2:3], v[84:85], v[2:3]
	v_pk_mul_f32 v[0:1], v[86:87], v[0:1]
	v_and_b32_sdwa v84, v3, v134 dst_sel:DWORD dst_unused:UNUSED_PAD src0_sel:WORD_1 src1_sel:DWORD
	v_and_b32_sdwa v85, v2, v134 dst_sel:DWORD dst_unused:UNUSED_PAD src0_sel:WORD_1 src1_sel:DWORD
	v_and_b32_sdwa v82, v1, v134 dst_sel:DWORD dst_unused:UNUSED_PAD src0_sel:WORD_1 src1_sel:DWORD
	v_and_b32_sdwa v83, v0, v134 dst_sel:DWORD dst_unused:UNUSED_PAD src0_sel:WORD_1 src1_sel:DWORD
	v_add3_u32 v3, v3, v84, s31
	v_add3_u32 v2, v2, v85, s31
	v_add3_u32 v0, v0, v83, s31
	v_add3_u32 v1, v1, v82, s31
	v_and_b32_e32 v3, 0xffff0000, v3
	v_and_b32_e32 v2, 0xffff0000, v2
	v_or_b32_sdwa v1, v3, v1 dst_sel:DWORD dst_unused:UNUSED_PAD src0_sel:DWORD src1_sel:WORD_1
	v_or_b32_sdwa v0, v2, v0 dst_sel:DWORD dst_unused:UNUSED_PAD src0_sel:DWORD src1_sel:WORD_1
	global_store_dwordx2 v[74:75], v[0:1], off offset:1024
	ds_read_b128 v[0:3], v150 offset:19456
	s_waitcnt lgkmcnt(0)
	v_mov_b32_e32 v83, v2
	v_mov_b32_e32 v2, v1
	v_mov_b32_e32 v82, v0
	v_pk_mul_f32 v[2:3], v[78:79], v[2:3]
	v_pk_mul_f32 v[0:1], v[80:81], v[82:83]
	v_and_b32_sdwa v80, v3, v134 dst_sel:DWORD dst_unused:UNUSED_PAD src0_sel:WORD_1 src1_sel:DWORD
	v_and_b32_sdwa v81, v2, v134 dst_sel:DWORD dst_unused:UNUSED_PAD src0_sel:WORD_1 src1_sel:DWORD
	v_and_b32_sdwa v78, v1, v134 dst_sel:DWORD dst_unused:UNUSED_PAD src0_sel:WORD_1 src1_sel:DWORD
	v_and_b32_sdwa v79, v0, v134 dst_sel:DWORD dst_unused:UNUSED_PAD src0_sel:WORD_1 src1_sel:DWORD
	v_add3_u32 v3, v3, v80, s31
	v_add3_u32 v2, v2, v81, s31
	v_add3_u32 v0, v0, v79, s31
	v_add3_u32 v1, v1, v78, s31
	v_and_b32_e32 v3, 0xffff0000, v3
	v_and_b32_e32 v2, 0xffff0000, v2
	v_or_b32_sdwa v1, v3, v1 dst_sel:DWORD dst_unused:UNUSED_PAD src0_sel:DWORD src1_sel:WORD_1
	v_or_b32_sdwa v0, v2, v0 dst_sel:DWORD dst_unused:UNUSED_PAD src0_sel:DWORD src1_sel:WORD_1
	global_store_dwordx2 v[74:75], v[0:1], off offset:1536
	ds_read_b128 v[0:3], v150 offset:20480
	v_pk_mul_f32 v[80:81], v[88:89], v[124:125] op_sel_hi:[1,0]
	v_pk_mul_f32 v[78:79], v[90:91], v[124:125] op_sel_hi:[1,0]
	s_waitcnt lgkmcnt(0)
	v_mov_b32_e32 v83, v2
	v_mov_b32_e32 v2, v1
	v_mov_b32_e32 v82, v0
	v_pk_mul_f32 v[2:3], v[80:81], v[2:3]
	v_pk_mul_f32 v[0:1], v[78:79], v[82:83]
	v_and_b32_sdwa v80, v3, v134 dst_sel:DWORD dst_unused:UNUSED_PAD src0_sel:WORD_1 src1_sel:DWORD
	v_and_b32_sdwa v81, v2, v134 dst_sel:DWORD dst_unused:UNUSED_PAD src0_sel:WORD_1 src1_sel:DWORD
	v_and_b32_sdwa v78, v1, v134 dst_sel:DWORD dst_unused:UNUSED_PAD src0_sel:WORD_1 src1_sel:DWORD
	v_and_b32_sdwa v79, v0, v134 dst_sel:DWORD dst_unused:UNUSED_PAD src0_sel:WORD_1 src1_sel:DWORD
	v_add3_u32 v3, v3, v80, s31
	v_add3_u32 v2, v2, v81, s31
	v_add3_u32 v0, v0, v79, s31
	v_add3_u32 v1, v1, v78, s31
	v_and_b32_e32 v3, 0xffff0000, v3
	v_and_b32_e32 v2, 0xffff0000, v2
	v_or_b32_sdwa v1, v3, v1 dst_sel:DWORD dst_unused:UNUSED_PAD src0_sel:DWORD src1_sel:WORD_1
	v_or_b32_sdwa v0, v2, v0 dst_sel:DWORD dst_unused:UNUSED_PAD src0_sel:DWORD src1_sel:WORD_1
	global_store_dwordx2 v[74:75], v[0:1], off offset:2048
	ds_read_b128 v[0:3], v150 offset:21504
	v_pk_mul_f32 v[80:81], v[94:95], v[124:125] op_sel_hi:[1,0]
	v_pk_mul_f32 v[78:79], v[98:99], v[124:125] op_sel_hi:[1,0]
	s_waitcnt lgkmcnt(0)
	v_mov_b32_e32 v83, v2
	v_mov_b32_e32 v2, v1
	v_mov_b32_e32 v82, v0
	v_pk_mul_f32 v[2:3], v[80:81], v[2:3]
	v_pk_mul_f32 v[0:1], v[78:79], v[82:83]
	v_and_b32_sdwa v80, v3, v134 dst_sel:DWORD dst_unused:UNUSED_PAD src0_sel:WORD_1 src1_sel:DWORD
	v_and_b32_sdwa v81, v2, v134 dst_sel:DWORD dst_unused:UNUSED_PAD src0_sel:WORD_1 src1_sel:DWORD
	v_and_b32_sdwa v78, v1, v134 dst_sel:DWORD dst_unused:UNUSED_PAD src0_sel:WORD_1 src1_sel:DWORD
	v_and_b32_sdwa v79, v0, v134 dst_sel:DWORD dst_unused:UNUSED_PAD src0_sel:WORD_1 src1_sel:DWORD
	v_add3_u32 v3, v3, v80, s31
	v_add3_u32 v2, v2, v81, s31
	v_add3_u32 v0, v0, v79, s31
	v_add3_u32 v1, v1, v78, s31
	v_and_b32_e32 v3, 0xffff0000, v3
	v_and_b32_e32 v2, 0xffff0000, v2
	v_or_b32_sdwa v1, v3, v1 dst_sel:DWORD dst_unused:UNUSED_PAD src0_sel:DWORD src1_sel:WORD_1
	v_or_b32_sdwa v0, v2, v0 dst_sel:DWORD dst_unused:UNUSED_PAD src0_sel:DWORD src1_sel:WORD_1
	global_store_dwordx2 v[74:75], v[0:1], off offset:2560
	ds_read_b128 v[0:3], v150 offset:22528
	v_mov_b32_e32 v78, v4
	v_mov_b32_e32 v79, v6
	v_mov_b32_e32 v6, v5
	v_pk_mul_f32 v[4:5], v[78:79], v[124:125] op_sel_hi:[1,0]
	v_pk_mul_f32 v[6:7], v[6:7], v[124:125] op_sel_hi:[1,0]
	s_waitcnt lgkmcnt(0)
	v_mov_b32_e32 v79, v2
	v_mov_b32_e32 v2, v1
	v_mov_b32_e32 v78, v0
	v_pk_mul_f32 v[2:3], v[6:7], v[2:3]
	v_pk_mul_f32 v[0:1], v[4:5], v[78:79]
	v_and_b32_sdwa v6, v3, v134 dst_sel:DWORD dst_unused:UNUSED_PAD src0_sel:WORD_1 src1_sel:DWORD
	v_and_b32_sdwa v7, v2, v134 dst_sel:DWORD dst_unused:UNUSED_PAD src0_sel:WORD_1 src1_sel:DWORD
	v_and_b32_sdwa v4, v1, v134 dst_sel:DWORD dst_unused:UNUSED_PAD src0_sel:WORD_1 src1_sel:DWORD
	v_and_b32_sdwa v5, v0, v134 dst_sel:DWORD dst_unused:UNUSED_PAD src0_sel:WORD_1 src1_sel:DWORD
	v_add3_u32 v3, v3, v6, s31
	v_add3_u32 v2, v2, v7, s31
	v_add3_u32 v0, v0, v5, s31
	v_add3_u32 v1, v1, v4, s31
	v_and_b32_e32 v3, 0xffff0000, v3
	v_and_b32_e32 v2, 0xffff0000, v2
	v_or_b32_sdwa v1, v3, v1 dst_sel:DWORD dst_unused:UNUSED_PAD src0_sel:DWORD src1_sel:WORD_1
	v_or_b32_sdwa v0, v2, v0 dst_sel:DWORD dst_unused:UNUSED_PAD src0_sel:DWORD src1_sel:WORD_1
	global_store_dwordx2 v[74:75], v[0:1], off offset:3072
	ds_read_b128 v[0:3], v150 offset:23552
	v_pk_mul_f32 v[6:7], v[92:93], v[124:125] op_sel_hi:[1,0]
	v_pk_mul_f32 v[4:5], v[96:97], v[124:125] op_sel_hi:[1,0]
	s_waitcnt lgkmcnt(0)
	v_mov_b32_e32 v79, v2
	v_mov_b32_e32 v2, v1
	v_mov_b32_e32 v78, v0
	v_pk_mul_f32 v[2:3], v[6:7], v[2:3]
	v_pk_mul_f32 v[0:1], v[4:5], v[78:79]
	v_and_b32_sdwa v6, v3, v134 dst_sel:DWORD dst_unused:UNUSED_PAD src0_sel:WORD_1 src1_sel:DWORD
	v_and_b32_sdwa v7, v2, v134 dst_sel:DWORD dst_unused:UNUSED_PAD src0_sel:WORD_1 src1_sel:DWORD
	v_and_b32_sdwa v4, v1, v134 dst_sel:DWORD dst_unused:UNUSED_PAD src0_sel:WORD_1 src1_sel:DWORD
	v_and_b32_sdwa v5, v0, v134 dst_sel:DWORD dst_unused:UNUSED_PAD src0_sel:WORD_1 src1_sel:DWORD
	v_add3_u32 v3, v3, v6, s31
	v_add3_u32 v2, v2, v7, s31
	v_add3_u32 v0, v0, v5, s31
	v_add3_u32 v1, v1, v4, s31
	v_and_b32_e32 v3, 0xffff0000, v3
	v_and_b32_e32 v2, 0xffff0000, v2
	v_or_b32_sdwa v1, v3, v1 dst_sel:DWORD dst_unused:UNUSED_PAD src0_sel:DWORD src1_sel:WORD_1
	v_or_b32_sdwa v0, v2, v0 dst_sel:DWORD dst_unused:UNUSED_PAD src0_sel:DWORD src1_sel:WORD_1
	global_store_dwordx2 v[74:75], v[0:1], off offset:3584
	ds_read_b128 v[0:3], v150 offset:24576
	v_pk_mul_f32 v[6:7], v[100:101], v[124:125] op_sel_hi:[1,0]
	v_pk_mul_f32 v[4:5], v[102:103], v[124:125] op_sel_hi:[1,0]
	s_waitcnt lgkmcnt(0)
	v_mov_b32_e32 v75, v2
	v_mov_b32_e32 v2, v1
	v_mov_b32_e32 v74, v0
	v_pk_mul_f32 v[2:3], v[6:7], v[2:3]
	v_pk_mul_f32 v[0:1], v[4:5], v[74:75]
	v_and_b32_sdwa v6, v3, v134 dst_sel:DWORD dst_unused:UNUSED_PAD src0_sel:WORD_1 src1_sel:DWORD
	v_and_b32_sdwa v7, v2, v134 dst_sel:DWORD dst_unused:UNUSED_PAD src0_sel:WORD_1 src1_sel:DWORD
	v_and_b32_sdwa v4, v1, v134 dst_sel:DWORD dst_unused:UNUSED_PAD src0_sel:WORD_1 src1_sel:DWORD
	v_and_b32_sdwa v5, v0, v134 dst_sel:DWORD dst_unused:UNUSED_PAD src0_sel:WORD_1 src1_sel:DWORD
	v_add3_u32 v3, v3, v6, s31
	v_add3_u32 v2, v2, v7, s31
	v_add3_u32 v0, v0, v5, s31
	v_add3_u32 v1, v1, v4, s31
	v_and_b32_e32 v3, 0xffff0000, v3
	v_and_b32_e32 v2, 0xffff0000, v2
	v_or_b32_sdwa v1, v3, v1 dst_sel:DWORD dst_unused:UNUSED_PAD src0_sel:DWORD src1_sel:WORD_1
	v_or_b32_sdwa v0, v2, v0 dst_sel:DWORD dst_unused:UNUSED_PAD src0_sel:DWORD src1_sel:WORD_1
	global_store_dwordx2 v[76:77], v[0:1], off
	ds_read_b128 v[0:3], v150 offset:25600
	v_pk_mul_f32 v[6:7], v[108:109], v[124:125] op_sel_hi:[1,0]
	v_pk_mul_f32 v[4:5], v[110:111], v[124:125] op_sel_hi:[1,0]
	s_waitcnt lgkmcnt(0)
	v_mov_b32_e32 v75, v2
	v_mov_b32_e32 v2, v1
	v_mov_b32_e32 v74, v0
	v_pk_mul_f32 v[2:3], v[6:7], v[2:3]
	v_pk_mul_f32 v[0:1], v[4:5], v[74:75]
	v_and_b32_sdwa v6, v3, v134 dst_sel:DWORD dst_unused:UNUSED_PAD src0_sel:WORD_1 src1_sel:DWORD
	v_and_b32_sdwa v7, v2, v134 dst_sel:DWORD dst_unused:UNUSED_PAD src0_sel:WORD_1 src1_sel:DWORD
	v_and_b32_sdwa v4, v1, v134 dst_sel:DWORD dst_unused:UNUSED_PAD src0_sel:WORD_1 src1_sel:DWORD
	v_and_b32_sdwa v5, v0, v134 dst_sel:DWORD dst_unused:UNUSED_PAD src0_sel:WORD_1 src1_sel:DWORD
	v_add3_u32 v3, v3, v6, s31
	v_add3_u32 v2, v2, v7, s31
	v_add3_u32 v0, v0, v5, s31
	v_add3_u32 v1, v1, v4, s31
	v_and_b32_e32 v3, 0xffff0000, v3
	v_and_b32_e32 v2, 0xffff0000, v2
	v_or_b32_sdwa v1, v3, v1 dst_sel:DWORD dst_unused:UNUSED_PAD src0_sel:DWORD src1_sel:WORD_1
	v_or_b32_sdwa v0, v2, v0 dst_sel:DWORD dst_unused:UNUSED_PAD src0_sel:DWORD src1_sel:WORD_1
	global_store_dwordx2 v[76:77], v[0:1], off offset:512
	ds_read_b128 v[0:3], v150 offset:26624
	v_mov_b32_e32 v5, v10
	v_mov_b32_e32 v10, v9
	v_mov_b32_e32 v4, v8
	v_pk_mul_f32 v[6:7], v[10:11], v[124:125] op_sel_hi:[1,0]
	v_pk_mul_f32 v[4:5], v[4:5], v[124:125] op_sel_hi:[1,0]
	s_waitcnt lgkmcnt(0)
	v_mov_b32_e32 v9, v2
	v_mov_b32_e32 v2, v1
	v_mov_b32_e32 v8, v0
	v_pk_mul_f32 v[2:3], v[6:7], v[2:3]
	v_pk_mul_f32 v[0:1], v[4:5], v[8:9]
	v_and_b32_sdwa v6, v3, v134 dst_sel:DWORD dst_unused:UNUSED_PAD src0_sel:WORD_1 src1_sel:DWORD
	v_and_b32_sdwa v7, v2, v134 dst_sel:DWORD dst_unused:UNUSED_PAD src0_sel:WORD_1 src1_sel:DWORD
	v_and_b32_sdwa v4, v1, v134 dst_sel:DWORD dst_unused:UNUSED_PAD src0_sel:WORD_1 src1_sel:DWORD
	v_and_b32_sdwa v5, v0, v134 dst_sel:DWORD dst_unused:UNUSED_PAD src0_sel:WORD_1 src1_sel:DWORD
	v_add3_u32 v3, v3, v6, s31
	v_add3_u32 v2, v2, v7, s31
	v_add3_u32 v0, v0, v5, s31
	v_add3_u32 v1, v1, v4, s31
	v_and_b32_e32 v3, 0xffff0000, v3
	v_and_b32_e32 v2, 0xffff0000, v2
	v_or_b32_sdwa v1, v3, v1 dst_sel:DWORD dst_unused:UNUSED_PAD src0_sel:DWORD src1_sel:WORD_1
	v_or_b32_sdwa v0, v2, v0 dst_sel:DWORD dst_unused:UNUSED_PAD src0_sel:DWORD src1_sel:WORD_1
	global_store_dwordx2 v[76:77], v[0:1], off offset:1024
	ds_read_b128 v[0:3], v150 offset:27648
	v_pk_mul_f32 v[6:7], v[104:105], v[124:125] op_sel_hi:[1,0]
	v_pk_mul_f32 v[4:5], v[106:107], v[124:125] op_sel_hi:[1,0]
	s_waitcnt lgkmcnt(0)
	v_mov_b32_e32 v9, v2
	v_mov_b32_e32 v2, v1
	v_mov_b32_e32 v8, v0
	v_pk_mul_f32 v[2:3], v[6:7], v[2:3]
	v_pk_mul_f32 v[0:1], v[4:5], v[8:9]
	v_and_b32_sdwa v6, v3, v134 dst_sel:DWORD dst_unused:UNUSED_PAD src0_sel:WORD_1 src1_sel:DWORD
	v_and_b32_sdwa v7, v2, v134 dst_sel:DWORD dst_unused:UNUSED_PAD src0_sel:WORD_1 src1_sel:DWORD
	v_and_b32_sdwa v4, v1, v134 dst_sel:DWORD dst_unused:UNUSED_PAD src0_sel:WORD_1 src1_sel:DWORD
	v_and_b32_sdwa v5, v0, v134 dst_sel:DWORD dst_unused:UNUSED_PAD src0_sel:WORD_1 src1_sel:DWORD
	v_add3_u32 v3, v3, v6, s31
	v_add3_u32 v2, v2, v7, s31
	v_add3_u32 v0, v0, v5, s31
	v_add3_u32 v1, v1, v4, s31
	v_and_b32_e32 v3, 0xffff0000, v3
	v_and_b32_e32 v2, 0xffff0000, v2
	v_or_b32_sdwa v1, v3, v1 dst_sel:DWORD dst_unused:UNUSED_PAD src0_sel:DWORD src1_sel:WORD_1
	v_or_b32_sdwa v0, v2, v0 dst_sel:DWORD dst_unused:UNUSED_PAD src0_sel:DWORD src1_sel:WORD_1
	global_store_dwordx2 v[76:77], v[0:1], off offset:1536
	ds_read_b128 v[0:3], v150 offset:28672
	v_pk_mul_f32 v[6:7], v[112:113], v[124:125] op_sel_hi:[1,0]
	v_pk_mul_f32 v[4:5], v[114:115], v[124:125] op_sel_hi:[1,0]
	s_waitcnt lgkmcnt(0)
	v_mov_b32_e32 v9, v2
	v_mov_b32_e32 v2, v1
	v_mov_b32_e32 v8, v0
	v_pk_mul_f32 v[2:3], v[6:7], v[2:3]
	v_pk_mul_f32 v[0:1], v[4:5], v[8:9]
	v_and_b32_sdwa v6, v3, v134 dst_sel:DWORD dst_unused:UNUSED_PAD src0_sel:WORD_1 src1_sel:DWORD
	v_and_b32_sdwa v7, v2, v134 dst_sel:DWORD dst_unused:UNUSED_PAD src0_sel:WORD_1 src1_sel:DWORD
	v_and_b32_sdwa v4, v1, v134 dst_sel:DWORD dst_unused:UNUSED_PAD src0_sel:WORD_1 src1_sel:DWORD
	v_and_b32_sdwa v5, v0, v134 dst_sel:DWORD dst_unused:UNUSED_PAD src0_sel:WORD_1 src1_sel:DWORD
	v_add3_u32 v3, v3, v6, s31
	v_add3_u32 v2, v2, v7, s31
	v_add3_u32 v0, v0, v5, s31
	v_add3_u32 v1, v1, v4, s31
	v_and_b32_e32 v3, 0xffff0000, v3
	v_and_b32_e32 v2, 0xffff0000, v2
	v_or_b32_sdwa v1, v3, v1 dst_sel:DWORD dst_unused:UNUSED_PAD src0_sel:DWORD src1_sel:WORD_1
	v_or_b32_sdwa v0, v2, v0 dst_sel:DWORD dst_unused:UNUSED_PAD src0_sel:DWORD src1_sel:WORD_1
	global_store_dwordx2 v[76:77], v[0:1], off offset:2048
	ds_read_b128 v[0:3], v150 offset:29696
	v_pk_mul_f32 v[6:7], v[116:117], v[124:125] op_sel_hi:[1,0]
	v_pk_mul_f32 v[4:5], v[118:119], v[124:125] op_sel_hi:[1,0]
	s_waitcnt lgkmcnt(0)
	v_mov_b32_e32 v9, v2
	v_mov_b32_e32 v2, v1
	v_mov_b32_e32 v8, v0
	v_pk_mul_f32 v[2:3], v[6:7], v[2:3]
	v_pk_mul_f32 v[0:1], v[4:5], v[8:9]
	v_and_b32_sdwa v6, v3, v134 dst_sel:DWORD dst_unused:UNUSED_PAD src0_sel:WORD_1 src1_sel:DWORD
	v_and_b32_sdwa v7, v2, v134 dst_sel:DWORD dst_unused:UNUSED_PAD src0_sel:WORD_1 src1_sel:DWORD
	v_and_b32_sdwa v4, v1, v134 dst_sel:DWORD dst_unused:UNUSED_PAD src0_sel:WORD_1 src1_sel:DWORD
	v_and_b32_sdwa v5, v0, v134 dst_sel:DWORD dst_unused:UNUSED_PAD src0_sel:WORD_1 src1_sel:DWORD
	v_add3_u32 v3, v3, v6, s31
	v_add3_u32 v2, v2, v7, s31
	v_add3_u32 v0, v0, v5, s31
	v_add3_u32 v1, v1, v4, s31
	v_and_b32_e32 v3, 0xffff0000, v3
	v_and_b32_e32 v2, 0xffff0000, v2
	v_or_b32_sdwa v1, v3, v1 dst_sel:DWORD dst_unused:UNUSED_PAD src0_sel:DWORD src1_sel:WORD_1
	v_or_b32_sdwa v0, v2, v0 dst_sel:DWORD dst_unused:UNUSED_PAD src0_sel:DWORD src1_sel:WORD_1
	global_store_dwordx2 v[76:77], v[0:1], off offset:2560
	ds_read_b128 v[0:3], v150 offset:30720
	v_mov_b32_e32 v5, v14
	v_mov_b32_e32 v14, v13
	v_mov_b32_e32 v4, v12
	v_pk_mul_f32 v[6:7], v[14:15], v[124:125] op_sel_hi:[1,0]
	v_pk_mul_f32 v[4:5], v[4:5], v[124:125] op_sel_hi:[1,0]
	s_waitcnt lgkmcnt(0)
	v_mov_b32_e32 v9, v2
	v_mov_b32_e32 v2, v1
	v_mov_b32_e32 v8, v0
	v_pk_mul_f32 v[2:3], v[6:7], v[2:3]
	v_pk_mul_f32 v[0:1], v[4:5], v[8:9]
	v_and_b32_sdwa v6, v3, v134 dst_sel:DWORD dst_unused:UNUSED_PAD src0_sel:WORD_1 src1_sel:DWORD
	v_and_b32_sdwa v7, v2, v134 dst_sel:DWORD dst_unused:UNUSED_PAD src0_sel:WORD_1 src1_sel:DWORD
	v_and_b32_sdwa v4, v1, v134 dst_sel:DWORD dst_unused:UNUSED_PAD src0_sel:WORD_1 src1_sel:DWORD
	v_and_b32_sdwa v5, v0, v134 dst_sel:DWORD dst_unused:UNUSED_PAD src0_sel:WORD_1 src1_sel:DWORD
	v_add3_u32 v3, v3, v6, s31
	v_add3_u32 v2, v2, v7, s31
	v_add3_u32 v0, v0, v5, s31
	v_add3_u32 v1, v1, v4, s31
	v_and_b32_e32 v3, 0xffff0000, v3
	v_and_b32_e32 v2, 0xffff0000, v2
	v_or_b32_sdwa v1, v3, v1 dst_sel:DWORD dst_unused:UNUSED_PAD src0_sel:DWORD src1_sel:WORD_1
	v_or_b32_sdwa v0, v2, v0 dst_sel:DWORD dst_unused:UNUSED_PAD src0_sel:DWORD src1_sel:WORD_1
	global_store_dwordx2 v[76:77], v[0:1], off offset:3072
	ds_read_b128 v[0:3], v150 offset:31744
	v_pk_mul_f32 v[6:7], v[120:121], v[124:125] op_sel_hi:[1,0]
	v_pk_mul_f32 v[4:5], v[122:123], v[124:125] op_sel_hi:[1,0]
	s_waitcnt lgkmcnt(0)
	v_mov_b32_e32 v9, v2
	v_mov_b32_e32 v2, v1
	v_mov_b32_e32 v8, v0
	v_pk_mul_f32 v[2:3], v[6:7], v[2:3]
	v_pk_mul_f32 v[0:1], v[4:5], v[8:9]
	v_and_b32_sdwa v6, v3, v134 dst_sel:DWORD dst_unused:UNUSED_PAD src0_sel:WORD_1 src1_sel:DWORD
	v_and_b32_sdwa v7, v2, v134 dst_sel:DWORD dst_unused:UNUSED_PAD src0_sel:WORD_1 src1_sel:DWORD
	v_and_b32_sdwa v4, v1, v134 dst_sel:DWORD dst_unused:UNUSED_PAD src0_sel:WORD_1 src1_sel:DWORD
	v_and_b32_sdwa v5, v0, v134 dst_sel:DWORD dst_unused:UNUSED_PAD src0_sel:WORD_1 src1_sel:DWORD
	v_add3_u32 v3, v3, v6, s31
	v_add3_u32 v2, v2, v7, s31
	v_add3_u32 v0, v0, v5, s31
	v_add3_u32 v1, v1, v4, s31
	v_and_b32_e32 v3, 0xffff0000, v3
	v_and_b32_e32 v2, 0xffff0000, v2
	v_or_b32_sdwa v1, v3, v1 dst_sel:DWORD dst_unused:UNUSED_PAD src0_sel:DWORD src1_sel:WORD_1
	v_or_b32_sdwa v0, v2, v0 dst_sel:DWORD dst_unused:UNUSED_PAD src0_sel:DWORD src1_sel:WORD_1
	global_store_dwordx2 v[76:77], v[0:1], off offset:3584
	s_branch .LBB0_1691

.LBB0_2073:
	s_cmp_gt_i32 s78, 9
	s_cselect_b64 s[2:3], -1, 0
	s_cmp_lt_i32 s79, 10
	s_cselect_b64 s[4:5], -1, 0
	s_or_b64 s[2:3], s[2:3], s[4:5]
	s_and_b64 vcc, exec, s[2:3]
	s_cbranch_vccnz .LBB0_2480
	s_mov_b64 s[2:3], s[0:1]
	s_getreg_b32 s4, hwreg(HW_REG_HW_ID, 0, 6)
	s_lshl_b32 s4, s4, 2
	s_and_b32 s4, s4, 0xfc
	s_add_i32 s4, s4, 0
	s_add_i32 s4, s4, 0x20200
	s_waitcnt vmcnt(0)
	v_mov_b32_e32 v0, s4
	ds_read_b32 v0, v0
	s_mov_b32 s4, s64
	v_mbcnt_lo_u32_b32 v1, -1, 0
	v_mbcnt_hi_u32_b32 v1, -1, v1
	s_waitcnt lgkmcnt(0)
	v_readfirstlane_b32 s5, v0
	s_nop 1
	v_lshl_add_u32 v0, s5, 6, v1
	s_load_dword s26, s[0:1], 0xa0
	v_readfirstlane_b32 s5, v0
	s_ashr_i32 s5, s5, 6
	s_add_u32 s8, s0, 0xa0
	s_addc_u32 s9, s1, 0
	s_lshl_b32 s4, s4, 3
	s_add_i32 s12, s4, s5
	s_waitcnt lgkmcnt(0)
	s_lshl_b32 s10, s26, 3
	s_cmpk_gt_i32 s12, 0x3fff
	s_cbranch_scc1 .LBB0_2077
	s_load_dwordx2 s[16:17], s[2:3], 0x8
	s_load_dwordx4 s[4:7], s[2:3], 0x80
	v_and_b32_e32 v4, 63, v0
	v_lshlrev_b32_e32 v0, 4, v4
	v_mov_b32_e32 v1, 0
	v_or_b32_e32 v2, 0x1000, v0
	v_mov_b32_e32 v3, v1
	s_waitcnt lgkmcnt(0)
	v_lshl_add_u64 v[56:57], s[4:5], 0, v[2:3]
	v_or_b32_e32 v2, 0x1400, v0
	v_lshl_add_u64 v[58:59], s[4:5], 0, v[2:3]
	v_or_b32_e32 v2, 0x1800, v0
	v_lshl_add_u64 v[60:61], s[4:5], 0, v[2:3]
	v_or_b32_e32 v2, 0x1c00, v0
	v_lshl_add_u64 v[62:63], s[4:5], 0, v[2:3]
	v_or_b32_e32 v2, 0x2000, v0
	v_lshl_add_u64 v[64:65], s[4:5], 0, v[2:3]
	v_or_b32_e32 v2, 0x2400, v0
	v_lshl_add_u64 v[66:67], s[4:5], 0, v[2:3]
	v_or_b32_e32 v2, 0x2800, v0
	v_lshl_add_u64 v[68:69], s[4:5], 0, v[2:3]
	v_or_b32_e32 v2, 0x2c00, v0
	v_lshl_add_u64 v[70:71], s[4:5], 0, v[2:3]
	v_or_b32_e32 v2, 0x3000, v0
	v_lshl_add_u64 v[72:73], s[4:5], 0, v[2:3]
	v_or_b32_e32 v2, 0x3400, v0
	v_lshl_add_u64 v[74:75], s[4:5], 0, v[2:3]
	v_or_b32_e32 v2, 0x3800, v0
	v_lshl_add_u64 v[76:77], s[4:5], 0, v[2:3]
	v_or_b32_e32 v2, 0x3c00, v0
	s_load_dwordx2 s[14:15], s[2:3], 0x90
	v_lshl_add_u64 v[78:79], s[4:5], 0, v[2:3]
	v_lshl_add_u64 v[2:3], s[16:17], 0, v[0:1]
	s_mov_b64 s[2:3], 0x4000
	v_lshl_add_u64 v[80:81], v[2:3], 0, s[2:3]
	s_mov_b64 s[2:3], 0x5000
	v_lshl_add_u64 v[82:83], v[2:3], 0, s[2:3]
	s_mov_b64 s[2:3], 0x5400
	v_lshl_add_u64 v[84:85], v[2:3], 0, s[2:3]
	s_mov_b64 s[2:3], 0x5800
	v_lshl_add_u64 v[86:87], v[2:3], 0, s[2:3]
	s_mov_b64 s[2:3], 0x5c00
	v_lshl_add_u64 v[88:89], v[2:3], 0, s[2:3]
	s_mov_b64 s[2:3], 0x6000
	v_lshl_add_u64 v[90:91], v[2:3], 0, s[2:3]
	s_mov_b64 s[2:3], 0x6400
	v_lshl_add_u64 v[92:93], v[2:3], 0, s[2:3]
	s_mov_b64 s[2:3], 0x6800
	v_lshl_add_u64 v[94:95], v[2:3], 0, s[2:3]
	s_mov_b64 s[2:3], 0x6c00
	v_lshl_add_u64 v[96:97], v[2:3], 0, s[2:3]
	s_mov_b64 s[2:3], 0x7000
	v_lshl_add_u64 v[98:99], v[2:3], 0, s[2:3]
	s_mov_b64 s[2:3], 0x7400
	v_lshl_add_u64 v[54:55], s[4:5], 0, v[0:1]
	v_lshl_add_u64 v[100:101], v[2:3], 0, s[2:3]
	s_mov_b64 s[2:3], 0x7800
	v_mbcnt_lo_u32_b32 v1, -1, 0
	v_lshl_add_u64 v[102:103], v[2:3], 0, s[2:3]
	s_mov_b64 s[2:3], 0x7c00
	v_mbcnt_hi_u32_b32 v1, -1, v1
	v_lshl_add_u64 v[104:105], v[2:3], 0, s[2:3]
	v_and_b32_e32 v2, 64, v1
	v_add_u32_e32 v2, 64, v2
	v_xor_b32_e32 v3, 1, v1
	v_cmp_lt_i32_e32 vcc, v3, v2
	s_ashr_i32 s13, s12, 31
	s_lshl_b64 s[2:3], s[12:13], 8
	v_cndmask_b32_e32 v3, v1, v3, vcc
	v_lshlrev_b32_e32 v123, 2, v3
	v_xor_b32_e32 v3, 2, v1
	v_cmp_lt_i32_e32 vcc, v3, v2
	s_ashr_i32 s11, s10, 31
	s_movk_i32 s20, 0x1000
	v_cndmask_b32_e32 v3, v1, v3, vcc
	v_lshlrev_b32_e32 v132, 2, v3
	v_xor_b32_e32 v3, 4, v1
	v_cmp_lt_i32_e32 vcc, v3, v2
	s_movk_i32 s21, 0x2000
	s_movk_i32 s22, 0x3000
	v_cndmask_b32_e32 v3, v1, v3, vcc
	v_lshlrev_b32_e32 v133, 2, v3
	v_xor_b32_e32 v3, 8, v1
	v_cmp_lt_i32_e32 vcc, v3, v2
	s_lshl_b64 s[4:5], s[10:11], 8
	s_lshl_b64 s[16:17], s[10:11], 13
	v_cndmask_b32_e32 v3, v1, v3, vcc
	v_lshlrev_b32_e32 v134, 2, v3
	v_xor_b32_e32 v3, 16, v1
	v_cmp_lt_i32_e32 vcc, v3, v2
	s_lshl_b64 s[18:19], s[10:11], 14
	v_mov_b32_e32 v137, 0x358637bd
	v_cndmask_b32_e32 v3, v1, v3, vcc
	v_lshlrev_b32_e32 v135, 2, v3
	v_xor_b32_e32 v3, 32, v1
	v_cmp_lt_i32_e32 vcc, v3, v2
	v_lshl_or_b32 v2, v4, 2, s2
	s_mov_b32 s11, 0xf800000
	v_cndmask_b32_e32 v1, v1, v3, vcc
	v_mov_b32_e32 v3, s3
	s_mov_b64 s[2:3], 0x5dc00000
	v_lshl_add_u64 v[106:107], v[2:3], 0, s[2:3]
	s_lshl_b64 s[2:3], s[12:13], 13
	v_lshl_or_b32 v108, v4, 3, s2
	v_mov_b32_e32 v109, s3
	s_lshl_b64 s[2:3], s[12:13], 14
	v_lshlrev_b32_e32 v136, 2, v1
	v_or_b32_e32 v110, s2, v0
	v_mov_b32_e32 v111, s3
	v_mov_b32_e32 v138, 0x260
	s_mov_b32 s13, 0x2a000000
	s_mov_b32 s23, 0x32000000
	s_mov_b32 s24, 0x32001000
	s_mov_b32 s25, 0x2a001000
	s_mov_b32 s27, 0x32002000
	s_mov_b32 s28, 0x32003000
	s_movk_i32 s29, 0x7fff
	s_mov_b32 s30, 0x1a000000
	s_mov_b32 s31, 0x1a001000
	v_mov_b32_e32 v139, 1
	s_add_u32 s80, s14, 0x32000000
	s_addc_u32 s81, s15, 0
	s_add_u32 s82, s14, 0x32001000
	s_addc_u32 s83, s15, 0
	s_add_u32 s84, s14, 0x32002000
	s_addc_u32 s85, s15, 0
	s_add_u32 s86, s14, 0x32003000
	s_addc_u32 s87, s15, 0
	s_add_u32 s88, s14, 0x2a000000
	s_addc_u32 s89, s15, 0
	s_add_u32 s90, s14, 0x2a001000
	s_addc_u32 s91, s15, 0
	v_mbcnt_lo_u32_b32 v154, -1, 0
	v_mbcnt_hi_u32_b32 v154, -1, v154
	v_lshlrev_b32_e32 v154, 4, v154
	global_load_dwordx4 v[160:163], v[54:55], off
	global_load_dwordx4 v[164:167], v[54:55], off offset:1024
	global_load_dwordx4 v[168:171], v[54:55], off offset:2048
	global_load_dwordx4 v[172:175], v[54:55], off offset:3072
	global_load_dwordx4 v[176:179], v[56:57], off
	global_load_dwordx4 v[180:183], v[58:59], off
	global_load_dwordx4 v[184:187], v[60:61], off
	global_load_dwordx4 v[188:191], v[62:63], off
	s_waitcnt vmcnt(0)
	ds_write_b128 v154, v[160:163] offset:0
	ds_write_b128 v154, v[164:167] offset:1024
	ds_write_b128 v154, v[168:171] offset:2048
	ds_write_b128 v154, v[172:175] offset:3072
	ds_write_b128 v154, v[176:179] offset:4096
	ds_write_b128 v154, v[180:183] offset:5120
	ds_write_b128 v154, v[184:187] offset:6144
	ds_write_b128 v154, v[188:191] offset:7168
	global_load_dwordx4 v[160:163], v[64:65], off
	global_load_dwordx4 v[164:167], v[66:67], off
	global_load_dwordx4 v[168:171], v[68:69], off
	global_load_dwordx4 v[172:175], v[70:71], off
	global_load_dwordx4 v[176:179], v[72:73], off
	global_load_dwordx4 v[180:183], v[74:75], off
	global_load_dwordx4 v[184:187], v[76:77], off
	global_load_dwordx4 v[188:191], v[78:79], off
	s_waitcnt vmcnt(0)
	ds_write_b128 v154, v[160:163] offset:8192
	ds_write_b128 v154, v[164:167] offset:9216
	ds_write_b128 v154, v[168:171] offset:10240
	ds_write_b128 v154, v[172:175] offset:11264
	ds_write_b128 v154, v[176:179] offset:12288
	ds_write_b128 v154, v[180:183] offset:13312
	ds_write_b128 v154, v[184:187] offset:14336
	ds_write_b128 v154, v[188:191] offset:15360
	global_load_dwordx4 v[160:163], v[80:81], off
	global_load_dwordx4 v[164:167], v[80:81], off offset:1024
	global_load_dwordx4 v[168:171], v[80:81], off offset:2048
	global_load_dwordx4 v[172:175], v[80:81], off offset:3072
	global_load_dwordx4 v[176:179], v[82:83], off
	global_load_dwordx4 v[180:183], v[84:85], off
	global_load_dwordx4 v[184:187], v[86:87], off
	global_load_dwordx4 v[188:191], v[88:89], off
	s_waitcnt vmcnt(0)
	ds_write_b128 v154, v[160:163] offset:16384
	ds_write_b128 v154, v[164:167] offset:17408
	ds_write_b128 v154, v[168:171] offset:18432
	ds_write_b128 v154, v[172:175] offset:19456
	ds_write_b128 v154, v[176:179] offset:20480
	ds_write_b128 v154, v[180:183] offset:21504
	ds_write_b128 v154, v[184:187] offset:22528
	ds_write_b128 v154, v[188:191] offset:23552
	global_load_dwordx4 v[160:163], v[90:91], off
	global_load_dwordx4 v[164:167], v[92:93], off
	global_load_dwordx4 v[168:171], v[94:95], off
	global_load_dwordx4 v[172:175], v[96:97], off
	global_load_dwordx4 v[176:179], v[98:99], off
	global_load_dwordx4 v[180:183], v[100:101], off
	global_load_dwordx4 v[184:187], v[102:103], off
	global_load_dwordx4 v[188:191], v[104:105], off
	s_waitcnt vmcnt(0)
	ds_write_b128 v154, v[160:163] offset:24576
	ds_write_b128 v154, v[164:167] offset:25600
	ds_write_b128 v154, v[168:171] offset:26624
	ds_write_b128 v154, v[172:175] offset:27648
	ds_write_b128 v154, v[176:179] offset:28672
	ds_write_b128 v154, v[180:183] offset:29696
	ds_write_b128 v154, v[184:187] offset:30720
	ds_write_b128 v154, v[188:191] offset:31744
	s_waitcnt lgkmcnt(0)
.LBB0_2076:
	s_waitcnt lgkmcnt(0)
	v_lshl_add_u64 v[6:7], s[14:15], 0, v[108:109]
	v_add_co_u32_e32 v28, vcc, s13, v6
	v_lshl_add_u64 v[8:9], s[14:15], 0, v[110:111]
	s_nop 0
	v_addc_co_u32_e32 v29, vcc, 0, v7, vcc
	v_add_co_u32_e32 v16, vcc, s25, v6
	v_lshl_add_u64 v[18:19], s[6:7], 0, v[110:111]
	s_nop 0
	v_addc_co_u32_e32 v17, vcc, 0, v7, vcc
	v_add_co_u32_e32 v12, vcc, s23, v8
	v_lshl_add_u64 v[4:5], s[14:15], 0, v[106:107]
	global_load_dword v14, v[4:5], off
	global_load_dwordx4 v[160:163], v110, s[80:81] offset:0
	global_load_dwordx2 v[224:225], v108, s[88:89] offset:0
	global_load_dwordx4 v[164:167], v110, s[80:81] offset:1024
	global_load_dwordx2 v[226:227], v108, s[88:89] offset:512
	global_load_dwordx4 v[168:171], v110, s[80:81] offset:2048
	global_load_dwordx2 v[228:229], v108, s[88:89] offset:1024
	global_load_dwordx4 v[172:175], v110, s[80:81] offset:3072
	global_load_dwordx2 v[230:231], v108, s[88:89] offset:1536
	global_load_dwordx4 v[176:179], v110, s[82:83] offset:0
	global_load_dwordx2 v[232:233], v108, s[88:89] offset:2048
	global_load_dwordx4 v[180:183], v110, s[82:83] offset:1024
	global_load_dwordx2 v[234:235], v108, s[88:89] offset:2560
	global_load_dwordx4 v[184:187], v110, s[82:83] offset:2048
	global_load_dwordx2 v[236:237], v108, s[88:89] offset:3072
	global_load_dwordx4 v[188:191], v110, s[82:83] offset:3072
	global_load_dwordx2 v[238:239], v108, s[88:89] offset:3584
	global_load_dwordx4 v[192:195], v110, s[84:85] offset:0
	global_load_dwordx2 v[240:241], v108, s[90:91] offset:0
	global_load_dwordx4 v[196:199], v110, s[84:85] offset:1024
	global_load_dwordx2 v[242:243], v108, s[90:91] offset:512
	global_load_dwordx4 v[200:203], v110, s[84:85] offset:2048
	global_load_dwordx2 v[244:245], v108, s[90:91] offset:1024
	global_load_dwordx4 v[204:207], v110, s[84:85] offset:3072
	global_load_dwordx2 v[246:247], v108, s[90:91] offset:1536
	global_load_dwordx4 v[208:211], v110, s[86:87] offset:0
	global_load_dwordx2 v[248:249], v108, s[90:91] offset:2048
	global_load_dwordx4 v[212:215], v110, s[86:87] offset:1024
	global_load_dwordx2 v[250:251], v108, s[90:91] offset:2560
	global_load_dwordx4 v[216:219], v110, s[86:87] offset:2048
	global_load_dwordx2 v[252:253], v108, s[90:91] offset:3072
	global_load_dwordx4 v[220:223], v110, s[86:87] offset:3072
	global_load_dwordx2 v[254:255], v108, s[90:91] offset:3584
	s_nop 0
	v_addc_co_u32_e32 v13, vcc, 0, v9, vcc
	v_add_co_u32_e32 v30, vcc, s24, v8
	ds_read_b128 v[0:3], v154 offset:0
	s_nop 0
	v_addc_co_u32_e32 v31, vcc, 0, v9, vcc
	v_add_co_u32_e32 v34, vcc, s20, v18
	s_add_i32 s12, s12, s10
	s_nop 0
	v_addc_co_u32_e32 v35, vcc, 0, v19, vcc
	v_add_co_u32_e32 v22, vcc, s21, v18
	v_lshl_add_u64 v[106:107], v[106:107], 0, s[4:5]
	s_nop 0
	v_addc_co_u32_e32 v23, vcc, 0, v19, vcc
	v_add_co_u32_e32 v32, vcc, s27, v8
	v_lshl_add_u64 v[108:109], v[108:109], 0, s[16:17]
	s_nop 0
	v_addc_co_u32_e32 v33, vcc, 0, v9, vcc
	v_add_co_u32_e32 v114, vcc, s28, v8
	v_lshl_add_u64 v[110:111], v[110:111], 0, s[18:19]
	s_nop 0
	v_addc_co_u32_e32 v115, vcc, 0, v9, vcc
	v_add_co_u32_e32 v116, vcc, s22, v18
	s_cmpk_gt_i32 s12, 0x3fff
	s_nop 0
	v_addc_co_u32_e32 v117, vcc, 0, v19, vcc
	v_add_co_u32_e32 v118, vcc, s30, v6
	s_nop 1
	v_addc_co_u32_e32 v119, vcc, 0, v7, vcc
	v_add_co_u32_e32 v112, vcc, s31, v6
	s_nop 1
	v_addc_co_u32_e32 v113, vcc, 0, v7, vcc
	s_waitcnt vmcnt(30)
	s_nop 1
	v_mov_b32_e32 v10, v224
	v_mov_b32_e32 v11, v225
	s_waitcnt vmcnt(31)
	s_nop 1
	v_mov_b32_e32 v6, v160
	v_mov_b32_e32 v7, v161
	v_mov_b32_e32 v8, v162
	v_mov_b32_e32 v9, v163
	s_waitcnt vmcnt(32) lgkmcnt(0)
	ds_bpermute_b32 v15, v123, v14
	s_waitcnt lgkmcnt(0)
	v_lshlrev_b32_e32 v4, 16, v10
	v_and_b32_e32 v5, 0xffff0000, v10
	v_lshlrev_b32_e32 v10, 16, v11
	v_and_b32_e32 v11, 0xffff0000, v11
	s_waitcnt lgkmcnt(0)
	v_add_f32_e32 v14, v14, v15
	ds_bpermute_b32 v15, v132, v14
	s_waitcnt lgkmcnt(0)
	v_add_f32_e32 v14, v14, v15
	ds_bpermute_b32 v15, v133, v14
	s_waitcnt lgkmcnt(0)
	v_add_f32_e32 v14, v14, v15
	ds_bpermute_b32 v15, v134, v14
	s_waitcnt lgkmcnt(0)
	v_add_f32_e32 v14, v14, v15
	ds_bpermute_b32 v15, v135, v14
	s_waitcnt lgkmcnt(0)
	v_add_f32_e32 v14, v14, v15
	ds_bpermute_b32 v15, v136, v14
	s_waitcnt lgkmcnt(0)
	v_add_f32_e32 v14, v14, v15
	v_fmamk_f32 v14, v14, 0x39800000, v137
	v_mul_f32_e32 v15, 0x4f800000, v14
	v_cmp_gt_f32_e32 vcc, s11, v14
	s_nop 1
	v_cndmask_b32_e32 v14, v14, v15, vcc
	v_sqrt_f32_e32 v15, v14
	s_nop 0
	v_add_u32_e32 v20, -1, v15
	v_add_u32_e32 v21, 1, v15
	v_fma_f32 v24, -v20, v15, v14
	v_fma_f32 v25, -v21, v15, v14
	v_cmp_ge_f32_e64 s[2:3], 0, v24
	s_nop 1
	v_cndmask_b32_e64 v15, v15, v20, s[2:3]
	v_cmp_lt_f32_e64 s[2:3], 0, v25
	s_nop 1
	v_cndmask_b32_e64 v15, v15, v21, s[2:3]
	v_mul_f32_e32 v20, 0x37800000, v15
	v_cndmask_b32_e32 v15, v15, v20, vcc
	v_cmp_class_f32_e32 vcc, v14, v138
	s_nop 1
	v_cndmask_b32_e32 v14, v15, v14, vcc
	v_div_scale_f32 v15, s[2:3], v14, v14, 1.0
	v_rcp_f32_e32 v21, v15
	v_div_scale_f32 v20, vcc, 1.0, v14, 1.0
	v_fma_f32 v24, -v15, v21, 1.0
	v_fmac_f32_e32 v21, v24, v21
	v_mul_f32_e32 v24, v20, v21
	v_fma_f32 v25, -v15, v24, v20
	v_fmac_f32_e32 v24, v25, v21
	v_fma_f32 v15, -v15, v24, v20
	v_div_fmas_f32 v15, v15, v21, v24
	v_div_fixup_f32 v122, v15, v14, 1.0
	v_pk_mul_f32 v[4:5], v[122:123], v[4:5] op_sel_hi:[0,1]
	v_pk_mul_f32 v[10:11], v[122:123], v[10:11] op_sel_hi:[0,1]
	s_waitcnt lgkmcnt(0)
	v_pk_fma_f32 v[0:1], v[0:1], v[4:5], v[6:7]
	v_pk_fma_f32 v[2:3], v[2:3], v[10:11], v[8:9]
	global_store_dwordx4 v[18:19], v[0:3], off
	v_mov_b32_e32 v120, v0
	v_mov_b32_e32 v121, v2
	v_mov_b32_e32 v2, v1
	s_waitcnt vmcnt(29)
	s_nop 1
	v_mov_b32_e32 v0, v226
	v_mov_b32_e32 v1, v227
	s_waitcnt vmcnt(30)
	s_nop 1
	v_mov_b32_e32 v4, v164
	v_mov_b32_e32 v5, v165
	v_mov_b32_e32 v6, v166
	v_mov_b32_e32 v7, v167
	ds_read_b128 v[8:11], v154 offset:1024
	v_pk_mul_f32 v[14:15], v[2:3], v[2:3]
	s_nop 0
	v_pk_fma_f32 v[14:15], v[120:121], v[120:121], v[14:15]
	s_nop 0
	v_pk_add_f32 v[40:41], v[14:15], v[14:15] op_sel:[0,1] op_sel_hi:[1,0]
	s_waitcnt lgkmcnt(0)
	v_lshlrev_b32_e32 v14, 16, v0
	v_and_b32_e32 v15, 0xffff0000, v0
	v_lshlrev_b32_e32 v0, 16, v1
	v_and_b32_e32 v1, 0xffff0000, v1
	v_pk_mul_f32 v[14:15], v[122:123], v[14:15] op_sel_hi:[0,1]
	v_pk_mul_f32 v[0:1], v[122:123], v[0:1] op_sel_hi:[0,1]
	s_waitcnt lgkmcnt(0)
	v_pk_fma_f32 v[4:5], v[8:9], v[14:15], v[4:5]
	v_pk_fma_f32 v[6:7], v[10:11], v[0:1], v[6:7]
	global_store_dwordx4 v[18:19], v[4:7], off offset:1024
	v_mov_b32_e32 v0, v4
	v_mov_b32_e32 v1, v6
	v_mov_b32_e32 v6, v5
	s_waitcnt vmcnt(28)
	s_nop 1
	v_mov_b32_e32 v4, v228
	v_mov_b32_e32 v5, v229
	s_waitcnt vmcnt(29)
	s_nop 1
	v_mov_b32_e32 v8, v168
	v_mov_b32_e32 v9, v169
	v_mov_b32_e32 v10, v170
	v_mov_b32_e32 v11, v171
	ds_read_b128 v[24:27], v154 offset:2048
	v_pk_mul_f32 v[14:15], v[6:7], v[6:7]
	s_nop 0
	v_pk_fma_f32 v[14:15], v[0:1], v[0:1], v[14:15]
	s_nop 0
	v_pk_add_f32 v[42:43], v[14:15], v[14:15] op_sel:[0,1] op_sel_hi:[1,0]
	s_waitcnt lgkmcnt(0)
	v_lshlrev_b32_e32 v14, 16, v4
	v_and_b32_e32 v15, 0xffff0000, v4
	v_lshlrev_b32_e32 v4, 16, v5
	v_and_b32_e32 v5, 0xffff0000, v5
	v_pk_mul_f32 v[14:15], v[122:123], v[14:15] op_sel_hi:[0,1]
	v_pk_mul_f32 v[4:5], v[122:123], v[4:5] op_sel_hi:[0,1]
	s_waitcnt lgkmcnt(0)
	v_pk_fma_f32 v[8:9], v[24:25], v[14:15], v[8:9]
	v_pk_fma_f32 v[10:11], v[26:27], v[4:5], v[10:11]
	global_store_dwordx4 v[18:19], v[8:11], off offset:2048
	s_waitcnt vmcnt(27)
	s_nop 1
	v_mov_b32_e32 v44, v230
	v_mov_b32_e32 v45, v231
	s_waitcnt vmcnt(28)
	s_nop 1
	v_mov_b32_e32 v24, v172
	v_mov_b32_e32 v25, v173
	v_mov_b32_e32 v26, v174
	v_mov_b32_e32 v27, v175
	ds_read_b128 v[36:39], v154 offset:3072
	v_mul_f32_e32 v14, v9, v9
	v_mul_f32_e32 v20, v11, v11
	v_mov_b32_e32 v4, v8
	v_mov_b32_e32 v5, v10
	v_pk_fma_f32 v[46:47], v[8:9], v[8:9], v[14:15] op_sel_hi:[1,1,0]
	v_pk_fma_f32 v[48:49], v[10:11], v[10:11], v[20:21] op_sel_hi:[1,1,0]
	v_mov_b32_e32 v10, v9
	s_waitcnt lgkmcnt(0)
	v_lshlrev_b32_e32 v8, 16, v44
	v_and_b32_e32 v9, 0xffff0000, v44
	v_lshlrev_b32_e32 v12, 16, v45
	v_and_b32_e32 v13, 0xffff0000, v45
	v_pk_mul_f32 v[8:9], v[122:123], v[8:9] op_sel_hi:[0,1]
	v_pk_mul_f32 v[14:15], v[122:123], v[12:13] op_sel_hi:[0,1]
	s_waitcnt lgkmcnt(0)
	v_pk_fma_f32 v[12:13], v[36:37], v[8:9], v[24:25]
	v_pk_fma_f32 v[14:15], v[38:39], v[14:15], v[26:27]
	global_store_dwordx4 v[18:19], v[12:15], off offset:3072
	v_pk_mul_f32 v[36:37], v[12:13], v[12:13]
	v_pk_mul_f32 v[38:39], v[14:15], v[14:15]
	v_mov_b32_e32 v8, v12
	v_mov_b32_e32 v9, v14
	v_mov_b32_e32 v14, v13
	s_waitcnt vmcnt(26)
	s_nop 1
	v_mov_b32_e32 v12, v232
	v_mov_b32_e32 v13, v233
	s_waitcnt vmcnt(27)
	s_nop 1
	v_mov_b32_e32 v18, v176
	v_mov_b32_e32 v19, v177
	v_mov_b32_e32 v20, v178
	v_mov_b32_e32 v21, v179
	ds_read_b128 v[24:27], v154 offset:4096
	v_mov_b32_e32 v41, v36
	v_mov_b32_e32 v43, v37
	v_mov_b32_e32 v47, v38
	v_mov_b32_e32 v49, v39
	v_pk_add_f32 v[36:37], v[40:41], v[42:43]
	v_pk_add_f32 v[38:39], v[46:47], v[48:49]
	s_nop 0
	v_pk_add_f32 v[36:37], v[36:37], v[38:39]
	s_nop 0
	v_pk_add_f32 v[40:41], v[36:37], v[36:37] op_sel:[0,1] op_sel_hi:[1,0]
	s_waitcnt lgkmcnt(0)
	v_lshlrev_b32_e32 v36, 16, v12
	v_and_b32_e32 v37, 0xffff0000, v12
	v_lshlrev_b32_e32 v12, 16, v13
	v_and_b32_e32 v13, 0xffff0000, v13
	v_pk_mul_f32 v[36:37], v[122:123], v[36:37] op_sel_hi:[0,1]
	v_pk_mul_f32 v[12:13], v[122:123], v[12:13] op_sel_hi:[0,1]
	s_waitcnt lgkmcnt(0)
	v_pk_fma_f32 v[18:19], v[24:25], v[36:37], v[18:19]
	v_pk_fma_f32 v[20:21], v[26:27], v[12:13], v[20:21]
	global_store_dwordx4 v[22:23], v[18:21], off offset:-4096
	v_mov_b32_e32 v12, v18
	v_mov_b32_e32 v13, v20
	v_mov_b32_e32 v20, v19
	s_waitcnt vmcnt(25)
	s_nop 1
	v_mov_b32_e32 v18, v234
	v_mov_b32_e32 v19, v235
	s_waitcnt vmcnt(26)
	s_nop 1
	v_mov_b32_e32 v24, v180
	v_mov_b32_e32 v25, v181
	v_mov_b32_e32 v26, v182
	v_mov_b32_e32 v27, v183
	ds_read_b128 v[36:39], v154 offset:5120
	v_pk_mul_f32 v[42:43], v[20:21], v[20:21]
	s_nop 0
	v_pk_fma_f32 v[42:43], v[12:13], v[12:13], v[42:43]
	s_nop 0
	v_pk_add_f32 v[46:47], v[42:43], v[42:43] op_sel:[0,1] op_sel_hi:[1,0]
	s_waitcnt lgkmcnt(0)
	v_lshlrev_b32_e32 v42, 16, v18
	v_and_b32_e32 v43, 0xffff0000, v18
	v_lshlrev_b32_e32 v18, 16, v19
	v_and_b32_e32 v19, 0xffff0000, v19
	v_pk_mul_f32 v[42:43], v[122:123], v[42:43] op_sel_hi:[0,1]
	v_pk_mul_f32 v[18:19], v[122:123], v[18:19] op_sel_hi:[0,1]
	s_waitcnt lgkmcnt(0)
	v_pk_fma_f32 v[24:25], v[36:37], v[42:43], v[24:25]
	v_pk_fma_f32 v[26:27], v[38:39], v[18:19], v[26:27]
	global_store_dwordx4 v[34:35], v[24:27], off offset:1024
	s_waitcnt vmcnt(24)
	s_nop 1
	v_mov_b32_e32 v50, v236
	v_mov_b32_e32 v51, v237
	s_waitcnt vmcnt(25)
	s_nop 1
	v_mov_b32_e32 v36, v184
	v_mov_b32_e32 v37, v185
	v_mov_b32_e32 v38, v186
	v_mov_b32_e32 v39, v187
	ds_read_b128 v[42:45], v154 offset:6144
	v_mul_f32_e32 v18, v25, v25
	v_mul_f32_e32 v48, v27, v27
	v_mov_b32_e32 v124, v24
	v_mov_b32_e32 v125, v26
	v_pk_fma_f32 v[18:19], v[24:25], v[24:25], v[18:19] op_sel_hi:[1,1,0]
	v_pk_fma_f32 v[48:49], v[26:27], v[26:27], v[48:49] op_sel_hi:[1,1,0]
	v_mov_b32_e32 v26, v25
	s_waitcnt lgkmcnt(0)
	v_lshlrev_b32_e32 v24, 16, v50
	v_and_b32_e32 v25, 0xffff0000, v50
	v_lshlrev_b32_e32 v50, 16, v51
	v_and_b32_e32 v51, 0xffff0000, v51
	v_pk_mul_f32 v[24:25], v[122:123], v[24:25] op_sel_hi:[0,1]
	v_pk_mul_f32 v[50:51], v[122:123], v[50:51] op_sel_hi:[0,1]
	s_waitcnt lgkmcnt(0)
	v_pk_fma_f32 v[42:43], v[42:43], v[24:25], v[36:37]
	v_pk_fma_f32 v[44:45], v[44:45], v[50:51], v[38:39]
	global_store_dwordx4 v[34:35], v[42:45], off offset:2048
	v_pk_mul_f32 v[24:25], v[42:43], v[42:43]
	v_pk_mul_f32 v[50:51], v[44:45], v[44:45]
	v_mov_b32_e32 v128, v42
	v_mov_b32_e32 v129, v44
	v_mov_b32_e32 v44, v43
	s_waitcnt vmcnt(23)
	s_nop 1
	v_mov_b32_e32 v42, v238
	v_mov_b32_e32 v43, v239
	s_nop 0
	s_waitcnt vmcnt(24)
	s_nop 1
	v_mov_b32_e32 v28, v188
	v_mov_b32_e32 v29, v189
	v_mov_b32_e32 v30, v190
	v_mov_b32_e32 v31, v191
	s_nop 0
	ds_read_b128 v[36:39], v154 offset:7168
	v_mov_b32_e32 v41, v24
	v_mov_b32_e32 v47, v25
	v_mov_b32_e32 v19, v50
	v_mov_b32_e32 v49, v51
	v_pk_add_f32 v[24:25], v[40:41], v[46:47]
	v_pk_add_f32 v[18:19], v[18:19], v[48:49]
	s_waitcnt lgkmcnt(0)
	v_lshlrev_b32_e32 v40, 16, v43
	v_pk_add_f32 v[18:19], v[24:25], v[18:19]
	v_lshlrev_b32_e32 v24, 16, v42
	v_and_b32_e32 v25, 0xffff0000, v42
	v_and_b32_e32 v41, 0xffff0000, v43
	v_pk_mul_f32 v[24:25], v[122:123], v[24:25] op_sel_hi:[0,1]
	v_pk_mul_f32 v[40:41], v[122:123], v[40:41] op_sel_hi:[0,1]
	s_waitcnt lgkmcnt(0)
	v_pk_fma_f32 v[46:47], v[36:37], v[24:25], v[28:29]
	v_pk_fma_f32 v[48:49], v[38:39], v[40:41], v[30:31]
	global_store_dwordx4 v[34:35], v[46:49], off offset:3072
	s_waitcnt vmcnt(22)
	s_nop 1
	v_mov_b32_e32 v24, v240
	v_mov_b32_e32 v25, v241
	s_waitcnt vmcnt(23)
	s_nop 1
	v_mov_b32_e32 v28, v192
	v_mov_b32_e32 v29, v193
	v_mov_b32_e32 v30, v194
	v_mov_b32_e32 v31, v195
	s_nop 0
	ds_read_b128 v[34:37], v154 offset:8192
	v_mov_b32_e32 v130, v46
	v_mov_b32_e32 v131, v48
	v_mov_b32_e32 v48, v47
	v_pk_mul_f32 v[38:39], v[48:49], v[48:49]
	v_pk_add_f32 v[18:19], v[18:19], v[18:19] op_sel:[0,1] op_sel_hi:[1,0]
	v_pk_fma_f32 v[38:39], v[130:131], v[130:131], v[38:39]
	s_waitcnt lgkmcnt(0)
	v_lshlrev_b32_e32 v40, 16, v24
	v_and_b32_e32 v41, 0xffff0000, v24
	v_lshlrev_b32_e32 v24, 16, v25
	v_and_b32_e32 v25, 0xffff0000, v25
	v_pk_mul_f32 v[40:41], v[122:123], v[40:41] op_sel_hi:[0,1]
	v_pk_mul_f32 v[24:25], v[122:123], v[24:25] op_sel_hi:[0,1]
	s_waitcnt lgkmcnt(0)
	v_pk_fma_f32 v[50:51], v[34:35], v[40:41], v[28:29]
	v_pk_fma_f32 v[52:53], v[36:37], v[24:25], v[30:31]
	global_store_dwordx4 v[22:23], v[50:53], off
	s_waitcnt vmcnt(21)
	s_nop 1
	v_mov_b32_e32 v42, v242
	v_mov_b32_e32 v43, v243
	s_waitcnt vmcnt(22)
	s_nop 1
	v_mov_b32_e32 v28, v196
	v_mov_b32_e32 v29, v197
	v_mov_b32_e32 v30, v198
	v_mov_b32_e32 v31, v199
	ds_read_b128 v[34:37], v154 offset:9216
	v_mul_f32_e32 v40, v53, v53
	v_pk_fma_f32 v[46:47], v[52:53], v[52:53], v[40:41] op_sel_hi:[1,1,0]
	v_mul_f32_e32 v24, v51, v51
	v_mov_b32_e32 v144, v50
	v_mov_b32_e32 v145, v52
	v_pk_fma_f32 v[24:25], v[50:51], v[50:51], v[24:25] op_sel_hi:[1,1,0]
	v_mov_b32_e32 v52, v51
	v_pk_add_f32 v[38:39], v[38:39], v[38:39] op_sel:[0,1] op_sel_hi:[1,0]
	s_waitcnt lgkmcnt(0)
	v_lshlrev_b32_e32 v40, 16, v42
	v_and_b32_e32 v41, 0xffff0000, v42
	v_lshlrev_b32_e32 v42, 16, v43
	v_and_b32_e32 v43, 0xffff0000, v43
	v_pk_mul_f32 v[40:41], v[122:123], v[40:41] op_sel_hi:[0,1]
	v_pk_mul_f32 v[42:43], v[122:123], v[42:43] op_sel_hi:[0,1]
	s_waitcnt lgkmcnt(0)
	v_pk_fma_f32 v[34:35], v[34:35], v[40:41], v[28:29]
	v_pk_fma_f32 v[36:37], v[36:37], v[42:43], v[30:31]
	global_store_dwordx4 v[22:23], v[34:37], off offset:1024
	v_pk_mul_f32 v[126:127], v[34:35], v[34:35]
	v_pk_mul_f32 v[140:141], v[36:37], v[36:37]
	v_mov_b32_e32 v50, v34
	v_mov_b32_e32 v51, v36
	v_mov_b32_e32 v36, v35
	s_waitcnt vmcnt(20)
	s_nop 1
	v_mov_b32_e32 v34, v244
	v_mov_b32_e32 v35, v245
	s_waitcnt vmcnt(21)
	s_nop 1
	v_mov_b32_e32 v28, v200
	v_mov_b32_e32 v29, v201
	v_mov_b32_e32 v30, v202
	v_mov_b32_e32 v31, v203
	ds_read_b128 v[40:43], v154 offset:10240
	v_mov_b32_e32 v19, v126
	v_mov_b32_e32 v39, v127
	v_mov_b32_e32 v25, v140
	v_mov_b32_e32 v47, v141
	v_pk_add_f32 v[18:19], v[18:19], v[38:39]
	v_pk_add_f32 v[24:25], v[24:25], v[46:47]
	s_nop 0
	v_pk_add_f32 v[18:19], v[18:19], v[24:25]
	s_waitcnt lgkmcnt(0)
	v_lshlrev_b32_e32 v24, 16, v34
	v_and_b32_e32 v25, 0xffff0000, v34
	v_lshlrev_b32_e32 v34, 16, v35
	v_and_b32_e32 v35, 0xffff0000, v35
	v_pk_mul_f32 v[24:25], v[122:123], v[24:25] op_sel_hi:[0,1]
	v_pk_mul_f32 v[34:35], v[122:123], v[34:35] op_sel_hi:[0,1]
	s_waitcnt lgkmcnt(0)
	v_pk_fma_f32 v[40:41], v[40:41], v[24:25], v[28:29]
	v_pk_fma_f32 v[42:43], v[42:43], v[34:35], v[30:31]
	global_store_dwordx4 v[22:23], v[40:43], off offset:2048
	s_waitcnt vmcnt(19)
	s_nop 1
	v_mov_b32_e32 v24, v246
	v_mov_b32_e32 v25, v247
	s_waitcnt vmcnt(20)
	s_nop 1
	v_mov_b32_e32 v28, v204
	v_mov_b32_e32 v29, v205
	v_mov_b32_e32 v30, v206
	v_mov_b32_e32 v31, v207
	s_nop 0
	ds_read_b128 v[32:35], v154 offset:11264
	v_mov_b32_e32 v127, v42
	v_mov_b32_e32 v42, v41
	v_mov_b32_e32 v126, v40
	v_pk_mul_f32 v[38:39], v[42:43], v[42:43]
	v_pk_add_f32 v[18:19], v[18:19], v[18:19] op_sel:[0,1] op_sel_hi:[1,0]
	v_pk_fma_f32 v[38:39], v[126:127], v[126:127], v[38:39]
	s_nop 0
	v_pk_add_f32 v[46:47], v[38:39], v[38:39] op_sel:[0,1] op_sel_hi:[1,0]
	s_waitcnt lgkmcnt(0)
	v_lshlrev_b32_e32 v38, 16, v24
	v_and_b32_e32 v39, 0xffff0000, v24
	v_lshlrev_b32_e32 v24, 16, v25
	v_and_b32_e32 v25, 0xffff0000, v25
	v_pk_mul_f32 v[38:39], v[122:123], v[38:39] op_sel_hi:[0,1]
	v_pk_mul_f32 v[24:25], v[122:123], v[24:25] op_sel_hi:[0,1]
	s_waitcnt lgkmcnt(0)
	v_pk_fma_f32 v[38:39], v[32:33], v[38:39], v[28:29]
	v_pk_fma_f32 v[40:41], v[34:35], v[24:25], v[30:31]
	global_store_dwordx4 v[22:23], v[38:41], off offset:3072
	s_waitcnt vmcnt(18)
	s_nop 1
	v_mov_b32_e32 v140, v248
	v_mov_b32_e32 v141, v249
	s_nop 0
	s_waitcnt vmcnt(19)
	s_nop 1
	v_mov_b32_e32 v22, v208
	v_mov_b32_e32 v23, v209
	v_mov_b32_e32 v24, v210
	v_mov_b32_e32 v25, v211
	ds_read_b128 v[28:31], v154 offset:12288
	v_mul_f32_e32 v32, v39, v39
	v_mul_f32_e32 v34, v41, v41
	v_pk_fma_f32 v[142:143], v[38:39], v[38:39], v[32:33] op_sel_hi:[1,1,0]
	v_pk_fma_f32 v[146:147], v[40:41], v[40:41], v[34:35] op_sel_hi:[1,1,0]
	s_waitcnt lgkmcnt(0)
	v_lshlrev_b32_e32 v32, 16, v140
	v_and_b32_e32 v33, 0xffff0000, v140
	v_lshlrev_b32_e32 v34, 16, v141
	v_and_b32_e32 v35, 0xffff0000, v141
	v_pk_mul_f32 v[32:33], v[122:123], v[32:33] op_sel_hi:[0,1]
	v_pk_mul_f32 v[34:35], v[122:123], v[34:35] op_sel_hi:[0,1]
	s_waitcnt lgkmcnt(0)
	v_pk_fma_f32 v[32:33], v[28:29], v[32:33], v[22:23]
	v_pk_fma_f32 v[34:35], v[30:31], v[34:35], v[24:25]
	global_store_dwordx4 v[116:117], v[32:35], off
	s_waitcnt vmcnt(17)
	s_nop 1
	v_mov_b32_e32 v150, v250
	v_mov_b32_e32 v151, v251
	s_waitcnt vmcnt(18)
	s_nop 1
	v_mov_b32_e32 v22, v212
	v_mov_b32_e32 v23, v213
	v_mov_b32_e32 v24, v214
	v_mov_b32_e32 v25, v215
	ds_read_b128 v[28:31], v154 offset:13312
	v_pk_mul_f32 v[140:141], v[32:33], v[32:33]
	v_pk_mul_f32 v[148:149], v[34:35], v[34:35]
	v_mov_b32_e32 v19, v140
	v_mov_b32_e32 v47, v141
	v_mov_b32_e32 v143, v148
	v_mov_b32_e32 v147, v149
	v_pk_add_f32 v[18:19], v[18:19], v[46:47]
	v_pk_add_f32 v[46:47], v[142:143], v[146:147]
	s_nop 0
	v_pk_add_f32 v[18:19], v[18:19], v[46:47]
	s_waitcnt lgkmcnt(0)
	v_lshlrev_b32_e32 v46, 16, v151
	v_pk_add_f32 v[146:147], v[18:19], v[18:19] op_sel:[0,1] op_sel_hi:[1,0]
	v_lshlrev_b32_e32 v18, 16, v150
	v_and_b32_e32 v19, 0xffff0000, v150
	v_and_b32_e32 v47, 0xffff0000, v151
	v_pk_mul_f32 v[18:19], v[122:123], v[18:19] op_sel_hi:[0,1]
	v_pk_mul_f32 v[46:47], v[122:123], v[46:47] op_sel_hi:[0,1]
	s_waitcnt lgkmcnt(0)
	v_pk_fma_f32 v[28:29], v[28:29], v[18:19], v[22:23]
	v_pk_fma_f32 v[30:31], v[30:31], v[46:47], v[24:25]
	global_store_dwordx4 v[116:117], v[28:31], off offset:1024
	s_waitcnt vmcnt(16)
	s_nop 1
	v_mov_b32_e32 v18, v252
	v_mov_b32_e32 v19, v253
	s_waitcnt vmcnt(17)
	s_nop 1
	v_mov_b32_e32 v22, v216
	v_mov_b32_e32 v23, v217
	v_mov_b32_e32 v24, v218
	v_mov_b32_e32 v25, v219
	ds_read_b128 v[140:143], v154 offset:14336
	v_mov_b32_e32 v47, v30
	v_mov_b32_e32 v30, v29
	v_mov_b32_e32 v46, v28
	v_pk_mul_f32 v[28:29], v[30:31], v[30:31]
	s_waitcnt lgkmcnt(0)
	v_lshlrev_b32_e32 v148, 16, v18
	v_and_b32_e32 v149, 0xffff0000, v18
	v_lshlrev_b32_e32 v18, 16, v19
	v_and_b32_e32 v19, 0xffff0000, v19
	v_pk_mul_f32 v[148:149], v[122:123], v[148:149] op_sel_hi:[0,1]
	v_pk_mul_f32 v[18:19], v[122:123], v[18:19] op_sel_hi:[0,1]
	s_waitcnt lgkmcnt(0)
	v_pk_fma_f32 v[22:23], v[140:141], v[148:149], v[22:23]
	v_pk_fma_f32 v[24:25], v[142:143], v[18:19], v[24:25]
	global_store_dwordx4 v[116:117], v[22:25], off offset:2048
	s_waitcnt vmcnt(15)
	s_nop 1
	v_mov_b32_e32 v152, v254
	v_mov_b32_e32 v153, v255
	s_nop 0
	s_waitcnt vmcnt(16)
	s_nop 1
	v_mov_b32_e32 v16, v220
	v_mov_b32_e32 v17, v221
	v_mov_b32_e32 v18, v222
	v_mov_b32_e32 v19, v223
	ds_read_b128 v[140:143], v154 offset:15360
	v_pk_fma_f32 v[28:29], v[46:47], v[46:47], v[28:29]
	v_mul_f32_e32 v148, v23, v23
	v_mul_f32_e32 v150, v25, v25
	v_pk_add_f32 v[28:29], v[28:29], v[28:29] op_sel:[0,1] op_sel_hi:[1,0]
	v_pk_fma_f32 v[148:149], v[22:23], v[22:23], v[148:149] op_sel_hi:[1,1,0]
	v_pk_fma_f32 v[150:151], v[24:25], v[24:25], v[150:151] op_sel_hi:[1,1,0]
	s_waitcnt lgkmcnt(0)
	v_lshlrev_b32_e32 v114, 16, v152
	v_and_b32_e32 v115, 0xffff0000, v152
	v_lshlrev_b32_e32 v152, 16, v153
	v_and_b32_e32 v153, 0xffff0000, v153
	v_pk_mul_f32 v[114:115], v[122:123], v[114:115] op_sel_hi:[0,1]
	v_pk_mul_f32 v[152:153], v[122:123], v[152:153] op_sel_hi:[0,1]
	s_waitcnt lgkmcnt(0)
	v_pk_fma_f32 v[16:17], v[140:141], v[114:115], v[16:17]
	v_pk_fma_f32 v[18:19], v[142:143], v[152:153], v[18:19]
	global_store_dwordx4 v[116:117], v[16:19], off offset:3072
	v_pk_mul_f32 v[114:115], v[16:17], v[16:17]
	v_pk_mul_f32 v[116:117], v[18:19], v[18:19]
	v_mov_b32_e32 v147, v114
	v_mov_b32_e32 v29, v115
	v_mov_b32_e32 v149, v116
	v_mov_b32_e32 v151, v117
	ds_read_b128 v[114:117], v154 offset:16384
	v_pk_add_f32 v[28:29], v[146:147], v[28:29]
	v_pk_add_f32 v[140:141], v[148:149], v[150:151]
	s_nop 0
	v_pk_add_f32 v[28:29], v[28:29], v[140:141]
	s_nop 0
	v_add_f32_e32 v28, v28, v29
	ds_bpermute_b32 v29, v123, v28
	s_waitcnt lgkmcnt(0)
	v_add_f32_e32 v28, v28, v29
	ds_bpermute_b32 v29, v132, v28
	s_waitcnt lgkmcnt(0)
	v_add_f32_e32 v28, v28, v29
	ds_bpermute_b32 v29, v133, v28
	s_waitcnt lgkmcnt(0)
	v_add_f32_e32 v28, v28, v29
	ds_bpermute_b32 v29, v134, v28
	s_waitcnt lgkmcnt(0)
	v_add_f32_e32 v28, v28, v29
	ds_bpermute_b32 v29, v135, v28
	s_waitcnt lgkmcnt(0)
	v_add_f32_e32 v28, v28, v29
	ds_bpermute_b32 v29, v136, v28
	s_waitcnt lgkmcnt(0)
	v_add_f32_e32 v28, v28, v29
	v_fmamk_f32 v28, v28, 0x39800000, v137
	v_mul_f32_e32 v29, 0x4f800000, v28
	v_cmp_gt_f32_e32 vcc, s11, v28
	s_nop 1
	v_cndmask_b32_e32 v28, v28, v29, vcc
	v_sqrt_f32_e32 v29, v28
	s_nop 0
	v_add_u32_e32 v122, -1, v29
	v_add_u32_e32 v140, 1, v29
	v_fma_f32 v141, -v122, v29, v28
	v_fma_f32 v142, -v140, v29, v28
	v_cmp_ge_f32_e64 s[2:3], 0, v141
	s_nop 1
	v_cndmask_b32_e64 v29, v29, v122, s[2:3]
	v_cmp_lt_f32_e64 s[2:3], 0, v142
	s_nop 1
	v_cndmask_b32_e64 v29, v29, v140, s[2:3]
	v_mul_f32_e32 v122, 0x37800000, v29
	v_cndmask_b32_e32 v29, v29, v122, vcc
	v_cmp_class_f32_e32 vcc, v28, v138
	s_nop 1
	v_cndmask_b32_e32 v28, v29, v28, vcc
	v_div_scale_f32 v29, s[2:3], v28, v28, 1.0
	v_rcp_f32_e32 v140, v29
	v_div_scale_f32 v122, vcc, 1.0, v28, 1.0
	v_fma_f32 v141, -v29, v140, 1.0
	v_fmac_f32_e32 v140, v141, v140
	v_mul_f32_e32 v141, v122, v140
	v_fma_f32 v142, -v29, v141, v122
	v_fmac_f32_e32 v141, v142, v140
	v_fma_f32 v29, -v29, v141, v122
	v_div_fmas_f32 v29, v29, v140, v141
	v_div_fixup_f32 v28, v29, v28, 1.0
	v_pk_mul_f32 v[2:3], v[2:3], v[28:29] op_sel_hi:[1,0]
	v_pk_mul_f32 v[140:141], v[0:1], v[28:29] op_sel_hi:[1,0]
	s_waitcnt lgkmcnt(0)
	v_mov_b32_e32 v1, v116
	v_mov_b32_e32 v116, v115
	v_pk_mul_f32 v[120:121], v[120:121], v[28:29] op_sel_hi:[1,0]
	v_mov_b32_e32 v0, v114
	v_pk_mul_f32 v[2:3], v[116:117], v[2:3]
	v_pk_mul_f32 v[0:1], v[0:1], v[120:121]
	v_and_b32_sdwa v115, v3, v139 dst_sel:DWORD dst_unused:UNUSED_PAD src0_sel:WORD_1 src1_sel:DWORD
	v_and_b32_sdwa v116, v2, v139 dst_sel:DWORD dst_unused:UNUSED_PAD src0_sel:WORD_1 src1_sel:DWORD
	v_pk_mul_f32 v[6:7], v[6:7], v[28:29] op_sel_hi:[1,0]
	v_pk_mul_f32 v[4:5], v[4:5], v[28:29] op_sel_hi:[1,0]
	v_pk_mul_f32 v[10:11], v[10:11], v[28:29] op_sel_hi:[1,0]
	v_pk_mul_f32 v[8:9], v[8:9], v[28:29] op_sel_hi:[1,0]
	v_pk_mul_f32 v[14:15], v[14:15], v[28:29] op_sel_hi:[1,0]
	v_pk_mul_f32 v[12:13], v[12:13], v[28:29] op_sel_hi:[1,0]
	v_pk_mul_f32 v[20:21], v[20:21], v[28:29] op_sel_hi:[1,0]
	v_pk_mul_f32 v[124:125], v[124:125], v[28:29] op_sel_hi:[1,0]
	v_pk_mul_f32 v[26:27], v[26:27], v[28:29] op_sel_hi:[1,0]
	v_pk_mul_f32 v[128:129], v[128:129], v[28:29] op_sel_hi:[1,0]
	v_pk_mul_f32 v[44:45], v[44:45], v[28:29] op_sel_hi:[1,0]
	v_pk_mul_f32 v[130:131], v[130:131], v[28:29] op_sel_hi:[1,0]
	v_pk_mul_f32 v[48:49], v[48:49], v[28:29] op_sel_hi:[1,0]
	v_pk_mul_f32 v[142:143], v[144:145], v[28:29] op_sel_hi:[1,0]
	v_pk_mul_f32 v[52:53], v[52:53], v[28:29] op_sel_hi:[1,0]
	v_and_b32_sdwa v29, v1, v139 dst_sel:DWORD dst_unused:UNUSED_PAD src0_sel:WORD_1 src1_sel:DWORD
	v_and_b32_sdwa v114, v0, v139 dst_sel:DWORD dst_unused:UNUSED_PAD src0_sel:WORD_1 src1_sel:DWORD
	v_add3_u32 v3, v3, v115, s29
	v_add3_u32 v2, v2, v116, s29
	v_add3_u32 v0, v0, v114, s29
	v_add3_u32 v1, v1, v29, s29
	v_and_b32_e32 v3, 0xffff0000, v3
	v_and_b32_e32 v2, 0xffff0000, v2
	v_or_b32_sdwa v1, v3, v1 dst_sel:DWORD dst_unused:UNUSED_PAD src0_sel:DWORD src1_sel:WORD_1
	v_or_b32_sdwa v0, v2, v0 dst_sel:DWORD dst_unused:UNUSED_PAD src0_sel:DWORD src1_sel:WORD_1
	global_store_dwordx2 v[112:113], v[0:1], off offset:-4096
	ds_read_b128 v[0:3], v154 offset:17408
	s_waitcnt lgkmcnt(0)
	v_mov_b32_e32 v115, v2
	v_mov_b32_e32 v2, v1
	v_mov_b32_e32 v114, v0
	v_pk_mul_f32 v[2:3], v[2:3], v[6:7]
	v_pk_mul_f32 v[0:1], v[114:115], v[140:141]
	v_and_b32_sdwa v29, v3, v139 dst_sel:DWORD dst_unused:UNUSED_PAD src0_sel:WORD_1 src1_sel:DWORD
	v_and_b32_sdwa v114, v2, v139 dst_sel:DWORD dst_unused:UNUSED_PAD src0_sel:WORD_1 src1_sel:DWORD
	v_and_b32_sdwa v6, v1, v139 dst_sel:DWORD dst_unused:UNUSED_PAD src0_sel:WORD_1 src1_sel:DWORD
	v_and_b32_sdwa v7, v0, v139 dst_sel:DWORD dst_unused:UNUSED_PAD src0_sel:WORD_1 src1_sel:DWORD
	v_add3_u32 v3, v3, v29, s29
	v_add3_u32 v2, v2, v114, s29
	v_add3_u32 v0, v0, v7, s29
	v_add3_u32 v1, v1, v6, s29
	v_and_b32_e32 v3, 0xffff0000, v3
	v_and_b32_e32 v2, 0xffff0000, v2
	v_or_b32_sdwa v1, v3, v1 dst_sel:DWORD dst_unused:UNUSED_PAD src0_sel:DWORD src1_sel:WORD_1
	v_or_b32_sdwa v0, v2, v0 dst_sel:DWORD dst_unused:UNUSED_PAD src0_sel:DWORD src1_sel:WORD_1
	global_store_dwordx2 v[118:119], v[0:1], off offset:512
	ds_read_b128 v[0:3], v154 offset:18432
	s_waitcnt lgkmcnt(0)
	v_mov_b32_e32 v7, v2
	v_mov_b32_e32 v2, v1
	v_mov_b32_e32 v6, v0
	v_pk_mul_f32 v[2:3], v[2:3], v[10:11]
	v_pk_mul_f32 v[0:1], v[6:7], v[4:5]
	v_and_b32_sdwa v6, v3, v139 dst_sel:DWORD dst_unused:UNUSED_PAD src0_sel:WORD_1 src1_sel:DWORD
	v_and_b32_sdwa v7, v2, v139 dst_sel:DWORD dst_unused:UNUSED_PAD src0_sel:WORD_1 src1_sel:DWORD
	v_and_b32_sdwa v4, v1, v139 dst_sel:DWORD dst_unused:UNUSED_PAD src0_sel:WORD_1 src1_sel:DWORD
	v_and_b32_sdwa v5, v0, v139 dst_sel:DWORD dst_unused:UNUSED_PAD src0_sel:WORD_1 src1_sel:DWORD
	v_add3_u32 v3, v3, v6, s29
	v_add3_u32 v2, v2, v7, s29
	v_add3_u32 v0, v0, v5, s29
	v_add3_u32 v1, v1, v4, s29
	v_and_b32_e32 v3, 0xffff0000, v3
	v_and_b32_e32 v2, 0xffff0000, v2
	v_or_b32_sdwa v1, v3, v1 dst_sel:DWORD dst_unused:UNUSED_PAD src0_sel:DWORD src1_sel:WORD_1
	v_or_b32_sdwa v0, v2, v0 dst_sel:DWORD dst_unused:UNUSED_PAD src0_sel:DWORD src1_sel:WORD_1
	global_store_dwordx2 v[118:119], v[0:1], off offset:1024
	ds_read_b128 v[0:3], v154 offset:19456
	s_waitcnt lgkmcnt(0)
	v_mov_b32_e32 v5, v2
	v_mov_b32_e32 v2, v1
	v_mov_b32_e32 v4, v0
	v_pk_mul_f32 v[2:3], v[2:3], v[14:15]
	v_pk_mul_f32 v[0:1], v[4:5], v[8:9]
	v_and_b32_sdwa v6, v3, v139 dst_sel:DWORD dst_unused:UNUSED_PAD src0_sel:WORD_1 src1_sel:DWORD
	v_and_b32_sdwa v7, v2, v139 dst_sel:DWORD dst_unused:UNUSED_PAD src0_sel:WORD_1 src1_sel:DWORD
	v_and_b32_sdwa v4, v1, v139 dst_sel:DWORD dst_unused:UNUSED_PAD src0_sel:WORD_1 src1_sel:DWORD
	v_and_b32_sdwa v5, v0, v139 dst_sel:DWORD dst_unused:UNUSED_PAD src0_sel:WORD_1 src1_sel:DWORD
	v_add3_u32 v3, v3, v6, s29
	v_add3_u32 v2, v2, v7, s29
	v_add3_u32 v0, v0, v5, s29
	v_add3_u32 v1, v1, v4, s29
	v_and_b32_e32 v3, 0xffff0000, v3
	v_and_b32_e32 v2, 0xffff0000, v2
	v_or_b32_sdwa v1, v3, v1 dst_sel:DWORD dst_unused:UNUSED_PAD src0_sel:DWORD src1_sel:WORD_1
	v_or_b32_sdwa v0, v2, v0 dst_sel:DWORD dst_unused:UNUSED_PAD src0_sel:DWORD src1_sel:WORD_1
	global_store_dwordx2 v[118:119], v[0:1], off offset:1536
	ds_read_b128 v[0:3], v154 offset:20480
	s_waitcnt lgkmcnt(0)
	v_mov_b32_e32 v5, v2
	v_mov_b32_e32 v2, v1
	v_mov_b32_e32 v4, v0
	v_pk_mul_f32 v[2:3], v[2:3], v[20:21]
	v_pk_mul_f32 v[0:1], v[4:5], v[12:13]
	v_and_b32_sdwa v6, v3, v139 dst_sel:DWORD dst_unused:UNUSED_PAD src0_sel:WORD_1 src1_sel:DWORD
	v_and_b32_sdwa v7, v2, v139 dst_sel:DWORD dst_unused:UNUSED_PAD src0_sel:WORD_1 src1_sel:DWORD
	v_and_b32_sdwa v4, v1, v139 dst_sel:DWORD dst_unused:UNUSED_PAD src0_sel:WORD_1 src1_sel:DWORD
	v_and_b32_sdwa v5, v0, v139 dst_sel:DWORD dst_unused:UNUSED_PAD src0_sel:WORD_1 src1_sel:DWORD
	v_add3_u32 v3, v3, v6, s29
	v_add3_u32 v2, v2, v7, s29
	v_add3_u32 v0, v0, v5, s29
	v_add3_u32 v1, v1, v4, s29
	v_and_b32_e32 v3, 0xffff0000, v3
	v_and_b32_e32 v2, 0xffff0000, v2
	v_or_b32_sdwa v1, v3, v1 dst_sel:DWORD dst_unused:UNUSED_PAD src0_sel:DWORD src1_sel:WORD_1
	v_or_b32_sdwa v0, v2, v0 dst_sel:DWORD dst_unused:UNUSED_PAD src0_sel:DWORD src1_sel:WORD_1
	global_store_dwordx2 v[118:119], v[0:1], off offset:2048
	ds_read_b128 v[0:3], v154 offset:21504
	s_waitcnt lgkmcnt(0)
	v_mov_b32_e32 v5, v2
	v_mov_b32_e32 v2, v1
	v_mov_b32_e32 v4, v0
	v_pk_mul_f32 v[2:3], v[2:3], v[26:27]
	v_pk_mul_f32 v[0:1], v[4:5], v[124:125]
	v_and_b32_sdwa v6, v3, v139 dst_sel:DWORD dst_unused:UNUSED_PAD src0_sel:WORD_1 src1_sel:DWORD
	v_and_b32_sdwa v7, v2, v139 dst_sel:DWORD dst_unused:UNUSED_PAD src0_sel:WORD_1 src1_sel:DWORD
	v_and_b32_sdwa v4, v1, v139 dst_sel:DWORD dst_unused:UNUSED_PAD src0_sel:WORD_1 src1_sel:DWORD
	v_and_b32_sdwa v5, v0, v139 dst_sel:DWORD dst_unused:UNUSED_PAD src0_sel:WORD_1 src1_sel:DWORD
	v_add3_u32 v3, v3, v6, s29
	v_add3_u32 v2, v2, v7, s29
	v_add3_u32 v0, v0, v5, s29
	v_add3_u32 v1, v1, v4, s29
	v_and_b32_e32 v3, 0xffff0000, v3
	v_and_b32_e32 v2, 0xffff0000, v2
	v_or_b32_sdwa v1, v3, v1 dst_sel:DWORD dst_unused:UNUSED_PAD src0_sel:DWORD src1_sel:WORD_1
	v_or_b32_sdwa v0, v2, v0 dst_sel:DWORD dst_unused:UNUSED_PAD src0_sel:DWORD src1_sel:WORD_1
	global_store_dwordx2 v[118:119], v[0:1], off offset:2560
	ds_read_b128 v[0:3], v154 offset:22528
	s_waitcnt lgkmcnt(0)
	v_mov_b32_e32 v5, v2
	v_mov_b32_e32 v2, v1
	v_mov_b32_e32 v4, v0
	v_pk_mul_f32 v[2:3], v[44:45], v[2:3]
	v_pk_mul_f32 v[0:1], v[128:129], v[4:5]
	v_and_b32_sdwa v6, v3, v139 dst_sel:DWORD dst_unused:UNUSED_PAD src0_sel:WORD_1 src1_sel:DWORD
	v_and_b32_sdwa v7, v2, v139 dst_sel:DWORD dst_unused:UNUSED_PAD src0_sel:WORD_1 src1_sel:DWORD
	v_and_b32_sdwa v4, v1, v139 dst_sel:DWORD dst_unused:UNUSED_PAD src0_sel:WORD_1 src1_sel:DWORD
	v_and_b32_sdwa v5, v0, v139 dst_sel:DWORD dst_unused:UNUSED_PAD src0_sel:WORD_1 src1_sel:DWORD
	v_add3_u32 v3, v3, v6, s29
	v_add3_u32 v2, v2, v7, s29
	v_add3_u32 v0, v0, v5, s29
	v_add3_u32 v1, v1, v4, s29
	v_and_b32_e32 v3, 0xffff0000, v3
	v_and_b32_e32 v2, 0xffff0000, v2
	v_or_b32_sdwa v1, v3, v1 dst_sel:DWORD dst_unused:UNUSED_PAD src0_sel:DWORD src1_sel:WORD_1
	v_or_b32_sdwa v0, v2, v0 dst_sel:DWORD dst_unused:UNUSED_PAD src0_sel:DWORD src1_sel:WORD_1
	global_store_dwordx2 v[118:119], v[0:1], off offset:3072
	ds_read_b128 v[0:3], v154 offset:23552
	s_waitcnt lgkmcnt(0)
	v_mov_b32_e32 v5, v2
	v_mov_b32_e32 v2, v1
	v_mov_b32_e32 v4, v0
	v_pk_mul_f32 v[2:3], v[48:49], v[2:3]
	v_pk_mul_f32 v[0:1], v[130:131], v[4:5]
	v_and_b32_sdwa v6, v3, v139 dst_sel:DWORD dst_unused:UNUSED_PAD src0_sel:WORD_1 src1_sel:DWORD
	v_and_b32_sdwa v7, v2, v139 dst_sel:DWORD dst_unused:UNUSED_PAD src0_sel:WORD_1 src1_sel:DWORD
	v_and_b32_sdwa v4, v1, v139 dst_sel:DWORD dst_unused:UNUSED_PAD src0_sel:WORD_1 src1_sel:DWORD
	v_and_b32_sdwa v5, v0, v139 dst_sel:DWORD dst_unused:UNUSED_PAD src0_sel:WORD_1 src1_sel:DWORD
	v_add3_u32 v3, v3, v6, s29
	v_add3_u32 v2, v2, v7, s29
	v_add3_u32 v0, v0, v5, s29
	v_add3_u32 v1, v1, v4, s29
	v_and_b32_e32 v3, 0xffff0000, v3
	v_and_b32_e32 v2, 0xffff0000, v2
	v_or_b32_sdwa v1, v3, v1 dst_sel:DWORD dst_unused:UNUSED_PAD src0_sel:DWORD src1_sel:WORD_1
	v_or_b32_sdwa v0, v2, v0 dst_sel:DWORD dst_unused:UNUSED_PAD src0_sel:DWORD src1_sel:WORD_1
	global_store_dwordx2 v[118:119], v[0:1], off offset:3584
	ds_read_b128 v[0:3], v154 offset:24576
	s_waitcnt lgkmcnt(0)
	v_mov_b32_e32 v5, v2
	v_mov_b32_e32 v2, v1
	v_mov_b32_e32 v4, v0
	v_pk_mul_f32 v[2:3], v[52:53], v[2:3]
	v_pk_mul_f32 v[0:1], v[142:143], v[4:5]
	v_and_b32_sdwa v6, v3, v139 dst_sel:DWORD dst_unused:UNUSED_PAD src0_sel:WORD_1 src1_sel:DWORD
	v_and_b32_sdwa v7, v2, v139 dst_sel:DWORD dst_unused:UNUSED_PAD src0_sel:WORD_1 src1_sel:DWORD
	v_and_b32_sdwa v4, v1, v139 dst_sel:DWORD dst_unused:UNUSED_PAD src0_sel:WORD_1 src1_sel:DWORD
	v_and_b32_sdwa v5, v0, v139 dst_sel:DWORD dst_unused:UNUSED_PAD src0_sel:WORD_1 src1_sel:DWORD
	v_add3_u32 v3, v3, v6, s29
	v_add3_u32 v2, v2, v7, s29
	v_add3_u32 v0, v0, v5, s29
	v_add3_u32 v1, v1, v4, s29
	v_and_b32_e32 v3, 0xffff0000, v3
	v_and_b32_e32 v2, 0xffff0000, v2
	v_or_b32_sdwa v1, v3, v1 dst_sel:DWORD dst_unused:UNUSED_PAD src0_sel:DWORD src1_sel:WORD_1
	v_or_b32_sdwa v0, v2, v0 dst_sel:DWORD dst_unused:UNUSED_PAD src0_sel:DWORD src1_sel:WORD_1
	global_store_dwordx2 v[112:113], v[0:1], off
	ds_read_b128 v[0:3], v154 offset:25600
	v_pk_mul_f32 v[6:7], v[36:37], v[28:29] op_sel_hi:[1,0]
	v_pk_mul_f32 v[4:5], v[50:51], v[28:29] op_sel_hi:[1,0]
	s_waitcnt lgkmcnt(0)
	v_mov_b32_e32 v9, v2
	v_mov_b32_e32 v2, v1
	v_mov_b32_e32 v8, v0
	v_pk_mul_f32 v[2:3], v[6:7], v[2:3]
	v_pk_mul_f32 v[0:1], v[4:5], v[8:9]
	v_and_b32_sdwa v6, v3, v139 dst_sel:DWORD dst_unused:UNUSED_PAD src0_sel:WORD_1 src1_sel:DWORD
	v_and_b32_sdwa v7, v2, v139 dst_sel:DWORD dst_unused:UNUSED_PAD src0_sel:WORD_1 src1_sel:DWORD
	v_and_b32_sdwa v4, v1, v139 dst_sel:DWORD dst_unused:UNUSED_PAD src0_sel:WORD_1 src1_sel:DWORD
	v_and_b32_sdwa v5, v0, v139 dst_sel:DWORD dst_unused:UNUSED_PAD src0_sel:WORD_1 src1_sel:DWORD
	v_add3_u32 v3, v3, v6, s29
	v_add3_u32 v2, v2, v7, s29
	v_add3_u32 v0, v0, v5, s29
	v_add3_u32 v1, v1, v4, s29
	v_and_b32_e32 v3, 0xffff0000, v3
	v_and_b32_e32 v2, 0xffff0000, v2
	v_or_b32_sdwa v1, v3, v1 dst_sel:DWORD dst_unused:UNUSED_PAD src0_sel:DWORD src1_sel:WORD_1
	v_or_b32_sdwa v0, v2, v0 dst_sel:DWORD dst_unused:UNUSED_PAD src0_sel:DWORD src1_sel:WORD_1
	global_store_dwordx2 v[112:113], v[0:1], off offset:512
	ds_read_b128 v[0:3], v154 offset:26624
	v_pk_mul_f32 v[6:7], v[42:43], v[28:29] op_sel_hi:[1,0]
	v_pk_mul_f32 v[4:5], v[126:127], v[28:29] op_sel_hi:[1,0]
	s_waitcnt lgkmcnt(0)
	v_mov_b32_e32 v9, v2
	v_mov_b32_e32 v2, v1
	v_mov_b32_e32 v8, v0
	v_pk_mul_f32 v[2:3], v[6:7], v[2:3]
	v_pk_mul_f32 v[0:1], v[4:5], v[8:9]
	v_and_b32_sdwa v6, v3, v139 dst_sel:DWORD dst_unused:UNUSED_PAD src0_sel:WORD_1 src1_sel:DWORD
	v_and_b32_sdwa v7, v2, v139 dst_sel:DWORD dst_unused:UNUSED_PAD src0_sel:WORD_1 src1_sel:DWORD
	v_and_b32_sdwa v4, v1, v139 dst_sel:DWORD dst_unused:UNUSED_PAD src0_sel:WORD_1 src1_sel:DWORD
	v_and_b32_sdwa v5, v0, v139 dst_sel:DWORD dst_unused:UNUSED_PAD src0_sel:WORD_1 src1_sel:DWORD
	v_add3_u32 v3, v3, v6, s29
	v_add3_u32 v2, v2, v7, s29
	v_add3_u32 v0, v0, v5, s29
	v_add3_u32 v1, v1, v4, s29
	v_and_b32_e32 v3, 0xffff0000, v3
	v_and_b32_e32 v2, 0xffff0000, v2
	v_or_b32_sdwa v1, v3, v1 dst_sel:DWORD dst_unused:UNUSED_PAD src0_sel:DWORD src1_sel:WORD_1
	v_or_b32_sdwa v0, v2, v0 dst_sel:DWORD dst_unused:UNUSED_PAD src0_sel:DWORD src1_sel:WORD_1
	global_store_dwordx2 v[112:113], v[0:1], off offset:1024
	ds_read_b128 v[0:3], v154 offset:27648
	v_mov_b32_e32 v5, v40
	v_mov_b32_e32 v40, v39
	v_mov_b32_e32 v4, v38
	v_pk_mul_f32 v[6:7], v[40:41], v[28:29] op_sel_hi:[1,0]
	v_pk_mul_f32 v[4:5], v[4:5], v[28:29] op_sel_hi:[1,0]
	s_waitcnt lgkmcnt(0)
	v_mov_b32_e32 v9, v2
	v_mov_b32_e32 v2, v1
	v_mov_b32_e32 v8, v0
	v_pk_mul_f32 v[2:3], v[6:7], v[2:3]
	v_pk_mul_f32 v[0:1], v[4:5], v[8:9]
	v_and_b32_sdwa v6, v3, v139 dst_sel:DWORD dst_unused:UNUSED_PAD src0_sel:WORD_1 src1_sel:DWORD
	v_and_b32_sdwa v7, v2, v139 dst_sel:DWORD dst_unused:UNUSED_PAD src0_sel:WORD_1 src1_sel:DWORD
	v_and_b32_sdwa v4, v1, v139 dst_sel:DWORD dst_unused:UNUSED_PAD src0_sel:WORD_1 src1_sel:DWORD
	v_and_b32_sdwa v5, v0, v139 dst_sel:DWORD dst_unused:UNUSED_PAD src0_sel:WORD_1 src1_sel:DWORD
	v_add3_u32 v3, v3, v6, s29
	v_add3_u32 v2, v2, v7, s29
	v_add3_u32 v0, v0, v5, s29
	v_add3_u32 v1, v1, v4, s29
	v_and_b32_e32 v3, 0xffff0000, v3
	v_and_b32_e32 v2, 0xffff0000, v2
	v_or_b32_sdwa v1, v3, v1 dst_sel:DWORD dst_unused:UNUSED_PAD src0_sel:DWORD src1_sel:WORD_1
	v_or_b32_sdwa v0, v2, v0 dst_sel:DWORD dst_unused:UNUSED_PAD src0_sel:DWORD src1_sel:WORD_1
	global_store_dwordx2 v[112:113], v[0:1], off offset:1536
	ds_read_b128 v[0:3], v154 offset:28672
	v_mov_b32_e32 v5, v34
	v_mov_b32_e32 v34, v33
	v_mov_b32_e32 v4, v32
	v_pk_mul_f32 v[6:7], v[34:35], v[28:29] op_sel_hi:[1,0]
	v_pk_mul_f32 v[4:5], v[4:5], v[28:29] op_sel_hi:[1,0]
	s_waitcnt lgkmcnt(0)
	v_mov_b32_e32 v9, v2
	v_mov_b32_e32 v2, v1
	v_mov_b32_e32 v8, v0
	v_pk_mul_f32 v[2:3], v[6:7], v[2:3]
	v_pk_mul_f32 v[0:1], v[4:5], v[8:9]
	v_and_b32_sdwa v6, v3, v139 dst_sel:DWORD dst_unused:UNUSED_PAD src0_sel:WORD_1 src1_sel:DWORD
	v_and_b32_sdwa v7, v2, v139 dst_sel:DWORD dst_unused:UNUSED_PAD src0_sel:WORD_1 src1_sel:DWORD
	v_and_b32_sdwa v4, v1, v139 dst_sel:DWORD dst_unused:UNUSED_PAD src0_sel:WORD_1 src1_sel:DWORD
	v_and_b32_sdwa v5, v0, v139 dst_sel:DWORD dst_unused:UNUSED_PAD src0_sel:WORD_1 src1_sel:DWORD
	v_add3_u32 v3, v3, v6, s29
	v_add3_u32 v2, v2, v7, s29
	v_add3_u32 v0, v0, v5, s29
	v_add3_u32 v1, v1, v4, s29
	v_and_b32_e32 v3, 0xffff0000, v3
	v_and_b32_e32 v2, 0xffff0000, v2
	v_or_b32_sdwa v1, v3, v1 dst_sel:DWORD dst_unused:UNUSED_PAD src0_sel:DWORD src1_sel:WORD_1
	v_or_b32_sdwa v0, v2, v0 dst_sel:DWORD dst_unused:UNUSED_PAD src0_sel:DWORD src1_sel:WORD_1
	global_store_dwordx2 v[112:113], v[0:1], off offset:2048
	ds_read_b128 v[0:3], v154 offset:29696
	v_pk_mul_f32 v[6:7], v[30:31], v[28:29] op_sel_hi:[1,0]
	v_pk_mul_f32 v[4:5], v[46:47], v[28:29] op_sel_hi:[1,0]
	s_waitcnt lgkmcnt(0)
	v_mov_b32_e32 v9, v2
	v_mov_b32_e32 v2, v1
	v_mov_b32_e32 v8, v0
	v_pk_mul_f32 v[2:3], v[6:7], v[2:3]
	v_pk_mul_f32 v[0:1], v[4:5], v[8:9]
	v_and_b32_sdwa v6, v3, v139 dst_sel:DWORD dst_unused:UNUSED_PAD src0_sel:WORD_1 src1_sel:DWORD
	v_and_b32_sdwa v7, v2, v139 dst_sel:DWORD dst_unused:UNUSED_PAD src0_sel:WORD_1 src1_sel:DWORD
	v_and_b32_sdwa v4, v1, v139 dst_sel:DWORD dst_unused:UNUSED_PAD src0_sel:WORD_1 src1_sel:DWORD
	v_and_b32_sdwa v5, v0, v139 dst_sel:DWORD dst_unused:UNUSED_PAD src0_sel:WORD_1 src1_sel:DWORD
	v_add3_u32 v3, v3, v6, s29
	v_add3_u32 v2, v2, v7, s29
	v_add3_u32 v0, v0, v5, s29
	v_add3_u32 v1, v1, v4, s29
	v_and_b32_e32 v3, 0xffff0000, v3
	v_and_b32_e32 v2, 0xffff0000, v2
	v_or_b32_sdwa v1, v3, v1 dst_sel:DWORD dst_unused:UNUSED_PAD src0_sel:DWORD src1_sel:WORD_1
	v_or_b32_sdwa v0, v2, v0 dst_sel:DWORD dst_unused:UNUSED_PAD src0_sel:DWORD src1_sel:WORD_1
	global_store_dwordx2 v[112:113], v[0:1], off offset:2560
	ds_read_b128 v[0:3], v154 offset:30720
	v_mov_b32_e32 v5, v24
	v_mov_b32_e32 v24, v23
	v_mov_b32_e32 v4, v22
	v_pk_mul_f32 v[6:7], v[24:25], v[28:29] op_sel_hi:[1,0]
	v_pk_mul_f32 v[4:5], v[4:5], v[28:29] op_sel_hi:[1,0]
	s_waitcnt lgkmcnt(0)
	v_mov_b32_e32 v9, v2
	v_mov_b32_e32 v2, v1
	v_mov_b32_e32 v8, v0
	v_pk_mul_f32 v[2:3], v[6:7], v[2:3]
	v_pk_mul_f32 v[0:1], v[4:5], v[8:9]
	v_and_b32_sdwa v6, v3, v139 dst_sel:DWORD dst_unused:UNUSED_PAD src0_sel:WORD_1 src1_sel:DWORD
	v_and_b32_sdwa v7, v2, v139 dst_sel:DWORD dst_unused:UNUSED_PAD src0_sel:WORD_1 src1_sel:DWORD
	v_and_b32_sdwa v4, v1, v139 dst_sel:DWORD dst_unused:UNUSED_PAD src0_sel:WORD_1 src1_sel:DWORD
	v_and_b32_sdwa v5, v0, v139 dst_sel:DWORD dst_unused:UNUSED_PAD src0_sel:WORD_1 src1_sel:DWORD
	v_add3_u32 v3, v3, v6, s29
	v_add3_u32 v2, v2, v7, s29
	v_add3_u32 v0, v0, v5, s29
	v_add3_u32 v1, v1, v4, s29
	v_and_b32_e32 v3, 0xffff0000, v3
	v_and_b32_e32 v2, 0xffff0000, v2
	v_or_b32_sdwa v1, v3, v1 dst_sel:DWORD dst_unused:UNUSED_PAD src0_sel:DWORD src1_sel:WORD_1
	v_or_b32_sdwa v0, v2, v0 dst_sel:DWORD dst_unused:UNUSED_PAD src0_sel:DWORD src1_sel:WORD_1
	global_store_dwordx2 v[112:113], v[0:1], off offset:3072
	ds_read_b128 v[0:3], v154 offset:31744
	v_mov_b32_e32 v5, v18
	v_mov_b32_e32 v18, v17
	v_mov_b32_e32 v4, v16
	v_pk_mul_f32 v[6:7], v[18:19], v[28:29] op_sel_hi:[1,0]
	v_pk_mul_f32 v[4:5], v[4:5], v[28:29] op_sel_hi:[1,0]
	s_waitcnt lgkmcnt(0)
	v_mov_b32_e32 v9, v2
	v_mov_b32_e32 v2, v1
	v_mov_b32_e32 v8, v0
	v_pk_mul_f32 v[2:3], v[6:7], v[2:3]
	v_pk_mul_f32 v[0:1], v[4:5], v[8:9]
	v_and_b32_sdwa v6, v3, v139 dst_sel:DWORD dst_unused:UNUSED_PAD src0_sel:WORD_1 src1_sel:DWORD
	v_and_b32_sdwa v7, v2, v139 dst_sel:DWORD dst_unused:UNUSED_PAD src0_sel:WORD_1 src1_sel:DWORD
	v_and_b32_sdwa v4, v1, v139 dst_sel:DWORD dst_unused:UNUSED_PAD src0_sel:WORD_1 src1_sel:DWORD
	v_and_b32_sdwa v5, v0, v139 dst_sel:DWORD dst_unused:UNUSED_PAD src0_sel:WORD_1 src1_sel:DWORD
	v_add3_u32 v3, v3, v6, s29
	v_add3_u32 v2, v2, v7, s29
	v_add3_u32 v0, v0, v5, s29
	v_add3_u32 v1, v1, v4, s29
	v_and_b32_e32 v3, 0xffff0000, v3
	v_and_b32_e32 v2, 0xffff0000, v2
	v_or_b32_sdwa v1, v3, v1 dst_sel:DWORD dst_unused:UNUSED_PAD src0_sel:DWORD src1_sel:WORD_1
	v_or_b32_sdwa v0, v2, v0 dst_sel:DWORD dst_unused:UNUSED_PAD src0_sel:DWORD src1_sel:WORD_1
	global_store_dwordx2 v[112:113], v[0:1], off offset:3584
	s_cbranch_scc0 .LBB0_2076
.LBB0_2077:
	s_barrier
	s_mov_b64 s[2:3], s[0:1]
	s_getreg_b32 s4, hwreg(HW_REG_HW_ID, 0, 6)
	s_lshl_b32 s4, s4, 2
	s_and_b32 s4, s4, 0xfc
	s_add_i32 s4, s4, 0
	s_add_i32 s4, s4, 0x20200
	v_mov_b32_e32 v0, s4
	ds_read_b32 v0, v0
	s_mov_b32 s11, s64
	v_mbcnt_lo_u32_b32 v1, -1, 0
	v_mbcnt_hi_u32_b32 v1, -1, v1
	s_waitcnt lgkmcnt(0)
	v_readfirstlane_b32 s4, v0
	s_nop 1
	v_lshl_add_u32 v0, s4, 6, v1
	s_cmp_lt_i32 s11, 0
	v_readfirstlane_b32 s4, v0
	s_cbranch_scc1 .LBB0_2241
	s_ashr_i32 s18, s4, 6
	s_lshl_b32 s4, s11, 3
	s_add_i32 s4, s18, s4
	s_add_i32 s36, s4, 0x61a8
	s_cmp_gt_i32 s36, 0x139ff
	s_cbranch_scc1 .LBB0_2241
	s_cmpk_gt_i32 s36, 0x6dff
	v_and_b32_e32 v26, 7, v0
	s_cbranch_scc0 .LBB0_2082
	s_cmpk_gt_u32 s36, 0x8dff
	s_cbranch_scc0 .LBB0_2083
	s_add_i32 s4, s36, 0x7200
	s_and_b32 s5, s4, 0xffff
	s_mul_i32 s5, s5, 0xbe83
	s_lshr_b32 s6, s5, 25
	s_mul_i32 s5, s6, 0x2b0
	s_sub_i32 s4, s4, s5
	s_and_b32 s7, s4, 0xffff
	s_lshl_b32 s12, s7, 5
	s_bitcmp0_b32 s4, 2
	s_movk_i32 s4, 0x68
	s_cselect_b32 s4, s4, 0x70
	s_add_u32 s4, s2, s4
	s_addc_u32 s5, s3, 0
	s_load_dwordx2 s[4:5], s[4:5], 0x0
	s_waitcnt lgkmcnt(0)
	s_add_u32 s4, s4, 0xac00000
	s_addc_u32 s5, s5, 0
	s_lshl_b32 s7, s7, 4
	s_and_b32 s12, s12, 0x60
	s_lshl_b32 s16, s6, 6
	s_and_b32 s6, s7, 0x3f80
	s_or_b32 s6, s6, s12
	v_lshl_or_b32 v24, v26, 2, s6
	s_mov_b64 s[6:7], 0
	s_branch .LBB0_2084

.LBB0_3746:
	s_cmp_gt_i32 s78, 15
	s_cselect_b64 s[2:3], -1, 0
	s_cmp_lt_i32 s79, 16
	s_cselect_b64 s[4:5], -1, 0
	s_or_b64 s[2:3], s[2:3], s[4:5]
	s_and_b64 vcc, exec, s[2:3]
	s_cbranch_vccnz .LBB0_3804
	s_mov_b64 s[2:3], s[0:1]
	s_getreg_b32 s4, hwreg(HW_REG_HW_ID, 0, 6)
	s_lshl_b32 s4, s4, 2
	s_and_b32 s4, s4, 0xfc
	s_add_i32 s4, s4, 0
	s_add_i32 s4, s4, 0x20200
	s_waitcnt vmcnt(0)
	v_mov_b32_e32 v0, s4
	ds_read_b32 v0, v0
	v_mbcnt_lo_u32_b32 v1, -1, 0
	v_mbcnt_hi_u32_b32 v1, -1, v1
	s_mov_b32 s4, s64
	s_waitcnt lgkmcnt(0)
	v_readfirstlane_b32 s5, v0
	s_nop 1
	v_lshl_add_u32 v0, s5, 6, v1
	s_load_dword s20, s[0:1], 0xa0
	v_readfirstlane_b32 s5, v0
	s_ashr_i32 s5, s5, 6
	s_add_u32 s12, s0, 0xa0
	s_addc_u32 s13, s1, 0
	s_lshl_b32 s4, s4, 3
	s_add_i32 s14, s4, s5
	s_cmpk_lt_i32 s14, 0x4000
	s_cbranch_scc0 .LBB0_3750
	s_load_dwordx4 s[8:11], s[2:3], 0x58
	s_load_dwordx4 s[4:7], s[2:3], 0x88
	v_and_b32_e32 v4, 63, v0
	s_waitcnt lgkmcnt(0)
	s_lshl_b32 s16, s20, 3
	v_lshlrev_b32_e32 v0, 4, v4
	s_add_u32 s8, s8, 0x4000
	v_mov_b32_e32 v1, 0
	s_addc_u32 s9, s9, 0
	v_or_b32_e32 v2, 0x400, v0
	v_mov_b32_e32 v3, v1
	v_lshl_add_u64 v[56:57], s[8:9], 0, v[2:3]
	v_or_b32_e32 v2, 0x800, v0
	v_lshl_add_u64 v[58:59], s[8:9], 0, v[2:3]
	v_or_b32_e32 v2, 0xc00, v0
	v_lshl_add_u64 v[60:61], s[8:9], 0, v[2:3]
	v_or_b32_e32 v2, 0x1000, v0
	v_lshl_add_u64 v[62:63], s[8:9], 0, v[2:3]
	v_or_b32_e32 v2, 0x1400, v0
	v_lshl_add_u64 v[64:65], s[8:9], 0, v[2:3]
	v_or_b32_e32 v2, 0x1800, v0
	v_lshl_add_u64 v[66:67], s[8:9], 0, v[2:3]
	v_or_b32_e32 v2, 0x1c00, v0
	v_lshl_add_u64 v[68:69], s[8:9], 0, v[2:3]
	v_or_b32_e32 v2, 0x2000, v0
	v_lshl_add_u64 v[70:71], s[8:9], 0, v[2:3]
	v_or_b32_e32 v2, 0x2400, v0
	v_lshl_add_u64 v[72:73], s[8:9], 0, v[2:3]
	v_or_b32_e32 v2, 0x2800, v0
	v_lshl_add_u64 v[74:75], s[8:9], 0, v[2:3]
	v_or_b32_e32 v2, 0x2c00, v0
	v_lshl_add_u64 v[76:77], s[8:9], 0, v[2:3]
	v_or_b32_e32 v2, 0x3000, v0
	v_lshl_add_u64 v[78:79], s[8:9], 0, v[2:3]
	v_or_b32_e32 v2, 0x3400, v0
	v_lshl_add_u64 v[80:81], s[8:9], 0, v[2:3]
	v_or_b32_e32 v2, 0x3800, v0
	v_lshl_add_u64 v[82:83], s[8:9], 0, v[2:3]
	v_or_b32_e32 v2, 0x3c00, v0
	s_mov_b64 s[2:3], 0x4000
	v_lshl_add_u64 v[84:85], s[8:9], 0, v[2:3]
	v_lshl_add_u64 v[2:3], s[10:11], 0, v[0:1]
	v_lshl_add_u64 v[86:87], v[2:3], 0, s[2:3]
	s_mov_b64 s[2:3], 0x5000
	v_lshl_add_u64 v[88:89], v[2:3], 0, s[2:3]
	s_mov_b64 s[2:3], 0x5400
	v_lshl_add_u64 v[90:91], v[2:3], 0, s[2:3]
	s_mov_b64 s[2:3], 0x5800
	v_lshl_add_u64 v[92:93], v[2:3], 0, s[2:3]
	s_mov_b64 s[2:3], 0x5c00
	v_lshl_add_u64 v[94:95], v[2:3], 0, s[2:3]
	s_mov_b64 s[2:3], 0x6000
	v_lshl_add_u64 v[96:97], v[2:3], 0, s[2:3]
	s_mov_b64 s[2:3], 0x6400
	v_lshl_add_u64 v[98:99], v[2:3], 0, s[2:3]
	s_mov_b64 s[2:3], 0x6800
	v_lshl_add_u64 v[100:101], v[2:3], 0, s[2:3]
	s_mov_b64 s[2:3], 0x6c00
	v_lshl_add_u64 v[102:103], v[2:3], 0, s[2:3]
	s_mov_b64 s[2:3], 0x7000
	v_lshl_add_u64 v[104:105], v[2:3], 0, s[2:3]
	s_mov_b64 s[2:3], 0x7400
	v_lshl_add_u64 v[54:55], s[8:9], 0, v[0:1]
	v_lshl_add_u64 v[106:107], v[2:3], 0, s[2:3]
	s_mov_b64 s[2:3], 0x7800
	v_mbcnt_lo_u32_b32 v1, -1, 0
	v_lshl_add_u64 v[108:109], v[2:3], 0, s[2:3]
	s_mov_b64 s[2:3], 0x7c00
	v_mbcnt_hi_u32_b32 v1, -1, v1
	v_lshl_add_u64 v[110:111], v[2:3], 0, s[2:3]
	v_and_b32_e32 v2, 64, v1
	v_add_u32_e32 v2, 64, v2
	v_xor_b32_e32 v3, 1, v1
	v_cmp_lt_i32_e32 vcc, v3, v2
	s_ashr_i32 s15, s14, 31
	s_lshl_b64 s[2:3], s[14:15], 8
	v_cndmask_b32_e32 v3, v1, v3, vcc
	v_lshlrev_b32_e32 v129, 2, v3
	v_xor_b32_e32 v3, 2, v1
	v_cmp_lt_i32_e32 vcc, v3, v2
	s_ashr_i32 s17, s16, 31
	s_movk_i32 s21, 0x1000
	v_cndmask_b32_e32 v3, v1, v3, vcc
	v_lshlrev_b32_e32 v138, 2, v3
	v_xor_b32_e32 v3, 4, v1
	v_cmp_lt_i32_e32 vcc, v3, v2
	s_movk_i32 s22, 0x2000
	s_movk_i32 s23, 0x3000
	v_cndmask_b32_e32 v3, v1, v3, vcc
	v_lshlrev_b32_e32 v139, 2, v3
	v_xor_b32_e32 v3, 8, v1
	v_cmp_lt_i32_e32 vcc, v3, v2
	s_lshl_b64 s[8:9], s[16:17], 8
	s_lshl_b64 s[10:11], s[16:17], 13
	v_cndmask_b32_e32 v3, v1, v3, vcc
	v_lshlrev_b32_e32 v140, 2, v3
	v_xor_b32_e32 v3, 16, v1
	v_cmp_lt_i32_e32 vcc, v3, v2
	s_lshl_b64 s[18:19], s[16:17], 14
	v_mov_b32_e32 v143, 0x358637bd
	v_cndmask_b32_e32 v3, v1, v3, vcc
	v_lshlrev_b32_e32 v141, 2, v3
	v_xor_b32_e32 v3, 32, v1
	v_cmp_lt_i32_e32 vcc, v3, v2
	v_lshl_or_b32 v2, v4, 2, s2
	v_mov_b32_e32 v144, 0x260
	v_cndmask_b32_e32 v1, v1, v3, vcc
	v_mov_b32_e32 v3, s3
	s_mov_b64 s[2:3], 0x5dc00000
	v_lshl_add_u64 v[112:113], v[2:3], 0, s[2:3]
	s_lshl_b64 s[2:3], s[14:15], 13
	v_lshl_or_b32 v114, v4, 3, s2
	v_mov_b32_e32 v115, s3
	s_lshl_b64 s[2:3], s[14:15], 14
	v_lshlrev_b32_e32 v142, 2, v1
	v_or_b32_e32 v116, s2, v0
	v_mov_b32_e32 v117, s3
	s_mov_b32 s15, 0xf800000
	s_mov_b32 s17, 0x2a000000
	s_mov_b32 s24, 0x32000000
	s_mov_b32 s25, 0x32001000
	s_mov_b32 s26, 0x2a001000
	s_mov_b32 s27, 0x32002000
	s_mov_b32 s28, 0x32003000
	s_movk_i32 s29, 0x7fff
	s_mov_b32 s30, 0x1a000000
	s_mov_b32 s31, 0x1a001000
	v_mov_b32_e32 v145, 1
	s_add_u32 s80, s4, 0x0
	s_addc_u32 s81, s5, 0
	s_add_u32 s82, s4, 0x1000
	s_addc_u32 s83, s5, 0
	s_add_u32 s84, s4, 0x2000
	s_addc_u32 s85, s5, 0
	s_add_u32 s86, s4, 0x3000
	s_addc_u32 s87, s5, 0
	s_add_u32 s88, s6, 0x2a000000
	s_addc_u32 s89, s7, 0
	s_add_u32 s90, s6, 0x2a001000
	s_addc_u32 s91, s7, 0
	s_movk_i32 s92, 0x260
	v_mbcnt_lo_u32_b32 v144, -1, 0
	v_mbcnt_hi_u32_b32 v144, -1, v144
	v_lshlrev_b32_e32 v144, 4, v144
	global_load_dwordx4 v[160:163], v[54:55], off
	global_load_dwordx4 v[164:167], v[56:57], off
	global_load_dwordx4 v[168:171], v[58:59], off
	global_load_dwordx4 v[172:175], v[60:61], off
	global_load_dwordx4 v[176:179], v[62:63], off
	global_load_dwordx4 v[180:183], v[64:65], off
	global_load_dwordx4 v[184:187], v[66:67], off
	global_load_dwordx4 v[188:191], v[68:69], off
	s_waitcnt vmcnt(0)
	ds_write_b128 v144, v[160:163] offset:0
	ds_write_b128 v144, v[164:167] offset:1024
	ds_write_b128 v144, v[168:171] offset:2048
	ds_write_b128 v144, v[172:175] offset:3072
	ds_write_b128 v144, v[176:179] offset:4096
	ds_write_b128 v144, v[180:183] offset:5120
	ds_write_b128 v144, v[184:187] offset:6144
	ds_write_b128 v144, v[188:191] offset:7168
	global_load_dwordx4 v[160:163], v[70:71], off
	global_load_dwordx4 v[164:167], v[72:73], off
	global_load_dwordx4 v[168:171], v[74:75], off
	global_load_dwordx4 v[172:175], v[76:77], off
	global_load_dwordx4 v[176:179], v[78:79], off
	global_load_dwordx4 v[180:183], v[80:81], off
	global_load_dwordx4 v[184:187], v[82:83], off
	global_load_dwordx4 v[188:191], v[84:85], off
	s_waitcnt vmcnt(0)
	ds_write_b128 v144, v[160:163] offset:8192
	ds_write_b128 v144, v[164:167] offset:9216
	ds_write_b128 v144, v[168:171] offset:10240
	ds_write_b128 v144, v[172:175] offset:11264
	ds_write_b128 v144, v[176:179] offset:12288
	ds_write_b128 v144, v[180:183] offset:13312
	ds_write_b128 v144, v[184:187] offset:14336
	ds_write_b128 v144, v[188:191] offset:15360
	global_load_dwordx4 v[160:163], v[86:87], off
	global_load_dwordx4 v[164:167], v[86:87], off offset:1024
	global_load_dwordx4 v[168:171], v[86:87], off offset:2048
	global_load_dwordx4 v[172:175], v[86:87], off offset:3072
	global_load_dwordx4 v[176:179], v[88:89], off
	global_load_dwordx4 v[180:183], v[90:91], off
	global_load_dwordx4 v[184:187], v[92:93], off
	global_load_dwordx4 v[188:191], v[94:95], off
	s_waitcnt vmcnt(0)
	ds_write_b128 v144, v[160:163] offset:16384
	ds_write_b128 v144, v[164:167] offset:17408
	ds_write_b128 v144, v[168:171] offset:18432
	ds_write_b128 v144, v[172:175] offset:19456
	ds_write_b128 v144, v[176:179] offset:20480
	ds_write_b128 v144, v[180:183] offset:21504
	ds_write_b128 v144, v[184:187] offset:22528
	ds_write_b128 v144, v[188:191] offset:23552
	global_load_dwordx4 v[160:163], v[96:97], off
	global_load_dwordx4 v[164:167], v[98:99], off
	global_load_dwordx4 v[168:171], v[100:101], off
	global_load_dwordx4 v[172:175], v[102:103], off
	global_load_dwordx4 v[176:179], v[104:105], off
	global_load_dwordx4 v[180:183], v[106:107], off
	global_load_dwordx4 v[184:187], v[108:109], off
	global_load_dwordx4 v[188:191], v[110:111], off
	s_waitcnt vmcnt(0)
	ds_write_b128 v144, v[160:163] offset:24576
	ds_write_b128 v144, v[164:167] offset:25600
	ds_write_b128 v144, v[168:171] offset:26624
	ds_write_b128 v144, v[172:175] offset:27648
	ds_write_b128 v144, v[176:179] offset:28672
	ds_write_b128 v144, v[180:183] offset:29696
	ds_write_b128 v144, v[184:187] offset:30720
	ds_write_b128 v144, v[188:191] offset:31744
	s_waitcnt lgkmcnt(0)
.LBB0_3749:
	v_lshl_add_u64 v[4:5], s[6:7], 0, v[112:113]
	global_load_dword v10, v[4:5], off
	global_load_dwordx4 v[160:163], v116, s[80:81] offset:0
	global_load_dwordx2 v[224:225], v114, s[88:89] offset:0
	global_load_dwordx4 v[164:167], v116, s[80:81] offset:1024
	global_load_dwordx2 v[226:227], v114, s[88:89] offset:512
	global_load_dwordx4 v[168:171], v116, s[80:81] offset:2048
	global_load_dwordx2 v[228:229], v114, s[88:89] offset:1024
	global_load_dwordx4 v[172:175], v116, s[80:81] offset:3072
	global_load_dwordx2 v[230:231], v114, s[88:89] offset:1536
	global_load_dwordx4 v[176:179], v116, s[82:83] offset:0
	global_load_dwordx2 v[232:233], v114, s[88:89] offset:2048
	global_load_dwordx4 v[180:183], v116, s[82:83] offset:1024
	global_load_dwordx2 v[234:235], v114, s[88:89] offset:2560
	global_load_dwordx4 v[184:187], v116, s[82:83] offset:2048
	global_load_dwordx2 v[236:237], v114, s[88:89] offset:3072
	global_load_dwordx4 v[188:191], v116, s[82:83] offset:3072
	global_load_dwordx2 v[238:239], v114, s[88:89] offset:3584
	global_load_dwordx4 v[192:195], v116, s[84:85] offset:0
	global_load_dwordx2 v[240:241], v114, s[90:91] offset:0
	global_load_dwordx4 v[196:199], v116, s[84:85] offset:1024
	global_load_dwordx2 v[242:243], v114, s[90:91] offset:512
	global_load_dwordx4 v[200:203], v116, s[84:85] offset:2048
	global_load_dwordx2 v[244:245], v114, s[90:91] offset:1024
	global_load_dwordx4 v[204:207], v116, s[84:85] offset:3072
	global_load_dwordx2 v[246:247], v114, s[90:91] offset:1536
	global_load_dwordx4 v[208:211], v116, s[86:87] offset:0
	global_load_dwordx2 v[248:249], v114, s[90:91] offset:2048
	global_load_dwordx4 v[212:215], v116, s[86:87] offset:1024
	global_load_dwordx2 v[250:251], v114, s[90:91] offset:2560
	global_load_dwordx4 v[216:219], v116, s[86:87] offset:2048
	global_load_dwordx2 v[252:253], v114, s[90:91] offset:3072
	global_load_dwordx4 v[220:223], v116, s[86:87] offset:3072
	global_load_dwordx2 v[254:255], v114, s[90:91] offset:3584
	v_lshl_add_u64 v[8:9], s[6:7], 0, v[114:115]
	v_add_co_u32_e32 v30, vcc, s17, v8
	v_lshl_add_u64 v[14:15], s[6:7], 0, v[116:117]
	s_nop 0
	v_addc_co_u32_e32 v31, vcc, 0, v9, vcc
	v_add_co_u32_e32 v16, vcc, s26, v8
	v_lshl_add_u64 v[12:13], s[4:5], 0, v[116:117]
	s_nop 0
	v_addc_co_u32_e32 v17, vcc, 0, v9, vcc
	v_add_co_u32_e32 v18, vcc, s24, v14
	ds_read_b128 v[0:3], v144 offset:0
	s_nop 0
	v_addc_co_u32_e32 v19, vcc, 0, v15, vcc
	v_add_co_u32_e32 v28, vcc, s25, v14
	s_add_i32 s14, s14, s16
	s_nop 0
	v_addc_co_u32_e32 v29, vcc, 0, v15, vcc
	v_add_co_u32_e32 v34, vcc, s21, v12
	v_lshl_add_u64 v[112:113], v[112:113], 0, s[8:9]
	s_nop 0
	v_addc_co_u32_e32 v35, vcc, 0, v13, vcc
	v_add_co_u32_e32 v22, vcc, s22, v12
	v_lshl_add_u64 v[114:115], v[114:115], 0, s[10:11]
	s_nop 0
	v_addc_co_u32_e32 v23, vcc, 0, v13, vcc
	v_add_co_u32_e32 v32, vcc, s27, v14
	v_lshl_add_u64 v[116:117], v[116:117], 0, s[18:19]
	s_nop 0
	v_addc_co_u32_e32 v33, vcc, 0, v15, vcc
	v_add_co_u32_e32 v120, vcc, s28, v14
	s_cmpk_gt_i32 s14, 0x3fff
	s_nop 0
	v_addc_co_u32_e32 v121, vcc, 0, v15, vcc
	v_add_co_u32_e32 v122, vcc, s23, v12
	s_nop 1
	v_addc_co_u32_e32 v123, vcc, 0, v13, vcc
	v_add_co_u32_e32 v124, vcc, s30, v8
	s_nop 1
	v_addc_co_u32_e32 v125, vcc, 0, v9, vcc
	v_add_co_u32_e32 v118, vcc, s31, v8
	s_nop 1
	v_addc_co_u32_e32 v119, vcc, 0, v9, vcc
	s_waitcnt vmcnt(30)
	s_nop 1
	v_mov_b32_e32 v8, v224
	v_mov_b32_e32 v9, v225
	s_waitcnt vmcnt(31)
	s_nop 1
	v_mov_b32_e32 v4, v160
	v_mov_b32_e32 v5, v161
	v_mov_b32_e32 v6, v162
	v_mov_b32_e32 v7, v163
	s_waitcnt vmcnt(32) lgkmcnt(0)
	ds_bpermute_b32 v11, v129, v10
	s_waitcnt lgkmcnt(0)
	v_add_f32_e32 v10, v10, v11
	ds_bpermute_b32 v11, v138, v10
	s_waitcnt lgkmcnt(0)
	v_add_f32_e32 v10, v10, v11
	ds_bpermute_b32 v11, v139, v10
	s_waitcnt lgkmcnt(0)
	v_add_f32_e32 v10, v10, v11
	ds_bpermute_b32 v11, v140, v10
	s_waitcnt lgkmcnt(0)
	v_add_f32_e32 v10, v10, v11
	ds_bpermute_b32 v11, v141, v10
	s_waitcnt lgkmcnt(0)
	v_add_f32_e32 v10, v10, v11
	ds_bpermute_b32 v11, v142, v10
	s_waitcnt lgkmcnt(0)
	v_add_f32_e32 v10, v10, v11
	v_fmamk_f32 v10, v10, 0x39800000, v143
	v_mul_f32_e32 v11, 0x4f800000, v10
	v_cmp_gt_f32_e32 vcc, s15, v10
	s_waitcnt lgkmcnt(0)
	v_lshlrev_b32_e32 v14, 16, v8
	v_cndmask_b32_e32 v10, v10, v11, vcc
	v_sqrt_f32_e32 v11, v10
	v_and_b32_e32 v15, 0xffff0000, v8
	v_lshlrev_b32_e32 v8, 16, v9
	v_and_b32_e32 v9, 0xffff0000, v9
	v_add_u32_e32 v20, -1, v11
	v_add_u32_e32 v21, 1, v11
	v_fma_f32 v24, -v20, v11, v10
	v_fma_f32 v25, -v21, v11, v10
	v_cmp_ge_f32_e64 s[2:3], 0, v24
	s_nop 1
	v_cndmask_b32_e64 v11, v11, v20, s[2:3]
	v_cmp_lt_f32_e64 s[2:3], 0, v25
	s_nop 1
	v_cndmask_b32_e64 v11, v11, v21, s[2:3]
	v_mul_f32_e32 v20, 0x37800000, v11
	v_cndmask_b32_e32 v11, v11, v20, vcc
	v_cmp_class_f32_e64 vcc, v10, s92
	s_nop 1
	v_cndmask_b32_e32 v10, v11, v10, vcc
	v_div_scale_f32 v11, s[2:3], v10, v10, 1.0
	v_rcp_f32_e32 v21, v11
	v_div_scale_f32 v20, vcc, 1.0, v10, 1.0
	v_fma_f32 v24, -v11, v21, 1.0
	v_fmac_f32_e32 v21, v24, v21
	v_mul_f32_e32 v24, v20, v21
	v_fma_f32 v25, -v11, v24, v20
	v_fmac_f32_e32 v24, v25, v21
	v_fma_f32 v11, -v11, v24, v20
	v_div_fmas_f32 v11, v11, v21, v24
	v_div_fixup_f32 v128, v11, v10, 1.0
	v_pk_mul_f32 v[10:11], v[128:129], v[14:15] op_sel_hi:[0,1]
	v_pk_mul_f32 v[8:9], v[128:129], v[8:9] op_sel_hi:[0,1]
	s_waitcnt lgkmcnt(0)
	v_pk_fma_f32 v[0:1], v[0:1], v[10:11], v[4:5]
	v_pk_fma_f32 v[2:3], v[2:3], v[8:9], v[6:7]
	global_store_dwordx4 v[28:29], v[0:3], off offset:-4096
	v_mov_b32_e32 v126, v0
	v_mov_b32_e32 v127, v2
	v_mov_b32_e32 v2, v1
	s_waitcnt vmcnt(29)
	s_nop 1
	v_mov_b32_e32 v0, v226
	v_mov_b32_e32 v1, v227
	s_waitcnt vmcnt(30)
	s_nop 1
	v_mov_b32_e32 v4, v164
	v_mov_b32_e32 v5, v165
	v_mov_b32_e32 v6, v166
	v_mov_b32_e32 v7, v167
	ds_read_b128 v[8:11], v144 offset:1024
	v_pk_mul_f32 v[14:15], v[2:3], v[2:3]
	s_nop 0
	v_pk_fma_f32 v[14:15], v[126:127], v[126:127], v[14:15]
	s_nop 0
	v_pk_add_f32 v[40:41], v[14:15], v[14:15] op_sel:[0,1] op_sel_hi:[1,0]
	s_waitcnt lgkmcnt(0)
	v_lshlrev_b32_e32 v14, 16, v0
	v_and_b32_e32 v15, 0xffff0000, v0
	v_lshlrev_b32_e32 v0, 16, v1
	v_and_b32_e32 v1, 0xffff0000, v1
	v_pk_mul_f32 v[14:15], v[128:129], v[14:15] op_sel_hi:[0,1]
	v_pk_mul_f32 v[0:1], v[128:129], v[0:1] op_sel_hi:[0,1]
	s_waitcnt lgkmcnt(0)
	v_pk_fma_f32 v[4:5], v[8:9], v[14:15], v[4:5]
	v_pk_fma_f32 v[6:7], v[10:11], v[0:1], v[6:7]
	global_store_dwordx4 v[18:19], v[4:7], off offset:1024
	v_mov_b32_e32 v0, v4
	v_mov_b32_e32 v1, v6
	v_mov_b32_e32 v6, v5
	s_waitcnt vmcnt(28)
	s_nop 1
	v_mov_b32_e32 v4, v228
	v_mov_b32_e32 v5, v229
	s_waitcnt vmcnt(29)
	s_nop 1
	v_mov_b32_e32 v8, v168
	v_mov_b32_e32 v9, v169
	v_mov_b32_e32 v10, v170
	v_mov_b32_e32 v11, v171
	ds_read_b128 v[24:27], v144 offset:2048
	v_pk_mul_f32 v[14:15], v[6:7], v[6:7]
	s_nop 0
	v_pk_fma_f32 v[14:15], v[0:1], v[0:1], v[14:15]
	s_nop 0
	v_pk_add_f32 v[42:43], v[14:15], v[14:15] op_sel:[0,1] op_sel_hi:[1,0]
	s_waitcnt lgkmcnt(0)
	v_lshlrev_b32_e32 v14, 16, v4
	v_and_b32_e32 v15, 0xffff0000, v4
	v_lshlrev_b32_e32 v4, 16, v5
	v_and_b32_e32 v5, 0xffff0000, v5
	v_pk_mul_f32 v[14:15], v[128:129], v[14:15] op_sel_hi:[0,1]
	v_pk_mul_f32 v[4:5], v[128:129], v[4:5] op_sel_hi:[0,1]
	s_waitcnt lgkmcnt(0)
	v_pk_fma_f32 v[8:9], v[24:25], v[14:15], v[8:9]
	v_pk_fma_f32 v[10:11], v[26:27], v[4:5], v[10:11]
	global_store_dwordx4 v[18:19], v[8:11], off offset:2048
	s_waitcnt vmcnt(27)
	s_nop 1
	v_mov_b32_e32 v44, v230
	v_mov_b32_e32 v45, v231
	s_waitcnt vmcnt(28)
	s_nop 1
	v_mov_b32_e32 v24, v172
	v_mov_b32_e32 v25, v173
	v_mov_b32_e32 v26, v174
	v_mov_b32_e32 v27, v175
	ds_read_b128 v[36:39], v144 offset:3072
	v_mul_f32_e32 v14, v9, v9
	v_mul_f32_e32 v20, v11, v11
	v_mov_b32_e32 v4, v8
	v_mov_b32_e32 v5, v10
	v_pk_fma_f32 v[46:47], v[8:9], v[8:9], v[14:15] op_sel_hi:[1,1,0]
	v_pk_fma_f32 v[48:49], v[10:11], v[10:11], v[20:21] op_sel_hi:[1,1,0]
	v_mov_b32_e32 v10, v9
	s_waitcnt lgkmcnt(0)
	v_lshlrev_b32_e32 v8, 16, v44
	v_and_b32_e32 v9, 0xffff0000, v44
	v_lshlrev_b32_e32 v12, 16, v45
	v_and_b32_e32 v13, 0xffff0000, v45
	v_pk_mul_f32 v[8:9], v[128:129], v[8:9] op_sel_hi:[0,1]
	v_pk_mul_f32 v[14:15], v[128:129], v[12:13] op_sel_hi:[0,1]
	s_waitcnt lgkmcnt(0)
	v_pk_fma_f32 v[12:13], v[36:37], v[8:9], v[24:25]
	v_pk_fma_f32 v[14:15], v[38:39], v[14:15], v[26:27]
	global_store_dwordx4 v[18:19], v[12:15], off offset:3072
	v_pk_mul_f32 v[36:37], v[12:13], v[12:13]
	v_pk_mul_f32 v[38:39], v[14:15], v[14:15]
	v_mov_b32_e32 v8, v12
	v_mov_b32_e32 v9, v14
	v_mov_b32_e32 v14, v13
	s_waitcnt vmcnt(26)
	s_nop 1
	v_mov_b32_e32 v12, v232
	v_mov_b32_e32 v13, v233
	s_waitcnt vmcnt(27)
	s_nop 1
	v_mov_b32_e32 v18, v176
	v_mov_b32_e32 v19, v177
	v_mov_b32_e32 v20, v178
	v_mov_b32_e32 v21, v179
	ds_read_b128 v[24:27], v144 offset:4096
	v_mov_b32_e32 v41, v36
	v_mov_b32_e32 v43, v37
	v_mov_b32_e32 v47, v38
	v_mov_b32_e32 v49, v39
	v_pk_add_f32 v[36:37], v[40:41], v[42:43]
	v_pk_add_f32 v[38:39], v[46:47], v[48:49]
	s_nop 0
	v_pk_add_f32 v[36:37], v[36:37], v[38:39]
	s_nop 0
	v_pk_add_f32 v[46:47], v[36:37], v[36:37] op_sel:[0,1] op_sel_hi:[1,0]
	s_waitcnt lgkmcnt(0)
	v_lshlrev_b32_e32 v36, 16, v12
	v_and_b32_e32 v37, 0xffff0000, v12
	v_lshlrev_b32_e32 v12, 16, v13
	v_and_b32_e32 v13, 0xffff0000, v13
	v_pk_mul_f32 v[36:37], v[128:129], v[36:37] op_sel_hi:[0,1]
	v_pk_mul_f32 v[12:13], v[128:129], v[12:13] op_sel_hi:[0,1]
	s_waitcnt lgkmcnt(0)
	v_pk_fma_f32 v[18:19], v[24:25], v[36:37], v[18:19]
	v_pk_fma_f32 v[20:21], v[26:27], v[12:13], v[20:21]
	global_store_dwordx4 v[28:29], v[18:21], off
	v_mov_b32_e32 v12, v18
	v_mov_b32_e32 v13, v20
	v_mov_b32_e32 v20, v19
	s_waitcnt vmcnt(25)
	s_nop 1
	v_mov_b32_e32 v18, v234
	v_mov_b32_e32 v19, v235
	s_waitcnt vmcnt(26)
	s_nop 1
	v_mov_b32_e32 v24, v180
	v_mov_b32_e32 v25, v181
	v_mov_b32_e32 v26, v182
	v_mov_b32_e32 v27, v183
	ds_read_b128 v[36:39], v144 offset:5120
	v_pk_mul_f32 v[40:41], v[20:21], v[20:21]
	s_nop 0
	v_pk_fma_f32 v[40:41], v[12:13], v[12:13], v[40:41]
	s_nop 0
	v_pk_add_f32 v[48:49], v[40:41], v[40:41] op_sel:[0,1] op_sel_hi:[1,0]
	s_waitcnt lgkmcnt(0)
	v_lshlrev_b32_e32 v40, 16, v18
	v_and_b32_e32 v41, 0xffff0000, v18
	v_lshlrev_b32_e32 v18, 16, v19
	v_and_b32_e32 v19, 0xffff0000, v19
	v_pk_mul_f32 v[40:41], v[128:129], v[40:41] op_sel_hi:[0,1]
	v_pk_mul_f32 v[18:19], v[128:129], v[18:19] op_sel_hi:[0,1]
	s_waitcnt lgkmcnt(0)
	v_pk_fma_f32 v[24:25], v[36:37], v[40:41], v[24:25]
	v_pk_fma_f32 v[26:27], v[38:39], v[18:19], v[26:27]
	global_store_dwordx4 v[28:29], v[24:27], off offset:1024
	s_waitcnt vmcnt(24)
	s_nop 1
	v_mov_b32_e32 v50, v236
	v_mov_b32_e32 v51, v237
	s_waitcnt vmcnt(25)
	s_nop 1
	v_mov_b32_e32 v36, v184
	v_mov_b32_e32 v37, v185
	v_mov_b32_e32 v38, v186
	v_mov_b32_e32 v39, v187
	ds_read_b128 v[42:45], v144 offset:6144
	v_mul_f32_e32 v18, v25, v25
	v_mul_f32_e32 v40, v27, v27
	v_mov_b32_e32 v130, v24
	v_mov_b32_e32 v131, v26
	v_pk_fma_f32 v[18:19], v[24:25], v[24:25], v[18:19] op_sel_hi:[1,1,0]
	v_pk_fma_f32 v[52:53], v[26:27], v[26:27], v[40:41] op_sel_hi:[1,1,0]
	v_mov_b32_e32 v26, v25
	s_waitcnt lgkmcnt(0)
	v_lshlrev_b32_e32 v24, 16, v50
	v_and_b32_e32 v25, 0xffff0000, v50
	v_lshlrev_b32_e32 v40, 16, v51
	v_and_b32_e32 v41, 0xffff0000, v51
	v_pk_mul_f32 v[24:25], v[128:129], v[24:25] op_sel_hi:[0,1]
	v_pk_mul_f32 v[40:41], v[128:129], v[40:41] op_sel_hi:[0,1]
	s_waitcnt lgkmcnt(0)
	v_pk_fma_f32 v[42:43], v[42:43], v[24:25], v[36:37]
	v_pk_fma_f32 v[44:45], v[44:45], v[40:41], v[38:39]
	global_store_dwordx4 v[28:29], v[42:45], off offset:2048
	s_waitcnt vmcnt(23)
	s_nop 1
	v_mov_b32_e32 v30, v238
	v_mov_b32_e32 v31, v239
	s_nop 0
	s_waitcnt vmcnt(24)
	s_nop 1
	v_mov_b32_e32 v34, v188
	v_mov_b32_e32 v35, v189
	v_mov_b32_e32 v36, v190
	v_mov_b32_e32 v37, v191
	s_nop 0
	ds_read_b128 v[38:41], v144 offset:7168
	v_pk_mul_f32 v[24:25], v[42:43], v[42:43]
	v_pk_mul_f32 v[50:51], v[44:45], v[44:45]
	v_mov_b32_e32 v47, v24
	v_mov_b32_e32 v49, v25
	v_mov_b32_e32 v19, v50
	v_mov_b32_e32 v53, v51
	v_pk_add_f32 v[24:25], v[46:47], v[48:49]
	v_pk_add_f32 v[18:19], v[18:19], v[52:53]
	v_mov_b32_e32 v134, v42
	v_pk_add_f32 v[18:19], v[24:25], v[18:19]
	v_mov_b32_e32 v135, v44
	v_mov_b32_e32 v44, v43
	v_pk_add_f32 v[18:19], v[18:19], v[18:19] op_sel:[0,1] op_sel_hi:[1,0]
	s_waitcnt lgkmcnt(0)
	v_lshlrev_b32_e32 v24, 16, v30
	v_and_b32_e32 v25, 0xffff0000, v30
	v_lshlrev_b32_e32 v30, 16, v31
	v_and_b32_e32 v31, 0xffff0000, v31
	v_pk_mul_f32 v[24:25], v[128:129], v[24:25] op_sel_hi:[0,1]
	v_pk_mul_f32 v[30:31], v[128:129], v[30:31] op_sel_hi:[0,1]
	s_waitcnt lgkmcnt(0)
	v_pk_fma_f32 v[46:47], v[38:39], v[24:25], v[34:35]
	v_pk_fma_f32 v[48:49], v[40:41], v[30:31], v[36:37]
	global_store_dwordx4 v[28:29], v[46:49], off offset:3072
	s_waitcnt vmcnt(22)
	s_nop 1
	v_mov_b32_e32 v24, v240
	v_mov_b32_e32 v25, v241
	s_nop 0
	s_waitcnt vmcnt(23)
	s_nop 1
	v_mov_b32_e32 v28, v192
	v_mov_b32_e32 v29, v193
	v_mov_b32_e32 v30, v194
	v_mov_b32_e32 v31, v195
	ds_read_b128 v[34:37], v144 offset:8192
	v_mov_b32_e32 v136, v46
	v_mov_b32_e32 v137, v48
	v_mov_b32_e32 v48, v47
	v_pk_mul_f32 v[38:39], v[48:49], v[48:49]
	s_waitcnt lgkmcnt(0)
	v_lshlrev_b32_e32 v40, 16, v24
	v_and_b32_e32 v41, 0xffff0000, v24
	v_lshlrev_b32_e32 v24, 16, v25
	v_and_b32_e32 v25, 0xffff0000, v25
	v_pk_mul_f32 v[40:41], v[128:129], v[40:41] op_sel_hi:[0,1]
	v_pk_mul_f32 v[24:25], v[128:129], v[24:25] op_sel_hi:[0,1]
	s_waitcnt lgkmcnt(0)
	v_pk_fma_f32 v[50:51], v[34:35], v[40:41], v[28:29]
	v_pk_fma_f32 v[52:53], v[36:37], v[24:25], v[30:31]
	global_store_dwordx4 v[120:121], v[50:53], off offset:-4096
	s_waitcnt vmcnt(21)
	s_nop 1
	v_mov_b32_e32 v42, v242
	v_mov_b32_e32 v43, v243
	s_waitcnt vmcnt(22)
	s_nop 1
	v_mov_b32_e32 v28, v196
	v_mov_b32_e32 v29, v197
	v_mov_b32_e32 v30, v198
	v_mov_b32_e32 v31, v199
	ds_read_b128 v[34:37], v144 offset:9216
	v_mul_f32_e32 v40, v53, v53
	v_pk_fma_f32 v[46:47], v[52:53], v[52:53], v[40:41] op_sel_hi:[1,1,0]
	v_mul_f32_e32 v24, v51, v51
	v_mov_b32_e32 v150, v50
	v_mov_b32_e32 v151, v52
	v_pk_fma_f32 v[24:25], v[50:51], v[50:51], v[24:25] op_sel_hi:[1,1,0]
	v_mov_b32_e32 v52, v51
	v_pk_fma_f32 v[38:39], v[136:137], v[136:137], v[38:39]
	s_waitcnt lgkmcnt(0)
	v_lshlrev_b32_e32 v40, 16, v42
	v_and_b32_e32 v41, 0xffff0000, v42
	v_lshlrev_b32_e32 v42, 16, v43
	v_and_b32_e32 v43, 0xffff0000, v43
	v_pk_mul_f32 v[40:41], v[128:129], v[40:41] op_sel_hi:[0,1]
	v_pk_mul_f32 v[42:43], v[128:129], v[42:43] op_sel_hi:[0,1]
	s_waitcnt lgkmcnt(0)
	v_pk_fma_f32 v[34:35], v[34:35], v[40:41], v[28:29]
	v_pk_fma_f32 v[36:37], v[36:37], v[42:43], v[30:31]
	global_store_dwordx4 v[32:33], v[34:37], off offset:1024
	v_pk_mul_f32 v[132:133], v[34:35], v[34:35]
	v_pk_mul_f32 v[146:147], v[36:37], v[36:37]
	v_mov_b32_e32 v50, v34
	v_mov_b32_e32 v51, v36
	v_mov_b32_e32 v36, v35
	s_waitcnt vmcnt(20)
	s_nop 1
	v_mov_b32_e32 v34, v244
	v_mov_b32_e32 v35, v245
	s_waitcnt vmcnt(21)
	s_nop 1
	v_mov_b32_e32 v28, v200
	v_mov_b32_e32 v29, v201
	v_mov_b32_e32 v30, v202
	v_mov_b32_e32 v31, v203
	ds_read_b128 v[40:43], v144 offset:10240
	v_pk_add_f32 v[38:39], v[38:39], v[38:39] op_sel:[0,1] op_sel_hi:[1,0]
	v_mov_b32_e32 v19, v132
	v_mov_b32_e32 v39, v133
	v_mov_b32_e32 v25, v146
	v_mov_b32_e32 v47, v147
	v_pk_add_f32 v[18:19], v[18:19], v[38:39]
	v_pk_add_f32 v[24:25], v[24:25], v[46:47]
	s_nop 0
	v_pk_add_f32 v[18:19], v[18:19], v[24:25]
	s_waitcnt lgkmcnt(0)
	v_lshlrev_b32_e32 v24, 16, v34
	v_and_b32_e32 v25, 0xffff0000, v34
	v_lshlrev_b32_e32 v34, 16, v35
	v_and_b32_e32 v35, 0xffff0000, v35
	v_pk_mul_f32 v[24:25], v[128:129], v[24:25] op_sel_hi:[0,1]
	v_pk_mul_f32 v[34:35], v[128:129], v[34:35] op_sel_hi:[0,1]
	s_waitcnt lgkmcnt(0)
	v_pk_fma_f32 v[40:41], v[40:41], v[24:25], v[28:29]
	v_pk_fma_f32 v[42:43], v[42:43], v[34:35], v[30:31]
	global_store_dwordx4 v[32:33], v[40:43], off offset:2048
	s_waitcnt vmcnt(19)
	s_nop 1
	v_mov_b32_e32 v34, v246
	v_mov_b32_e32 v35, v247
	s_nop 0
	s_waitcnt vmcnt(20)
	s_nop 1
	v_mov_b32_e32 v22, v204
	v_mov_b32_e32 v23, v205
	v_mov_b32_e32 v24, v206
	v_mov_b32_e32 v25, v207
	s_nop 0
	ds_read_b128 v[28:31], v144 offset:11264
	v_mov_b32_e32 v133, v42
	v_mov_b32_e32 v42, v41
	v_mov_b32_e32 v132, v40
	v_pk_mul_f32 v[38:39], v[42:43], v[42:43]
	v_pk_add_f32 v[18:19], v[18:19], v[18:19] op_sel:[0,1] op_sel_hi:[1,0]
	v_pk_fma_f32 v[38:39], v[132:133], v[132:133], v[38:39]
	s_nop 0
	v_pk_add_f32 v[46:47], v[38:39], v[38:39] op_sel:[0,1] op_sel_hi:[1,0]
	s_waitcnt lgkmcnt(0)
	v_lshlrev_b32_e32 v38, 16, v34
	v_and_b32_e32 v39, 0xffff0000, v34
	v_lshlrev_b32_e32 v34, 16, v35
	v_and_b32_e32 v35, 0xffff0000, v35
	v_pk_mul_f32 v[38:39], v[128:129], v[38:39] op_sel_hi:[0,1]
	v_pk_mul_f32 v[34:35], v[128:129], v[34:35] op_sel_hi:[0,1]
	s_waitcnt lgkmcnt(0)
	v_pk_fma_f32 v[38:39], v[28:29], v[38:39], v[22:23]
	v_pk_fma_f32 v[40:41], v[30:31], v[34:35], v[24:25]
	global_store_dwordx4 v[32:33], v[38:41], off offset:3072
	s_waitcnt vmcnt(18)
	s_nop 1
	v_mov_b32_e32 v146, v248
	v_mov_b32_e32 v147, v249
	s_waitcnt vmcnt(19)
	s_nop 1
	v_mov_b32_e32 v22, v208
	v_mov_b32_e32 v23, v209
	v_mov_b32_e32 v24, v210
	v_mov_b32_e32 v25, v211
	ds_read_b128 v[28:31], v144 offset:12288
	v_mul_f32_e32 v32, v39, v39
	v_mul_f32_e32 v34, v41, v41
	v_pk_fma_f32 v[148:149], v[38:39], v[38:39], v[32:33] op_sel_hi:[1,1,0]
	v_pk_fma_f32 v[152:153], v[40:41], v[40:41], v[34:35] op_sel_hi:[1,1,0]
	s_waitcnt lgkmcnt(0)
	v_lshlrev_b32_e32 v32, 16, v146
	v_and_b32_e32 v33, 0xffff0000, v146
	v_lshlrev_b32_e32 v34, 16, v147
	v_and_b32_e32 v35, 0xffff0000, v147
	v_pk_mul_f32 v[32:33], v[128:129], v[32:33] op_sel_hi:[0,1]
	v_pk_mul_f32 v[34:35], v[128:129], v[34:35] op_sel_hi:[0,1]
	s_waitcnt lgkmcnt(0)
	v_pk_fma_f32 v[32:33], v[28:29], v[32:33], v[22:23]
	v_pk_fma_f32 v[34:35], v[30:31], v[34:35], v[24:25]
	global_store_dwordx4 v[120:121], v[32:35], off
	s_waitcnt vmcnt(17)
	s_nop 1
	v_mov_b32_e32 v156, v250
	v_mov_b32_e32 v157, v251
	s_waitcnt vmcnt(18)
	s_nop 1
	v_mov_b32_e32 v22, v212
	v_mov_b32_e32 v23, v213
	v_mov_b32_e32 v24, v214
	v_mov_b32_e32 v25, v215
	ds_read_b128 v[28:31], v144 offset:13312
	v_pk_mul_f32 v[146:147], v[32:33], v[32:33]
	v_pk_mul_f32 v[154:155], v[34:35], v[34:35]
	v_mov_b32_e32 v19, v146
	v_mov_b32_e32 v47, v147
	v_mov_b32_e32 v149, v154
	v_mov_b32_e32 v153, v155
	v_pk_add_f32 v[18:19], v[18:19], v[46:47]
	v_pk_add_f32 v[46:47], v[148:149], v[152:153]
	s_nop 0
	v_pk_add_f32 v[18:19], v[18:19], v[46:47]
	s_waitcnt lgkmcnt(0)
	v_lshlrev_b32_e32 v46, 16, v157
	v_pk_add_f32 v[152:153], v[18:19], v[18:19] op_sel:[0,1] op_sel_hi:[1,0]
	v_lshlrev_b32_e32 v18, 16, v156
	v_and_b32_e32 v19, 0xffff0000, v156
	v_and_b32_e32 v47, 0xffff0000, v157
	v_pk_mul_f32 v[18:19], v[128:129], v[18:19] op_sel_hi:[0,1]
	v_pk_mul_f32 v[46:47], v[128:129], v[46:47] op_sel_hi:[0,1]
	s_waitcnt lgkmcnt(0)
	v_pk_fma_f32 v[28:29], v[28:29], v[18:19], v[22:23]
	v_pk_fma_f32 v[30:31], v[30:31], v[46:47], v[24:25]
	global_store_dwordx4 v[120:121], v[28:31], off offset:1024
	s_waitcnt vmcnt(16)
	s_nop 1
	v_mov_b32_e32 v18, v252
	v_mov_b32_e32 v19, v253
	s_waitcnt vmcnt(17)
	s_nop 1
	v_mov_b32_e32 v22, v216
	v_mov_b32_e32 v23, v217
	v_mov_b32_e32 v24, v218
	v_mov_b32_e32 v25, v219
	ds_read_b128 v[146:149], v144 offset:14336
	v_mov_b32_e32 v47, v30
	v_mov_b32_e32 v30, v29
	v_mov_b32_e32 v46, v28
	v_pk_mul_f32 v[28:29], v[30:31], v[30:31]
	s_waitcnt lgkmcnt(0)
	v_lshlrev_b32_e32 v154, 16, v18
	v_and_b32_e32 v155, 0xffff0000, v18
	v_lshlrev_b32_e32 v18, 16, v19
	v_and_b32_e32 v19, 0xffff0000, v19
	v_pk_mul_f32 v[154:155], v[128:129], v[154:155] op_sel_hi:[0,1]
	v_pk_mul_f32 v[18:19], v[128:129], v[18:19] op_sel_hi:[0,1]
	s_waitcnt lgkmcnt(0)
	v_pk_fma_f32 v[22:23], v[146:147], v[154:155], v[22:23]
	v_pk_fma_f32 v[24:25], v[148:149], v[18:19], v[24:25]
	global_store_dwordx4 v[120:121], v[22:25], off offset:2048
	s_waitcnt vmcnt(15)
	s_nop 1
	v_mov_b32_e32 v158, v254
	v_mov_b32_e32 v159, v255
	s_nop 0
	s_waitcnt vmcnt(16)
	s_nop 1
	v_mov_b32_e32 v16, v220
	v_mov_b32_e32 v17, v221
	v_mov_b32_e32 v18, v222
	v_mov_b32_e32 v19, v223
	ds_read_b128 v[146:149], v144 offset:15360
	v_pk_fma_f32 v[28:29], v[46:47], v[46:47], v[28:29]
	v_mul_f32_e32 v154, v23, v23
	v_mul_f32_e32 v156, v25, v25
	v_pk_add_f32 v[28:29], v[28:29], v[28:29] op_sel:[0,1] op_sel_hi:[1,0]
	v_pk_fma_f32 v[154:155], v[22:23], v[22:23], v[154:155] op_sel_hi:[1,1,0]
	v_pk_fma_f32 v[156:157], v[24:25], v[24:25], v[156:157] op_sel_hi:[1,1,0]
	s_waitcnt lgkmcnt(0)
	v_lshlrev_b32_e32 v122, 16, v158
	v_and_b32_e32 v123, 0xffff0000, v158
	v_lshlrev_b32_e32 v158, 16, v159
	v_and_b32_e32 v159, 0xffff0000, v159
	v_pk_mul_f32 v[122:123], v[128:129], v[122:123] op_sel_hi:[0,1]
	v_pk_mul_f32 v[158:159], v[128:129], v[158:159] op_sel_hi:[0,1]
	s_waitcnt lgkmcnt(0)
	v_pk_fma_f32 v[16:17], v[146:147], v[122:123], v[16:17]
	v_pk_fma_f32 v[18:19], v[148:149], v[158:159], v[18:19]
	global_store_dwordx4 v[120:121], v[16:19], off offset:3072
	v_pk_mul_f32 v[120:121], v[16:17], v[16:17]
	v_pk_mul_f32 v[122:123], v[18:19], v[18:19]
	v_mov_b32_e32 v153, v120
	v_mov_b32_e32 v29, v121
	v_mov_b32_e32 v155, v122
	v_mov_b32_e32 v157, v123
	ds_read_b128 v[120:123], v144 offset:16384
	v_pk_add_f32 v[28:29], v[152:153], v[28:29]
	v_pk_add_f32 v[146:147], v[154:155], v[156:157]
	s_nop 0
	v_pk_add_f32 v[28:29], v[28:29], v[146:147]
	s_nop 0
	v_add_f32_e32 v28, v28, v29
	ds_bpermute_b32 v29, v129, v28
	s_waitcnt lgkmcnt(0)
	v_add_f32_e32 v28, v28, v29
	ds_bpermute_b32 v29, v138, v28
	s_waitcnt lgkmcnt(0)
	v_add_f32_e32 v28, v28, v29
	ds_bpermute_b32 v29, v139, v28
	s_waitcnt lgkmcnt(0)
	v_add_f32_e32 v28, v28, v29
	ds_bpermute_b32 v29, v140, v28
	s_waitcnt lgkmcnt(0)
	v_add_f32_e32 v28, v28, v29
	ds_bpermute_b32 v29, v141, v28
	s_waitcnt lgkmcnt(0)
	v_add_f32_e32 v28, v28, v29
	ds_bpermute_b32 v29, v142, v28
	s_waitcnt lgkmcnt(0)
	v_add_f32_e32 v28, v28, v29
	v_fmamk_f32 v28, v28, 0x39800000, v143
	v_mul_f32_e32 v29, 0x4f800000, v28
	v_cmp_gt_f32_e32 vcc, s15, v28
	s_nop 1
	v_cndmask_b32_e32 v28, v28, v29, vcc
	v_sqrt_f32_e32 v29, v28
	s_nop 0
	v_add_u32_e32 v128, -1, v29
	v_add_u32_e32 v146, 1, v29
	v_fma_f32 v147, -v128, v29, v28
	v_fma_f32 v148, -v146, v29, v28
	v_cmp_ge_f32_e64 s[2:3], 0, v147
	s_nop 1
	v_cndmask_b32_e64 v29, v29, v128, s[2:3]
	v_cmp_lt_f32_e64 s[2:3], 0, v148
	s_nop 1
	v_cndmask_b32_e64 v29, v29, v146, s[2:3]
	v_mul_f32_e32 v128, 0x37800000, v29
	v_cndmask_b32_e32 v29, v29, v128, vcc
	v_cmp_class_f32_e64 vcc, v28, s92
	s_nop 1
	v_cndmask_b32_e32 v28, v29, v28, vcc
	v_div_scale_f32 v29, s[2:3], v28, v28, 1.0
	v_rcp_f32_e32 v146, v29
	v_div_scale_f32 v128, vcc, 1.0, v28, 1.0
	v_fma_f32 v147, -v29, v146, 1.0
	v_fmac_f32_e32 v146, v147, v146
	v_mul_f32_e32 v147, v128, v146
	v_fma_f32 v148, -v29, v147, v128
	v_fmac_f32_e32 v147, v148, v146
	v_fma_f32 v29, -v29, v147, v128
	v_div_fmas_f32 v29, v29, v146, v147
	v_div_fixup_f32 v28, v29, v28, 1.0
	v_pk_mul_f32 v[2:3], v[2:3], v[28:29] op_sel_hi:[1,0]
	v_pk_mul_f32 v[146:147], v[0:1], v[28:29] op_sel_hi:[1,0]
	s_waitcnt lgkmcnt(0)
	v_mov_b32_e32 v1, v122
	v_mov_b32_e32 v122, v121
	v_pk_mul_f32 v[126:127], v[126:127], v[28:29] op_sel_hi:[1,0]
	v_mov_b32_e32 v0, v120
	v_pk_mul_f32 v[2:3], v[122:123], v[2:3]
	v_pk_mul_f32 v[0:1], v[0:1], v[126:127]
	v_and_b32_sdwa v121, v3, v145 dst_sel:DWORD dst_unused:UNUSED_PAD src0_sel:WORD_1 src1_sel:DWORD
	v_and_b32_sdwa v122, v2, v145 dst_sel:DWORD dst_unused:UNUSED_PAD src0_sel:WORD_1 src1_sel:DWORD
	v_pk_mul_f32 v[6:7], v[6:7], v[28:29] op_sel_hi:[1,0]
	v_pk_mul_f32 v[4:5], v[4:5], v[28:29] op_sel_hi:[1,0]
	v_pk_mul_f32 v[10:11], v[10:11], v[28:29] op_sel_hi:[1,0]
	v_pk_mul_f32 v[8:9], v[8:9], v[28:29] op_sel_hi:[1,0]
	v_pk_mul_f32 v[14:15], v[14:15], v[28:29] op_sel_hi:[1,0]
	v_pk_mul_f32 v[12:13], v[12:13], v[28:29] op_sel_hi:[1,0]
	v_pk_mul_f32 v[20:21], v[20:21], v[28:29] op_sel_hi:[1,0]
	v_pk_mul_f32 v[130:131], v[130:131], v[28:29] op_sel_hi:[1,0]
	v_pk_mul_f32 v[26:27], v[26:27], v[28:29] op_sel_hi:[1,0]
	v_pk_mul_f32 v[134:135], v[134:135], v[28:29] op_sel_hi:[1,0]
	v_pk_mul_f32 v[44:45], v[44:45], v[28:29] op_sel_hi:[1,0]
	v_pk_mul_f32 v[136:137], v[136:137], v[28:29] op_sel_hi:[1,0]
	v_pk_mul_f32 v[48:49], v[48:49], v[28:29] op_sel_hi:[1,0]
	v_pk_mul_f32 v[148:149], v[150:151], v[28:29] op_sel_hi:[1,0]
	v_pk_mul_f32 v[52:53], v[52:53], v[28:29] op_sel_hi:[1,0]
	v_and_b32_sdwa v29, v1, v145 dst_sel:DWORD dst_unused:UNUSED_PAD src0_sel:WORD_1 src1_sel:DWORD
	v_and_b32_sdwa v120, v0, v145 dst_sel:DWORD dst_unused:UNUSED_PAD src0_sel:WORD_1 src1_sel:DWORD
	v_add3_u32 v3, v3, v121, s29
	v_add3_u32 v2, v2, v122, s29
	v_add3_u32 v0, v0, v120, s29
	v_add3_u32 v1, v1, v29, s29
	v_and_b32_e32 v3, 0xffff0000, v3
	v_and_b32_e32 v2, 0xffff0000, v2
	v_or_b32_sdwa v1, v3, v1 dst_sel:DWORD dst_unused:UNUSED_PAD src0_sel:DWORD src1_sel:WORD_1
	v_or_b32_sdwa v0, v2, v0 dst_sel:DWORD dst_unused:UNUSED_PAD src0_sel:DWORD src1_sel:WORD_1
	global_store_dwordx2 v[118:119], v[0:1], off offset:-4096
	ds_read_b128 v[0:3], v144 offset:17408
	s_waitcnt lgkmcnt(0)
	v_mov_b32_e32 v121, v2
	v_mov_b32_e32 v2, v1
	v_mov_b32_e32 v120, v0
	v_pk_mul_f32 v[2:3], v[2:3], v[6:7]
	v_pk_mul_f32 v[0:1], v[120:121], v[146:147]
	v_and_b32_sdwa v29, v3, v145 dst_sel:DWORD dst_unused:UNUSED_PAD src0_sel:WORD_1 src1_sel:DWORD
	v_and_b32_sdwa v120, v2, v145 dst_sel:DWORD dst_unused:UNUSED_PAD src0_sel:WORD_1 src1_sel:DWORD
	v_and_b32_sdwa v6, v1, v145 dst_sel:DWORD dst_unused:UNUSED_PAD src0_sel:WORD_1 src1_sel:DWORD
	v_and_b32_sdwa v7, v0, v145 dst_sel:DWORD dst_unused:UNUSED_PAD src0_sel:WORD_1 src1_sel:DWORD
	v_add3_u32 v3, v3, v29, s29
	v_add3_u32 v2, v2, v120, s29
	v_add3_u32 v0, v0, v7, s29
	v_add3_u32 v1, v1, v6, s29
	v_and_b32_e32 v3, 0xffff0000, v3
	v_and_b32_e32 v2, 0xffff0000, v2
	v_or_b32_sdwa v1, v3, v1 dst_sel:DWORD dst_unused:UNUSED_PAD src0_sel:DWORD src1_sel:WORD_1
	v_or_b32_sdwa v0, v2, v0 dst_sel:DWORD dst_unused:UNUSED_PAD src0_sel:DWORD src1_sel:WORD_1
	global_store_dwordx2 v[124:125], v[0:1], off offset:512
	ds_read_b128 v[0:3], v144 offset:18432
	s_waitcnt lgkmcnt(0)
	v_mov_b32_e32 v7, v2
	v_mov_b32_e32 v2, v1
	v_mov_b32_e32 v6, v0
	v_pk_mul_f32 v[2:3], v[2:3], v[10:11]
	v_pk_mul_f32 v[0:1], v[6:7], v[4:5]
	v_and_b32_sdwa v6, v3, v145 dst_sel:DWORD dst_unused:UNUSED_PAD src0_sel:WORD_1 src1_sel:DWORD
	v_and_b32_sdwa v7, v2, v145 dst_sel:DWORD dst_unused:UNUSED_PAD src0_sel:WORD_1 src1_sel:DWORD
	v_and_b32_sdwa v4, v1, v145 dst_sel:DWORD dst_unused:UNUSED_PAD src0_sel:WORD_1 src1_sel:DWORD
	v_and_b32_sdwa v5, v0, v145 dst_sel:DWORD dst_unused:UNUSED_PAD src0_sel:WORD_1 src1_sel:DWORD
	v_add3_u32 v3, v3, v6, s29
	v_add3_u32 v2, v2, v7, s29
	v_add3_u32 v0, v0, v5, s29
	v_add3_u32 v1, v1, v4, s29
	v_and_b32_e32 v3, 0xffff0000, v3
	v_and_b32_e32 v2, 0xffff0000, v2
	v_or_b32_sdwa v1, v3, v1 dst_sel:DWORD dst_unused:UNUSED_PAD src0_sel:DWORD src1_sel:WORD_1
	v_or_b32_sdwa v0, v2, v0 dst_sel:DWORD dst_unused:UNUSED_PAD src0_sel:DWORD src1_sel:WORD_1
	global_store_dwordx2 v[124:125], v[0:1], off offset:1024
	ds_read_b128 v[0:3], v144 offset:19456
	s_waitcnt lgkmcnt(0)
	v_mov_b32_e32 v5, v2
	v_mov_b32_e32 v2, v1
	v_mov_b32_e32 v4, v0
	v_pk_mul_f32 v[2:3], v[2:3], v[14:15]
	v_pk_mul_f32 v[0:1], v[4:5], v[8:9]
	v_and_b32_sdwa v6, v3, v145 dst_sel:DWORD dst_unused:UNUSED_PAD src0_sel:WORD_1 src1_sel:DWORD
	v_and_b32_sdwa v7, v2, v145 dst_sel:DWORD dst_unused:UNUSED_PAD src0_sel:WORD_1 src1_sel:DWORD
	v_and_b32_sdwa v4, v1, v145 dst_sel:DWORD dst_unused:UNUSED_PAD src0_sel:WORD_1 src1_sel:DWORD
	v_and_b32_sdwa v5, v0, v145 dst_sel:DWORD dst_unused:UNUSED_PAD src0_sel:WORD_1 src1_sel:DWORD
	v_add3_u32 v3, v3, v6, s29
	v_add3_u32 v2, v2, v7, s29
	v_add3_u32 v0, v0, v5, s29
	v_add3_u32 v1, v1, v4, s29
	v_and_b32_e32 v3, 0xffff0000, v3
	v_and_b32_e32 v2, 0xffff0000, v2
	v_or_b32_sdwa v1, v3, v1 dst_sel:DWORD dst_unused:UNUSED_PAD src0_sel:DWORD src1_sel:WORD_1
	v_or_b32_sdwa v0, v2, v0 dst_sel:DWORD dst_unused:UNUSED_PAD src0_sel:DWORD src1_sel:WORD_1
	global_store_dwordx2 v[124:125], v[0:1], off offset:1536
	ds_read_b128 v[0:3], v144 offset:20480
	s_waitcnt lgkmcnt(0)
	v_mov_b32_e32 v5, v2
	v_mov_b32_e32 v2, v1
	v_mov_b32_e32 v4, v0
	v_pk_mul_f32 v[2:3], v[2:3], v[20:21]
	v_pk_mul_f32 v[0:1], v[4:5], v[12:13]
	v_and_b32_sdwa v6, v3, v145 dst_sel:DWORD dst_unused:UNUSED_PAD src0_sel:WORD_1 src1_sel:DWORD
	v_and_b32_sdwa v7, v2, v145 dst_sel:DWORD dst_unused:UNUSED_PAD src0_sel:WORD_1 src1_sel:DWORD
	v_and_b32_sdwa v4, v1, v145 dst_sel:DWORD dst_unused:UNUSED_PAD src0_sel:WORD_1 src1_sel:DWORD
	v_and_b32_sdwa v5, v0, v145 dst_sel:DWORD dst_unused:UNUSED_PAD src0_sel:WORD_1 src1_sel:DWORD
	v_add3_u32 v3, v3, v6, s29
	v_add3_u32 v2, v2, v7, s29
	v_add3_u32 v0, v0, v5, s29
	v_add3_u32 v1, v1, v4, s29
	v_and_b32_e32 v3, 0xffff0000, v3
	v_and_b32_e32 v2, 0xffff0000, v2
	v_or_b32_sdwa v1, v3, v1 dst_sel:DWORD dst_unused:UNUSED_PAD src0_sel:DWORD src1_sel:WORD_1
	v_or_b32_sdwa v0, v2, v0 dst_sel:DWORD dst_unused:UNUSED_PAD src0_sel:DWORD src1_sel:WORD_1
	global_store_dwordx2 v[124:125], v[0:1], off offset:2048
	ds_read_b128 v[0:3], v144 offset:21504
	s_waitcnt lgkmcnt(0)
	v_mov_b32_e32 v5, v2
	v_mov_b32_e32 v2, v1
	v_mov_b32_e32 v4, v0
	v_pk_mul_f32 v[2:3], v[2:3], v[26:27]
	v_pk_mul_f32 v[0:1], v[4:5], v[130:131]
	v_and_b32_sdwa v6, v3, v145 dst_sel:DWORD dst_unused:UNUSED_PAD src0_sel:WORD_1 src1_sel:DWORD
	v_and_b32_sdwa v7, v2, v145 dst_sel:DWORD dst_unused:UNUSED_PAD src0_sel:WORD_1 src1_sel:DWORD
	v_and_b32_sdwa v4, v1, v145 dst_sel:DWORD dst_unused:UNUSED_PAD src0_sel:WORD_1 src1_sel:DWORD
	v_and_b32_sdwa v5, v0, v145 dst_sel:DWORD dst_unused:UNUSED_PAD src0_sel:WORD_1 src1_sel:DWORD
	v_add3_u32 v3, v3, v6, s29
	v_add3_u32 v2, v2, v7, s29
	v_add3_u32 v0, v0, v5, s29
	v_add3_u32 v1, v1, v4, s29
	v_and_b32_e32 v3, 0xffff0000, v3
	v_and_b32_e32 v2, 0xffff0000, v2
	v_or_b32_sdwa v1, v3, v1 dst_sel:DWORD dst_unused:UNUSED_PAD src0_sel:DWORD src1_sel:WORD_1
	v_or_b32_sdwa v0, v2, v0 dst_sel:DWORD dst_unused:UNUSED_PAD src0_sel:DWORD src1_sel:WORD_1
	global_store_dwordx2 v[124:125], v[0:1], off offset:2560
	ds_read_b128 v[0:3], v144 offset:22528
	s_waitcnt lgkmcnt(0)
	v_mov_b32_e32 v5, v2
	v_mov_b32_e32 v2, v1
	v_mov_b32_e32 v4, v0
	v_pk_mul_f32 v[2:3], v[44:45], v[2:3]
	v_pk_mul_f32 v[0:1], v[134:135], v[4:5]
	v_and_b32_sdwa v6, v3, v145 dst_sel:DWORD dst_unused:UNUSED_PAD src0_sel:WORD_1 src1_sel:DWORD
	v_and_b32_sdwa v7, v2, v145 dst_sel:DWORD dst_unused:UNUSED_PAD src0_sel:WORD_1 src1_sel:DWORD
	v_and_b32_sdwa v4, v1, v145 dst_sel:DWORD dst_unused:UNUSED_PAD src0_sel:WORD_1 src1_sel:DWORD
	v_and_b32_sdwa v5, v0, v145 dst_sel:DWORD dst_unused:UNUSED_PAD src0_sel:WORD_1 src1_sel:DWORD
	v_add3_u32 v3, v3, v6, s29
	v_add3_u32 v2, v2, v7, s29
	v_add3_u32 v0, v0, v5, s29
	v_add3_u32 v1, v1, v4, s29
	v_and_b32_e32 v3, 0xffff0000, v3
	v_and_b32_e32 v2, 0xffff0000, v2
	v_or_b32_sdwa v1, v3, v1 dst_sel:DWORD dst_unused:UNUSED_PAD src0_sel:DWORD src1_sel:WORD_1
	v_or_b32_sdwa v0, v2, v0 dst_sel:DWORD dst_unused:UNUSED_PAD src0_sel:DWORD src1_sel:WORD_1
	global_store_dwordx2 v[124:125], v[0:1], off offset:3072
	ds_read_b128 v[0:3], v144 offset:23552
	s_waitcnt lgkmcnt(0)
	v_mov_b32_e32 v5, v2
	v_mov_b32_e32 v2, v1
	v_mov_b32_e32 v4, v0
	v_pk_mul_f32 v[2:3], v[48:49], v[2:3]
	v_pk_mul_f32 v[0:1], v[136:137], v[4:5]
	v_and_b32_sdwa v6, v3, v145 dst_sel:DWORD dst_unused:UNUSED_PAD src0_sel:WORD_1 src1_sel:DWORD
	v_and_b32_sdwa v7, v2, v145 dst_sel:DWORD dst_unused:UNUSED_PAD src0_sel:WORD_1 src1_sel:DWORD
	v_and_b32_sdwa v4, v1, v145 dst_sel:DWORD dst_unused:UNUSED_PAD src0_sel:WORD_1 src1_sel:DWORD
	v_and_b32_sdwa v5, v0, v145 dst_sel:DWORD dst_unused:UNUSED_PAD src0_sel:WORD_1 src1_sel:DWORD
	v_add3_u32 v3, v3, v6, s29
	v_add3_u32 v2, v2, v7, s29
	v_add3_u32 v0, v0, v5, s29
	v_add3_u32 v1, v1, v4, s29
	v_and_b32_e32 v3, 0xffff0000, v3
	v_and_b32_e32 v2, 0xffff0000, v2
	v_or_b32_sdwa v1, v3, v1 dst_sel:DWORD dst_unused:UNUSED_PAD src0_sel:DWORD src1_sel:WORD_1
	v_or_b32_sdwa v0, v2, v0 dst_sel:DWORD dst_unused:UNUSED_PAD src0_sel:DWORD src1_sel:WORD_1
	global_store_dwordx2 v[124:125], v[0:1], off offset:3584
	ds_read_b128 v[0:3], v144 offset:24576
	s_waitcnt lgkmcnt(0)
	v_mov_b32_e32 v5, v2
	v_mov_b32_e32 v2, v1
	v_mov_b32_e32 v4, v0
	v_pk_mul_f32 v[2:3], v[52:53], v[2:3]
	v_pk_mul_f32 v[0:1], v[148:149], v[4:5]
	v_and_b32_sdwa v6, v3, v145 dst_sel:DWORD dst_unused:UNUSED_PAD src0_sel:WORD_1 src1_sel:DWORD
	v_and_b32_sdwa v7, v2, v145 dst_sel:DWORD dst_unused:UNUSED_PAD src0_sel:WORD_1 src1_sel:DWORD
	v_and_b32_sdwa v4, v1, v145 dst_sel:DWORD dst_unused:UNUSED_PAD src0_sel:WORD_1 src1_sel:DWORD
	v_and_b32_sdwa v5, v0, v145 dst_sel:DWORD dst_unused:UNUSED_PAD src0_sel:WORD_1 src1_sel:DWORD
	v_add3_u32 v3, v3, v6, s29
	v_add3_u32 v2, v2, v7, s29
	v_add3_u32 v0, v0, v5, s29
	v_add3_u32 v1, v1, v4, s29
	v_and_b32_e32 v3, 0xffff0000, v3
	v_and_b32_e32 v2, 0xffff0000, v2
	v_or_b32_sdwa v1, v3, v1 dst_sel:DWORD dst_unused:UNUSED_PAD src0_sel:DWORD src1_sel:WORD_1
	v_or_b32_sdwa v0, v2, v0 dst_sel:DWORD dst_unused:UNUSED_PAD src0_sel:DWORD src1_sel:WORD_1
	global_store_dwordx2 v[118:119], v[0:1], off
	ds_read_b128 v[0:3], v144 offset:25600
	v_pk_mul_f32 v[6:7], v[36:37], v[28:29] op_sel_hi:[1,0]
	v_pk_mul_f32 v[4:5], v[50:51], v[28:29] op_sel_hi:[1,0]
	s_waitcnt lgkmcnt(0)
	v_mov_b32_e32 v9, v2
	v_mov_b32_e32 v2, v1
	v_mov_b32_e32 v8, v0
	v_pk_mul_f32 v[2:3], v[6:7], v[2:3]
	v_pk_mul_f32 v[0:1], v[4:5], v[8:9]
	v_and_b32_sdwa v6, v3, v145 dst_sel:DWORD dst_unused:UNUSED_PAD src0_sel:WORD_1 src1_sel:DWORD
	v_and_b32_sdwa v7, v2, v145 dst_sel:DWORD dst_unused:UNUSED_PAD src0_sel:WORD_1 src1_sel:DWORD
	v_and_b32_sdwa v4, v1, v145 dst_sel:DWORD dst_unused:UNUSED_PAD src0_sel:WORD_1 src1_sel:DWORD
	v_and_b32_sdwa v5, v0, v145 dst_sel:DWORD dst_unused:UNUSED_PAD src0_sel:WORD_1 src1_sel:DWORD
	v_add3_u32 v3, v3, v6, s29
	v_add3_u32 v2, v2, v7, s29
	v_add3_u32 v0, v0, v5, s29
	v_add3_u32 v1, v1, v4, s29
	v_and_b32_e32 v3, 0xffff0000, v3
	v_and_b32_e32 v2, 0xffff0000, v2
	v_or_b32_sdwa v1, v3, v1 dst_sel:DWORD dst_unused:UNUSED_PAD src0_sel:DWORD src1_sel:WORD_1
	v_or_b32_sdwa v0, v2, v0 dst_sel:DWORD dst_unused:UNUSED_PAD src0_sel:DWORD src1_sel:WORD_1
	global_store_dwordx2 v[118:119], v[0:1], off offset:512
	ds_read_b128 v[0:3], v144 offset:26624
	v_pk_mul_f32 v[6:7], v[42:43], v[28:29] op_sel_hi:[1,0]
	v_pk_mul_f32 v[4:5], v[132:133], v[28:29] op_sel_hi:[1,0]
	s_waitcnt lgkmcnt(0)
	v_mov_b32_e32 v9, v2
	v_mov_b32_e32 v2, v1
	v_mov_b32_e32 v8, v0
	v_pk_mul_f32 v[2:3], v[6:7], v[2:3]
	v_pk_mul_f32 v[0:1], v[4:5], v[8:9]
	v_and_b32_sdwa v6, v3, v145 dst_sel:DWORD dst_unused:UNUSED_PAD src0_sel:WORD_1 src1_sel:DWORD
	v_and_b32_sdwa v7, v2, v145 dst_sel:DWORD dst_unused:UNUSED_PAD src0_sel:WORD_1 src1_sel:DWORD
	v_and_b32_sdwa v4, v1, v145 dst_sel:DWORD dst_unused:UNUSED_PAD src0_sel:WORD_1 src1_sel:DWORD
	v_and_b32_sdwa v5, v0, v145 dst_sel:DWORD dst_unused:UNUSED_PAD src0_sel:WORD_1 src1_sel:DWORD
	v_add3_u32 v3, v3, v6, s29
	v_add3_u32 v2, v2, v7, s29
	v_add3_u32 v0, v0, v5, s29
	v_add3_u32 v1, v1, v4, s29
	v_and_b32_e32 v3, 0xffff0000, v3
	v_and_b32_e32 v2, 0xffff0000, v2
	v_or_b32_sdwa v1, v3, v1 dst_sel:DWORD dst_unused:UNUSED_PAD src0_sel:DWORD src1_sel:WORD_1
	v_or_b32_sdwa v0, v2, v0 dst_sel:DWORD dst_unused:UNUSED_PAD src0_sel:DWORD src1_sel:WORD_1
	global_store_dwordx2 v[118:119], v[0:1], off offset:1024
	ds_read_b128 v[0:3], v144 offset:27648
	v_mov_b32_e32 v5, v40
	v_mov_b32_e32 v40, v39
	v_mov_b32_e32 v4, v38
	v_pk_mul_f32 v[6:7], v[40:41], v[28:29] op_sel_hi:[1,0]
	v_pk_mul_f32 v[4:5], v[4:5], v[28:29] op_sel_hi:[1,0]
	s_waitcnt lgkmcnt(0)
	v_mov_b32_e32 v9, v2
	v_mov_b32_e32 v2, v1
	v_mov_b32_e32 v8, v0
	v_pk_mul_f32 v[2:3], v[6:7], v[2:3]
	v_pk_mul_f32 v[0:1], v[4:5], v[8:9]
	v_and_b32_sdwa v6, v3, v145 dst_sel:DWORD dst_unused:UNUSED_PAD src0_sel:WORD_1 src1_sel:DWORD
	v_and_b32_sdwa v7, v2, v145 dst_sel:DWORD dst_unused:UNUSED_PAD src0_sel:WORD_1 src1_sel:DWORD
	v_and_b32_sdwa v4, v1, v145 dst_sel:DWORD dst_unused:UNUSED_PAD src0_sel:WORD_1 src1_sel:DWORD
	v_and_b32_sdwa v5, v0, v145 dst_sel:DWORD dst_unused:UNUSED_PAD src0_sel:WORD_1 src1_sel:DWORD
	v_add3_u32 v3, v3, v6, s29
	v_add3_u32 v2, v2, v7, s29
	v_add3_u32 v0, v0, v5, s29
	v_add3_u32 v1, v1, v4, s29
	v_and_b32_e32 v3, 0xffff0000, v3
	v_and_b32_e32 v2, 0xffff0000, v2
	v_or_b32_sdwa v1, v3, v1 dst_sel:DWORD dst_unused:UNUSED_PAD src0_sel:DWORD src1_sel:WORD_1
	v_or_b32_sdwa v0, v2, v0 dst_sel:DWORD dst_unused:UNUSED_PAD src0_sel:DWORD src1_sel:WORD_1
	global_store_dwordx2 v[118:119], v[0:1], off offset:1536
	ds_read_b128 v[0:3], v144 offset:28672
	v_mov_b32_e32 v5, v34
	v_mov_b32_e32 v34, v33
	v_mov_b32_e32 v4, v32
	v_pk_mul_f32 v[6:7], v[34:35], v[28:29] op_sel_hi:[1,0]
	v_pk_mul_f32 v[4:5], v[4:5], v[28:29] op_sel_hi:[1,0]
	s_waitcnt lgkmcnt(0)
	v_mov_b32_e32 v9, v2
	v_mov_b32_e32 v2, v1
	v_mov_b32_e32 v8, v0
	v_pk_mul_f32 v[2:3], v[6:7], v[2:3]
	v_pk_mul_f32 v[0:1], v[4:5], v[8:9]
	v_and_b32_sdwa v6, v3, v145 dst_sel:DWORD dst_unused:UNUSED_PAD src0_sel:WORD_1 src1_sel:DWORD
	v_and_b32_sdwa v7, v2, v145 dst_sel:DWORD dst_unused:UNUSED_PAD src0_sel:WORD_1 src1_sel:DWORD
	v_and_b32_sdwa v4, v1, v145 dst_sel:DWORD dst_unused:UNUSED_PAD src0_sel:WORD_1 src1_sel:DWORD
	v_and_b32_sdwa v5, v0, v145 dst_sel:DWORD dst_unused:UNUSED_PAD src0_sel:WORD_1 src1_sel:DWORD
	v_add3_u32 v3, v3, v6, s29
	v_add3_u32 v2, v2, v7, s29
	v_add3_u32 v0, v0, v5, s29
	v_add3_u32 v1, v1, v4, s29
	v_and_b32_e32 v3, 0xffff0000, v3
	v_and_b32_e32 v2, 0xffff0000, v2
	v_or_b32_sdwa v1, v3, v1 dst_sel:DWORD dst_unused:UNUSED_PAD src0_sel:DWORD src1_sel:WORD_1
	v_or_b32_sdwa v0, v2, v0 dst_sel:DWORD dst_unused:UNUSED_PAD src0_sel:DWORD src1_sel:WORD_1
	global_store_dwordx2 v[118:119], v[0:1], off offset:2048
	ds_read_b128 v[0:3], v144 offset:29696
	v_pk_mul_f32 v[6:7], v[30:31], v[28:29] op_sel_hi:[1,0]
	v_pk_mul_f32 v[4:5], v[46:47], v[28:29] op_sel_hi:[1,0]
	s_waitcnt lgkmcnt(0)
	v_mov_b32_e32 v9, v2
	v_mov_b32_e32 v2, v1
	v_mov_b32_e32 v8, v0
	v_pk_mul_f32 v[2:3], v[6:7], v[2:3]
	v_pk_mul_f32 v[0:1], v[4:5], v[8:9]
	v_and_b32_sdwa v6, v3, v145 dst_sel:DWORD dst_unused:UNUSED_PAD src0_sel:WORD_1 src1_sel:DWORD
	v_and_b32_sdwa v7, v2, v145 dst_sel:DWORD dst_unused:UNUSED_PAD src0_sel:WORD_1 src1_sel:DWORD
	v_and_b32_sdwa v4, v1, v145 dst_sel:DWORD dst_unused:UNUSED_PAD src0_sel:WORD_1 src1_sel:DWORD
	v_and_b32_sdwa v5, v0, v145 dst_sel:DWORD dst_unused:UNUSED_PAD src0_sel:WORD_1 src1_sel:DWORD
	v_add3_u32 v3, v3, v6, s29
	v_add3_u32 v2, v2, v7, s29
	v_add3_u32 v0, v0, v5, s29
	v_add3_u32 v1, v1, v4, s29
	v_and_b32_e32 v3, 0xffff0000, v3
	v_and_b32_e32 v2, 0xffff0000, v2
	v_or_b32_sdwa v1, v3, v1 dst_sel:DWORD dst_unused:UNUSED_PAD src0_sel:DWORD src1_sel:WORD_1
	v_or_b32_sdwa v0, v2, v0 dst_sel:DWORD dst_unused:UNUSED_PAD src0_sel:DWORD src1_sel:WORD_1
	global_store_dwordx2 v[118:119], v[0:1], off offset:2560
	ds_read_b128 v[0:3], v144 offset:30720
	v_mov_b32_e32 v5, v24
	v_mov_b32_e32 v24, v23
	v_mov_b32_e32 v4, v22
	v_pk_mul_f32 v[6:7], v[24:25], v[28:29] op_sel_hi:[1,0]
	v_pk_mul_f32 v[4:5], v[4:5], v[28:29] op_sel_hi:[1,0]
	s_waitcnt lgkmcnt(0)
	v_mov_b32_e32 v9, v2
	v_mov_b32_e32 v2, v1
	v_mov_b32_e32 v8, v0
	v_pk_mul_f32 v[2:3], v[6:7], v[2:3]
	v_pk_mul_f32 v[0:1], v[4:5], v[8:9]
	v_and_b32_sdwa v6, v3, v145 dst_sel:DWORD dst_unused:UNUSED_PAD src0_sel:WORD_1 src1_sel:DWORD
	v_and_b32_sdwa v7, v2, v145 dst_sel:DWORD dst_unused:UNUSED_PAD src0_sel:WORD_1 src1_sel:DWORD
	v_and_b32_sdwa v4, v1, v145 dst_sel:DWORD dst_unused:UNUSED_PAD src0_sel:WORD_1 src1_sel:DWORD
	v_and_b32_sdwa v5, v0, v145 dst_sel:DWORD dst_unused:UNUSED_PAD src0_sel:WORD_1 src1_sel:DWORD
	v_add3_u32 v3, v3, v6, s29
	v_add3_u32 v2, v2, v7, s29
	v_add3_u32 v0, v0, v5, s29
	v_add3_u32 v1, v1, v4, s29
	v_and_b32_e32 v3, 0xffff0000, v3
	v_and_b32_e32 v2, 0xffff0000, v2
	v_or_b32_sdwa v1, v3, v1 dst_sel:DWORD dst_unused:UNUSED_PAD src0_sel:DWORD src1_sel:WORD_1
	v_or_b32_sdwa v0, v2, v0 dst_sel:DWORD dst_unused:UNUSED_PAD src0_sel:DWORD src1_sel:WORD_1
	global_store_dwordx2 v[118:119], v[0:1], off offset:3072
	ds_read_b128 v[0:3], v144 offset:31744
	v_mov_b32_e32 v5, v18
	v_mov_b32_e32 v18, v17
	v_mov_b32_e32 v4, v16
	v_pk_mul_f32 v[6:7], v[18:19], v[28:29] op_sel_hi:[1,0]
	v_pk_mul_f32 v[4:5], v[4:5], v[28:29] op_sel_hi:[1,0]
	s_waitcnt lgkmcnt(0)
	v_mov_b32_e32 v9, v2
	v_mov_b32_e32 v2, v1
	v_mov_b32_e32 v8, v0
	v_pk_mul_f32 v[2:3], v[6:7], v[2:3]
	v_pk_mul_f32 v[0:1], v[4:5], v[8:9]
	v_and_b32_sdwa v6, v3, v145 dst_sel:DWORD dst_unused:UNUSED_PAD src0_sel:WORD_1 src1_sel:DWORD
	v_and_b32_sdwa v7, v2, v145 dst_sel:DWORD dst_unused:UNUSED_PAD src0_sel:WORD_1 src1_sel:DWORD
	v_and_b32_sdwa v4, v1, v145 dst_sel:DWORD dst_unused:UNUSED_PAD src0_sel:WORD_1 src1_sel:DWORD
	v_and_b32_sdwa v5, v0, v145 dst_sel:DWORD dst_unused:UNUSED_PAD src0_sel:WORD_1 src1_sel:DWORD
	v_add3_u32 v3, v3, v6, s29
	v_add3_u32 v2, v2, v7, s29
	v_add3_u32 v0, v0, v5, s29
	v_add3_u32 v1, v1, v4, s29
	v_and_b32_e32 v3, 0xffff0000, v3
	v_and_b32_e32 v2, 0xffff0000, v2
	v_or_b32_sdwa v1, v3, v1 dst_sel:DWORD dst_unused:UNUSED_PAD src0_sel:DWORD src1_sel:WORD_1
	v_or_b32_sdwa v0, v2, v0 dst_sel:DWORD dst_unused:UNUSED_PAD src0_sel:DWORD src1_sel:WORD_1
	global_store_dwordx2 v[118:119], v[0:1], off offset:3584
	s_cbranch_scc0 .LBB0_3749

.LBB0_4006:
	s_cmp_gt_i32 s78, 18
	s_cselect_b64 s[2:3], -1, 0
	s_cmp_lt_i32 s79, 19
	s_cselect_b64 s[4:5], -1, 0
	s_or_b64 s[2:3], s[2:3], s[4:5]
	s_and_b64 vcc, exec, s[2:3]
	s_cbranch_vccnz .LBB0_4064
	s_mov_b64 s[2:3], s[0:1]
	s_getreg_b32 s4, hwreg(HW_REG_HW_ID, 0, 6)
	s_lshl_b32 s4, s4, 2
	s_and_b32 s4, s4, 0xfc
	s_add_i32 s4, s4, 0
	s_add_i32 s4, s4, 0x20200
	s_waitcnt vmcnt(0)
	v_mov_b32_e32 v0, s4
	ds_read_b32 v0, v0
	v_mbcnt_lo_u32_b32 v1, -1, 0
	v_mbcnt_hi_u32_b32 v1, -1, v1
	s_waitcnt lgkmcnt(0)
	v_readfirstlane_b32 s4, v0
	s_nop 1
	v_lshl_add_u32 v0, s4, 6, v1
	s_load_dword s20, s[0:1], 0xa0
	v_readfirstlane_b32 s4, v0
	s_ashr_i32 s4, s4, 6
	s_add_u32 s8, s0, 0xa0
	s_addc_u32 s9, s1, 0
	s_lshl_b32 s5, s64, 3
	s_add_i32 s10, s5, s4
	s_cmpk_lt_i32 s10, 0x4000
	s_cbranch_scc0 .LBB0_4010
	s_load_dwordx4 s[4:7], s[2:3], 0x80
	s_load_dwordx2 s[14:15], s[2:3], 0x90
	s_waitcnt lgkmcnt(0)
	s_lshl_b32 s12, s20, 3
	v_mbcnt_lo_u32_b32 v32, -1, 0
	v_and_b32_e32 v36, 63, v0
	s_add_u32 s2, s4, 0x4000
	v_mbcnt_hi_u32_b32 v32, -1, v32
	v_lshlrev_b32_e32 v34, 4, v36
	s_addc_u32 s3, s5, 0
	v_mov_b32_e32 v35, 0
	v_and_b32_e32 v33, 64, v32
	v_lshl_add_u64 v[0:1], s[2:3], 0, v[34:35]
	v_mov_b32_e32 v3, v35
	v_mov_b32_e32 v5, v35
	v_mov_b32_e32 v7, v35
	v_mov_b32_e32 v9, v35
	v_mov_b32_e32 v11, v35
	v_mov_b32_e32 v13, v35
	v_mov_b32_e32 v15, v35
	v_mov_b32_e32 v17, v35
	v_mov_b32_e32 v19, v35
	v_mov_b32_e32 v21, v35
	v_mov_b32_e32 v23, v35
	v_mov_b32_e32 v25, v35
	v_mov_b32_e32 v27, v35
	v_mov_b32_e32 v29, v35
	v_mov_b32_e32 v31, v35
	v_add_u32_e32 v33, 64, v33
	v_xor_b32_e32 v35, 1, v32
	v_cmp_lt_i32_e32 vcc, v35, v33
	v_or_b32_e32 v2, 0x400, v34
	v_or_b32_e32 v4, 0x800, v34
	v_cndmask_b32_e32 v35, v32, v35, vcc
	v_lshlrev_b32_e32 v41, 2, v35
	v_xor_b32_e32 v35, 2, v32
	v_cmp_lt_i32_e32 vcc, v35, v33
	v_or_b32_e32 v6, 0xc00, v34
	v_or_b32_e32 v8, 0x1000, v34
	v_cndmask_b32_e32 v35, v32, v35, vcc
	v_lshlrev_b32_e32 v46, 2, v35
	v_xor_b32_e32 v35, 4, v32
	v_cmp_lt_i32_e32 vcc, v35, v33
	v_or_b32_e32 v10, 0x1400, v34
	v_or_b32_e32 v12, 0x1800, v34
	v_cndmask_b32_e32 v35, v32, v35, vcc
	v_lshlrev_b32_e32 v47, 2, v35
	v_xor_b32_e32 v35, 8, v32
	v_cmp_lt_i32_e32 vcc, v35, v33
	v_or_b32_e32 v14, 0x1c00, v34
	v_or_b32_e32 v16, 0x2000, v34
	v_cndmask_b32_e32 v35, v32, v35, vcc
	v_lshlrev_b32_e32 v48, 2, v35
	v_xor_b32_e32 v35, 16, v32
	v_cmp_lt_i32_e32 vcc, v35, v33
	v_or_b32_e32 v18, 0x2400, v34
	v_or_b32_e32 v20, 0x2800, v34
	v_cndmask_b32_e32 v35, v32, v35, vcc
	v_lshlrev_b32_e32 v49, 2, v35
	v_xor_b32_e32 v35, 32, v32
	v_or_b32_e32 v22, 0x2c00, v34
	v_or_b32_e32 v24, 0x3000, v34
	v_or_b32_e32 v26, 0x3400, v34
	v_or_b32_e32 v28, 0x3800, v34
	v_or_b32_e32 v30, 0x3c00, v34
	v_cmp_lt_i32_e32 vcc, v35, v33
	s_ashr_i32 s11, s10, 31
	v_lshl_add_u64 v[2:3], s[2:3], 0, v[2:3]
	v_lshl_add_u64 v[4:5], s[2:3], 0, v[4:5]
	v_lshl_add_u64 v[6:7], s[2:3], 0, v[6:7]
	v_lshl_add_u64 v[8:9], s[2:3], 0, v[8:9]
	v_lshl_add_u64 v[10:11], s[2:3], 0, v[10:11]
	v_lshl_add_u64 v[12:13], s[2:3], 0, v[12:13]
	v_lshl_add_u64 v[14:15], s[2:3], 0, v[14:15]
	v_lshl_add_u64 v[16:17], s[2:3], 0, v[16:17]
	v_lshl_add_u64 v[18:19], s[2:3], 0, v[18:19]
	v_lshl_add_u64 v[20:21], s[2:3], 0, v[20:21]
	v_lshl_add_u64 v[22:23], s[2:3], 0, v[22:23]
	v_lshl_add_u64 v[24:25], s[2:3], 0, v[24:25]
	v_lshl_add_u64 v[26:27], s[2:3], 0, v[26:27]
	v_lshl_add_u64 v[28:29], s[2:3], 0, v[28:29]
	v_lshl_add_u64 v[30:31], s[2:3], 0, v[30:31]
	v_cndmask_b32_e32 v32, v32, v35, vcc
	s_lshl_b64 s[2:3], s[10:11], 8
	v_lshlrev_b32_e32 v50, 2, v32
	v_lshl_or_b32 v32, v36, 2, s2
	v_mov_b32_e32 v33, s3
	s_mov_b64 s[2:3], 0x5dc00000
	v_lshl_add_u64 v[32:33], v[32:33], 0, s[2:3]
	s_lshl_b64 s[2:3], s[10:11], 14
	s_ashr_i32 s13, s12, 31
	v_or_b32_e32 v34, s2, v34
	v_mov_b32_e32 v35, s3
	s_lshl_b64 s[2:3], s[10:11], 13
	s_movk_i32 s21, 0x1000
	s_movk_i32 s22, 0x2000
	s_movk_i32 s23, 0x3000
	s_lshl_b64 s[4:5], s[12:13], 8
	s_lshl_b64 s[16:17], s[12:13], 14
	v_lshl_or_b32 v36, v36, 3, s2
	v_mov_b32_e32 v37, s3
	s_lshl_b64 s[18:19], s[12:13], 13
	v_mov_b32_e32 v51, 0x358637bd
	s_mov_b32 s11, 0xf800000
	v_mov_b32_e32 v52, 0x260
	s_mov_b32 s13, 0x2a000000
	s_mov_b32 s24, 0x32000000
	s_mov_b32 s25, 0x32001000
	s_mov_b32 s26, 0x2a001000
	s_mov_b32 s27, 0x32002000
	s_mov_b32 s28, 0x32003000
	s_add_u32 s80, s14, 0x32000000
	s_addc_u32 s81, s15, 0
	s_add_u32 s82, s14, 0x32001000
	s_addc_u32 s83, s15, 0
	s_add_u32 s84, s14, 0x32002000
	s_addc_u32 s85, s15, 0
	s_add_u32 s86, s14, 0x32003000
	s_addc_u32 s87, s15, 0
	s_add_u32 s88, s14, 0x2a000000
	s_addc_u32 s89, s15, 0
	s_add_u32 s90, s14, 0x2a001000
	s_addc_u32 s91, s15, 0
	v_mbcnt_lo_u32_b32 v76, -1, 0
	v_mbcnt_hi_u32_b32 v76, -1, v76
	v_lshlrev_b32_e32 v76, 4, v76
	global_load_dwordx4 v[160:163], v[0:1], off
	global_load_dwordx4 v[164:167], v[2:3], off
	global_load_dwordx4 v[168:171], v[4:5], off
	global_load_dwordx4 v[172:175], v[6:7], off
	global_load_dwordx4 v[176:179], v[8:9], off
	global_load_dwordx4 v[180:183], v[10:11], off
	global_load_dwordx4 v[184:187], v[12:13], off
	global_load_dwordx4 v[188:191], v[14:15], off
	s_waitcnt vmcnt(0)
	ds_write_b128 v76, v[160:163] offset:0
	ds_write_b128 v76, v[164:167] offset:1024
	ds_write_b128 v76, v[168:171] offset:2048
	ds_write_b128 v76, v[172:175] offset:3072
	ds_write_b128 v76, v[176:179] offset:4096
	ds_write_b128 v76, v[180:183] offset:5120
	ds_write_b128 v76, v[184:187] offset:6144
	ds_write_b128 v76, v[188:191] offset:7168
	global_load_dwordx4 v[160:163], v[16:17], off
	global_load_dwordx4 v[164:167], v[18:19], off
	global_load_dwordx4 v[168:171], v[20:21], off
	global_load_dwordx4 v[172:175], v[22:23], off
	global_load_dwordx4 v[176:179], v[24:25], off
	global_load_dwordx4 v[180:183], v[26:27], off
	global_load_dwordx4 v[184:187], v[28:29], off
	global_load_dwordx4 v[188:191], v[30:31], off
	s_waitcnt vmcnt(0)
	ds_write_b128 v76, v[160:163] offset:8192
	ds_write_b128 v76, v[164:167] offset:9216
	ds_write_b128 v76, v[168:171] offset:10240
	ds_write_b128 v76, v[172:175] offset:11264
	ds_write_b128 v76, v[176:179] offset:12288
	ds_write_b128 v76, v[180:183] offset:13312
	ds_write_b128 v76, v[184:187] offset:14336
	ds_write_b128 v76, v[188:191] offset:15360
	s_waitcnt lgkmcnt(0)
.LBB0_4009:
	v_lshl_add_u64 v[38:39], s[14:15], 0, v[36:37]
	v_add_co_u32_e32 v64, vcc, s13, v38
	v_lshl_add_u64 v[44:45], s[14:15], 0, v[34:35]
	s_nop 0
	v_addc_co_u32_e32 v65, vcc, 0, v39, vcc
	v_add_co_u32_e32 v38, vcc, s26, v38
	v_lshl_add_u64 v[62:63], s[14:15], 0, v[32:33]
	global_load_dword v40, v[62:63], off
	global_load_dwordx4 v[160:163], v34, s[80:81] offset:0
	global_load_dwordx2 v[224:225], v36, s[88:89] offset:0
	global_load_dwordx4 v[164:167], v34, s[80:81] offset:1024
	global_load_dwordx2 v[226:227], v36, s[88:89] offset:512
	global_load_dwordx4 v[168:171], v34, s[80:81] offset:2048
	global_load_dwordx2 v[228:229], v36, s[88:89] offset:1024
	global_load_dwordx4 v[172:175], v34, s[80:81] offset:3072
	global_load_dwordx2 v[230:231], v36, s[88:89] offset:1536
	global_load_dwordx4 v[176:179], v34, s[82:83] offset:0
	global_load_dwordx2 v[232:233], v36, s[88:89] offset:2048
	global_load_dwordx4 v[180:183], v34, s[82:83] offset:1024
	global_load_dwordx2 v[234:235], v36, s[88:89] offset:2560
	global_load_dwordx4 v[184:187], v34, s[82:83] offset:2048
	global_load_dwordx2 v[236:237], v36, s[88:89] offset:3072
	global_load_dwordx4 v[188:191], v34, s[82:83] offset:3072
	global_load_dwordx2 v[238:239], v36, s[88:89] offset:3584
	global_load_dwordx4 v[192:195], v34, s[84:85] offset:0
	global_load_dwordx2 v[240:241], v36, s[90:91] offset:0
	global_load_dwordx4 v[196:199], v34, s[84:85] offset:1024
	global_load_dwordx2 v[242:243], v36, s[90:91] offset:512
	global_load_dwordx4 v[200:203], v34, s[84:85] offset:2048
	global_load_dwordx2 v[244:245], v36, s[90:91] offset:1024
	global_load_dwordx4 v[204:207], v34, s[84:85] offset:3072
	global_load_dwordx2 v[246:247], v36, s[90:91] offset:1536
	global_load_dwordx4 v[208:211], v34, s[86:87] offset:0
	global_load_dwordx2 v[248:249], v36, s[90:91] offset:2048
	global_load_dwordx4 v[212:215], v34, s[86:87] offset:1024
	global_load_dwordx2 v[250:251], v36, s[90:91] offset:2560
	global_load_dwordx4 v[216:219], v34, s[86:87] offset:2048
	global_load_dwordx2 v[252:253], v36, s[90:91] offset:3072
	global_load_dwordx4 v[220:223], v34, s[86:87] offset:3072
	global_load_dwordx2 v[254:255], v36, s[90:91] offset:3584
	s_nop 0
	v_addc_co_u32_e32 v39, vcc, 0, v39, vcc
	v_add_co_u32_e32 v66, vcc, s24, v44
	ds_read_b128 v[54:57], v76 offset:0
	s_nop 0
	v_addc_co_u32_e32 v67, vcc, 0, v45, vcc
	v_add_co_u32_e32 v68, vcc, s25, v44
	v_lshl_add_u64 v[42:43], s[6:7], 0, v[34:35]
	s_nop 0
	v_addc_co_u32_e32 v69, vcc, 0, v45, vcc
	s_waitcnt vmcnt(30)
	s_nop 1
	v_mov_b32_e32 v70, v224
	v_mov_b32_e32 v71, v225
	s_waitcnt vmcnt(31)
	s_nop 1
	v_mov_b32_e32 v58, v160
	v_mov_b32_e32 v59, v161
	v_mov_b32_e32 v60, v162
	v_mov_b32_e32 v61, v163
	s_add_i32 s10, s10, s12
	v_lshl_add_u64 v[32:33], v[32:33], 0, s[4:5]
	v_lshl_add_u64 v[34:35], v[34:35], 0, s[16:17]
	v_lshl_add_u64 v[36:37], v[36:37], 0, s[18:19]
	s_cmpk_gt_i32 s10, 0x3fff
	s_waitcnt vmcnt(32) lgkmcnt(0)
	ds_bpermute_b32 v53, v41, v40
	s_waitcnt lgkmcnt(0)
	v_lshlrev_b32_e32 v62, 16, v70
	v_and_b32_e32 v63, 0xffff0000, v70
	v_lshlrev_b32_e32 v70, 16, v71
	v_and_b32_e32 v71, 0xffff0000, v71
	s_waitcnt lgkmcnt(0)
	v_add_f32_e32 v40, v40, v53
	ds_bpermute_b32 v53, v46, v40
	s_waitcnt lgkmcnt(0)
	v_add_f32_e32 v40, v40, v53
	ds_bpermute_b32 v53, v47, v40
	s_waitcnt lgkmcnt(0)
	v_add_f32_e32 v40, v40, v53
	ds_bpermute_b32 v53, v48, v40
	s_waitcnt lgkmcnt(0)
	v_add_f32_e32 v40, v40, v53
	ds_bpermute_b32 v53, v49, v40
	s_waitcnt lgkmcnt(0)
	v_add_f32_e32 v40, v40, v53
	ds_bpermute_b32 v53, v50, v40
	s_waitcnt lgkmcnt(0)
	v_add_f32_e32 v40, v40, v53
	v_fmamk_f32 v40, v40, 0x39800000, v51
	v_mul_f32_e32 v53, 0x4f800000, v40
	v_cmp_gt_f32_e32 vcc, s11, v40
	s_nop 1
	v_cndmask_b32_e32 v40, v40, v53, vcc
	v_sqrt_f32_e32 v53, v40
	s_nop 0
	v_add_u32_e32 v72, -1, v53
	v_add_u32_e32 v73, 1, v53
	v_fma_f32 v74, -v72, v53, v40
	v_fma_f32 v75, -v73, v53, v40
	v_cmp_ge_f32_e64 s[2:3], 0, v74
	s_nop 1
	v_cndmask_b32_e64 v53, v53, v72, s[2:3]
	v_cmp_lt_f32_e64 s[2:3], 0, v75
	s_nop 1
	v_cndmask_b32_e64 v53, v53, v73, s[2:3]
	v_mul_f32_e32 v72, 0x37800000, v53
	v_cndmask_b32_e32 v53, v53, v72, vcc
	v_cmp_class_f32_e32 vcc, v40, v52
	s_nop 1
	v_cndmask_b32_e32 v40, v53, v40, vcc
	v_div_scale_f32 v53, s[2:3], v40, v40, 1.0
	v_rcp_f32_e32 v73, v53
	v_div_scale_f32 v72, vcc, 1.0, v40, 1.0
	v_fma_f32 v74, -v53, v73, 1.0
	v_fmac_f32_e32 v73, v74, v73
	v_mul_f32_e32 v74, v72, v73
	v_fma_f32 v75, -v53, v74, v72
	v_fmac_f32_e32 v74, v75, v73
	v_fma_f32 v53, -v53, v74, v72
	v_div_fmas_f32 v53, v53, v73, v74
	v_div_fixup_f32 v40, v53, v40, 1.0
	v_pk_mul_f32 v[62:63], v[40:41], v[62:63] op_sel_hi:[0,1]
	v_pk_mul_f32 v[70:71], v[40:41], v[70:71] op_sel_hi:[0,1]
	s_waitcnt lgkmcnt(0)
	v_pk_fma_f32 v[54:55], v[54:55], v[62:63], v[58:59]
	v_pk_fma_f32 v[56:57], v[56:57], v[70:71], v[60:61]
	global_store_dwordx4 v[42:43], v[54:57], off
	s_waitcnt vmcnt(29)
	s_nop 1
	v_mov_b32_e32 v62, v226
	v_mov_b32_e32 v63, v227
	s_nop 0
	s_waitcnt vmcnt(30)
	s_nop 1
	v_mov_b32_e32 v54, v164
	v_mov_b32_e32 v55, v165
	v_mov_b32_e32 v56, v166
	v_mov_b32_e32 v57, v167
	ds_read_b128 v[58:61], v76 offset:1024
	s_waitcnt lgkmcnt(0)
	v_lshlrev_b32_e32 v70, 16, v62
	v_and_b32_e32 v71, 0xffff0000, v62
	v_lshlrev_b32_e32 v62, 16, v63
	v_and_b32_e32 v63, 0xffff0000, v63
	v_pk_mul_f32 v[70:71], v[40:41], v[70:71] op_sel_hi:[0,1]
	v_pk_mul_f32 v[62:63], v[40:41], v[62:63] op_sel_hi:[0,1]
	s_waitcnt lgkmcnt(0)
	v_pk_fma_f32 v[54:55], v[58:59], v[70:71], v[54:55]
	v_pk_fma_f32 v[56:57], v[60:61], v[62:63], v[56:57]
	global_store_dwordx4 v[42:43], v[54:57], off offset:1024
	s_waitcnt vmcnt(28)
	s_nop 1
	v_mov_b32_e32 v62, v228
	v_mov_b32_e32 v63, v229
	s_nop 0
	s_waitcnt vmcnt(29)
	s_nop 1
	v_mov_b32_e32 v54, v168
	v_mov_b32_e32 v55, v169
	v_mov_b32_e32 v56, v170
	v_mov_b32_e32 v57, v171
	ds_read_b128 v[58:61], v76 offset:2048
	s_waitcnt lgkmcnt(0)
	v_lshlrev_b32_e32 v70, 16, v62
	v_and_b32_e32 v71, 0xffff0000, v62
	v_lshlrev_b32_e32 v62, 16, v63
	v_and_b32_e32 v63, 0xffff0000, v63
	v_pk_mul_f32 v[70:71], v[40:41], v[70:71] op_sel_hi:[0,1]
	v_pk_mul_f32 v[62:63], v[40:41], v[62:63] op_sel_hi:[0,1]
	s_waitcnt lgkmcnt(0)
	v_pk_fma_f32 v[54:55], v[58:59], v[70:71], v[54:55]
	v_pk_fma_f32 v[56:57], v[60:61], v[62:63], v[56:57]
	global_store_dwordx4 v[42:43], v[54:57], off offset:2048
	s_waitcnt vmcnt(27)
	s_nop 1
	v_mov_b32_e32 v62, v230
	v_mov_b32_e32 v63, v231
	s_nop 0
	s_waitcnt vmcnt(28)
	s_nop 1
	v_mov_b32_e32 v54, v172
	v_mov_b32_e32 v55, v173
	v_mov_b32_e32 v56, v174
	v_mov_b32_e32 v57, v175
	ds_read_b128 v[58:61], v76 offset:3072
	s_waitcnt lgkmcnt(0)
	v_lshlrev_b32_e32 v66, 16, v62
	v_and_b32_e32 v67, 0xffff0000, v62
	v_lshlrev_b32_e32 v62, 16, v63
	v_and_b32_e32 v63, 0xffff0000, v63
	v_pk_mul_f32 v[66:67], v[40:41], v[66:67] op_sel_hi:[0,1]
	v_pk_mul_f32 v[62:63], v[40:41], v[62:63] op_sel_hi:[0,1]
	s_waitcnt lgkmcnt(0)
	v_pk_fma_f32 v[54:55], v[58:59], v[66:67], v[54:55]
	v_pk_fma_f32 v[56:57], v[60:61], v[62:63], v[56:57]
	global_store_dwordx4 v[42:43], v[54:57], off offset:3072
	s_waitcnt vmcnt(26)
	s_nop 1
	v_mov_b32_e32 v62, v232
	v_mov_b32_e32 v63, v233
	s_nop 0
	s_waitcnt vmcnt(27)
	s_nop 1
	v_mov_b32_e32 v54, v176
	v_mov_b32_e32 v55, v177
	v_mov_b32_e32 v56, v178
	v_mov_b32_e32 v57, v179
	ds_read_b128 v[58:61], v76 offset:4096
	v_add_co_u32_e32 v66, vcc, s22, v42
	s_waitcnt lgkmcnt(0)
	v_lshlrev_b32_e32 v70, 16, v62
	v_and_b32_e32 v71, 0xffff0000, v62
	v_lshlrev_b32_e32 v62, 16, v63
	v_and_b32_e32 v63, 0xffff0000, v63
	v_pk_mul_f32 v[70:71], v[40:41], v[70:71] op_sel_hi:[0,1]
	v_pk_mul_f32 v[62:63], v[40:41], v[62:63] op_sel_hi:[0,1]
	v_addc_co_u32_e32 v67, vcc, 0, v43, vcc
	s_waitcnt lgkmcnt(0)
	v_pk_fma_f32 v[54:55], v[58:59], v[70:71], v[54:55]
	v_pk_fma_f32 v[56:57], v[60:61], v[62:63], v[56:57]
	global_store_dwordx4 v[66:67], v[54:57], off offset:-4096
	s_waitcnt vmcnt(25)
	s_nop 1
	v_mov_b32_e32 v62, v234
	v_mov_b32_e32 v63, v235
	s_nop 0
	s_waitcnt vmcnt(26)
	s_nop 1
	v_mov_b32_e32 v54, v180
	v_mov_b32_e32 v55, v181
	v_mov_b32_e32 v56, v182
	v_mov_b32_e32 v57, v183
	ds_read_b128 v[58:61], v76 offset:5120
	v_add_co_u32_e32 v70, vcc, s21, v42
	s_waitcnt lgkmcnt(0)
	v_lshlrev_b32_e32 v72, 16, v62
	v_and_b32_e32 v73, 0xffff0000, v62
	v_lshlrev_b32_e32 v62, 16, v63
	v_and_b32_e32 v63, 0xffff0000, v63
	v_pk_mul_f32 v[72:73], v[40:41], v[72:73] op_sel_hi:[0,1]
	v_pk_mul_f32 v[62:63], v[40:41], v[62:63] op_sel_hi:[0,1]
	v_addc_co_u32_e32 v71, vcc, 0, v43, vcc
	s_waitcnt lgkmcnt(0)
	v_pk_fma_f32 v[54:55], v[58:59], v[72:73], v[54:55]
	v_pk_fma_f32 v[56:57], v[60:61], v[62:63], v[56:57]
	global_store_dwordx4 v[70:71], v[54:57], off offset:1024
	s_waitcnt vmcnt(24)
	s_nop 1
	v_mov_b32_e32 v62, v236
	v_mov_b32_e32 v63, v237
	s_nop 0
	s_waitcnt vmcnt(25)
	s_nop 1
	v_mov_b32_e32 v54, v184
	v_mov_b32_e32 v55, v185
	v_mov_b32_e32 v56, v186
	v_mov_b32_e32 v57, v187
	ds_read_b128 v[58:61], v76 offset:6144
	s_waitcnt lgkmcnt(0)
	v_lshlrev_b32_e32 v72, 16, v62
	v_and_b32_e32 v73, 0xffff0000, v62
	v_lshlrev_b32_e32 v62, 16, v63
	v_and_b32_e32 v63, 0xffff0000, v63
	v_pk_mul_f32 v[72:73], v[40:41], v[72:73] op_sel_hi:[0,1]
	v_pk_mul_f32 v[62:63], v[40:41], v[62:63] op_sel_hi:[0,1]
	s_waitcnt lgkmcnt(0)
	v_pk_fma_f32 v[54:55], v[58:59], v[72:73], v[54:55]
	v_pk_fma_f32 v[56:57], v[60:61], v[62:63], v[56:57]
	global_store_dwordx4 v[70:71], v[54:57], off offset:2048
	s_waitcnt vmcnt(23)
	s_nop 1
	v_mov_b32_e32 v62, v238
	v_mov_b32_e32 v63, v239
	s_nop 0
	s_waitcnt vmcnt(24)
	s_nop 1
	v_mov_b32_e32 v54, v188
	v_mov_b32_e32 v55, v189
	v_mov_b32_e32 v56, v190
	v_mov_b32_e32 v57, v191
	ds_read_b128 v[58:61], v76 offset:7168
	v_add_co_u32_e32 v64, vcc, s28, v44
	s_waitcnt lgkmcnt(0)
	v_lshlrev_b32_e32 v68, 16, v62
	v_and_b32_e32 v69, 0xffff0000, v62
	v_lshlrev_b32_e32 v62, 16, v63
	v_and_b32_e32 v63, 0xffff0000, v63
	v_pk_mul_f32 v[68:69], v[40:41], v[68:69] op_sel_hi:[0,1]
	v_pk_mul_f32 v[62:63], v[40:41], v[62:63] op_sel_hi:[0,1]
	s_waitcnt lgkmcnt(0)
	v_pk_fma_f32 v[54:55], v[58:59], v[68:69], v[54:55]
	v_pk_fma_f32 v[56:57], v[60:61], v[62:63], v[56:57]
	global_store_dwordx4 v[70:71], v[54:57], off offset:3072
	v_addc_co_u32_e32 v65, vcc, 0, v45, vcc
	s_waitcnt vmcnt(22)
	s_nop 1
	v_mov_b32_e32 v62, v240
	v_mov_b32_e32 v63, v241
	s_waitcnt vmcnt(23)
	s_nop 1
	v_mov_b32_e32 v54, v192
	v_mov_b32_e32 v55, v193
	v_mov_b32_e32 v56, v194
	v_mov_b32_e32 v57, v195
	ds_read_b128 v[58:61], v76 offset:8192
	v_add_co_u32_e32 v44, vcc, s27, v44
	s_waitcnt lgkmcnt(0)
	v_lshlrev_b32_e32 v68, 16, v62
	v_and_b32_e32 v69, 0xffff0000, v62
	v_lshlrev_b32_e32 v62, 16, v63
	v_and_b32_e32 v63, 0xffff0000, v63
	v_pk_mul_f32 v[68:69], v[40:41], v[68:69] op_sel_hi:[0,1]
	v_pk_mul_f32 v[62:63], v[40:41], v[62:63] op_sel_hi:[0,1]
	s_waitcnt lgkmcnt(0)
	v_pk_fma_f32 v[54:55], v[58:59], v[68:69], v[54:55]
	v_pk_fma_f32 v[56:57], v[60:61], v[62:63], v[56:57]
	global_store_dwordx4 v[66:67], v[54:57], off
	v_addc_co_u32_e32 v45, vcc, 0, v45, vcc
	s_waitcnt vmcnt(21)
	s_nop 1
	v_mov_b32_e32 v62, v242
	v_mov_b32_e32 v63, v243
	s_waitcnt vmcnt(22)
	s_nop 1
	v_mov_b32_e32 v54, v196
	v_mov_b32_e32 v55, v197
	v_mov_b32_e32 v56, v198
	v_mov_b32_e32 v57, v199
	ds_read_b128 v[58:61], v76 offset:9216
	s_waitcnt lgkmcnt(0)
	v_lshlrev_b32_e32 v68, 16, v62
	v_and_b32_e32 v69, 0xffff0000, v62
	v_lshlrev_b32_e32 v62, 16, v63
	v_and_b32_e32 v63, 0xffff0000, v63
	v_pk_mul_f32 v[68:69], v[40:41], v[68:69] op_sel_hi:[0,1]
	v_pk_mul_f32 v[62:63], v[40:41], v[62:63] op_sel_hi:[0,1]
	s_waitcnt lgkmcnt(0)
	v_pk_fma_f32 v[54:55], v[58:59], v[68:69], v[54:55]
	v_pk_fma_f32 v[56:57], v[60:61], v[62:63], v[56:57]
	global_store_dwordx4 v[66:67], v[54:57], off offset:1024
	s_waitcnt vmcnt(20)
	s_nop 1
	v_mov_b32_e32 v62, v244
	v_mov_b32_e32 v63, v245
	s_nop 0
	s_waitcnt vmcnt(21)
	s_nop 1
	v_mov_b32_e32 v54, v200
	v_mov_b32_e32 v55, v201
	v_mov_b32_e32 v56, v202
	v_mov_b32_e32 v57, v203
	ds_read_b128 v[58:61], v76 offset:10240
	s_waitcnt lgkmcnt(0)
	v_lshlrev_b32_e32 v68, 16, v62
	v_and_b32_e32 v69, 0xffff0000, v62
	v_lshlrev_b32_e32 v62, 16, v63
	v_and_b32_e32 v63, 0xffff0000, v63
	v_pk_mul_f32 v[68:69], v[40:41], v[68:69] op_sel_hi:[0,1]
	v_pk_mul_f32 v[62:63], v[40:41], v[62:63] op_sel_hi:[0,1]
	s_waitcnt lgkmcnt(0)
	v_pk_fma_f32 v[54:55], v[58:59], v[68:69], v[54:55]
	v_pk_fma_f32 v[56:57], v[60:61], v[62:63], v[56:57]
	global_store_dwordx4 v[66:67], v[54:57], off offset:2048
	s_waitcnt vmcnt(19)
	s_nop 1
	v_mov_b32_e32 v62, v246
	v_mov_b32_e32 v63, v247
	s_nop 0
	s_waitcnt vmcnt(20)
	s_nop 1
	v_mov_b32_e32 v54, v204
	v_mov_b32_e32 v55, v205
	v_mov_b32_e32 v56, v206
	v_mov_b32_e32 v57, v207
	ds_read_b128 v[58:61], v76 offset:11264
	s_waitcnt lgkmcnt(0)
	v_lshlrev_b32_e32 v44, 16, v62
	v_and_b32_e32 v45, 0xffff0000, v62
	v_lshlrev_b32_e32 v62, 16, v63
	v_and_b32_e32 v63, 0xffff0000, v63
	v_pk_mul_f32 v[44:45], v[40:41], v[44:45] op_sel_hi:[0,1]
	v_pk_mul_f32 v[62:63], v[40:41], v[62:63] op_sel_hi:[0,1]
	s_waitcnt lgkmcnt(0)
	v_pk_fma_f32 v[54:55], v[58:59], v[44:45], v[54:55]
	v_pk_fma_f32 v[56:57], v[60:61], v[62:63], v[56:57]
	global_store_dwordx4 v[66:67], v[54:57], off offset:3072
	s_waitcnt vmcnt(18)
	s_nop 1
	v_mov_b32_e32 v44, v248
	v_mov_b32_e32 v45, v249
	s_nop 0
	s_waitcnt vmcnt(19)
	s_nop 1
	v_mov_b32_e32 v54, v208
	v_mov_b32_e32 v55, v209
	v_mov_b32_e32 v56, v210
	v_mov_b32_e32 v57, v211
	ds_read_b128 v[58:61], v76 offset:12288
	v_add_co_u32_e32 v62, vcc, s23, v42
	s_waitcnt lgkmcnt(0)
	v_lshlrev_b32_e32 v42, 16, v44
	v_addc_co_u32_e32 v63, vcc, 0, v43, vcc
	v_and_b32_e32 v43, 0xffff0000, v44
	v_lshlrev_b32_e32 v44, 16, v45
	v_and_b32_e32 v45, 0xffff0000, v45
	v_pk_mul_f32 v[42:43], v[40:41], v[42:43] op_sel_hi:[0,1]
	v_pk_mul_f32 v[44:45], v[40:41], v[44:45] op_sel_hi:[0,1]
	s_waitcnt lgkmcnt(0)
	v_pk_fma_f32 v[42:43], v[58:59], v[42:43], v[54:55]
	v_pk_fma_f32 v[44:45], v[60:61], v[44:45], v[56:57]
	global_store_dwordx4 v[62:63], v[42:45], off
	s_waitcnt vmcnt(17)
	s_nop 1
	v_mov_b32_e32 v58, v250
	v_mov_b32_e32 v59, v251
	s_nop 0
	s_waitcnt vmcnt(18)
	s_nop 1
	v_mov_b32_e32 v42, v212
	v_mov_b32_e32 v43, v213
	v_mov_b32_e32 v44, v214
	v_mov_b32_e32 v45, v215
	ds_read_b128 v[54:57], v76 offset:13312
	s_waitcnt lgkmcnt(0)
	v_lshlrev_b32_e32 v60, 16, v58
	v_and_b32_e32 v61, 0xffff0000, v58
	v_lshlrev_b32_e32 v58, 16, v59
	v_and_b32_e32 v59, 0xffff0000, v59
	v_pk_mul_f32 v[60:61], v[40:41], v[60:61] op_sel_hi:[0,1]
	v_pk_mul_f32 v[58:59], v[40:41], v[58:59] op_sel_hi:[0,1]
	s_waitcnt lgkmcnt(0)
	v_pk_fma_f32 v[42:43], v[54:55], v[60:61], v[42:43]
	v_pk_fma_f32 v[44:45], v[56:57], v[58:59], v[44:45]
	global_store_dwordx4 v[62:63], v[42:45], off offset:1024
	s_waitcnt vmcnt(16)
	s_nop 1
	v_mov_b32_e32 v58, v252
	v_mov_b32_e32 v59, v253
	s_nop 0
	s_waitcnt vmcnt(17)
	s_nop 1
	v_mov_b32_e32 v42, v216
	v_mov_b32_e32 v43, v217
	v_mov_b32_e32 v44, v218
	v_mov_b32_e32 v45, v219
	ds_read_b128 v[54:57], v76 offset:14336
	s_waitcnt lgkmcnt(0)
	v_lshlrev_b32_e32 v60, 16, v58
	v_and_b32_e32 v61, 0xffff0000, v58
	v_lshlrev_b32_e32 v58, 16, v59
	v_and_b32_e32 v59, 0xffff0000, v59
	v_pk_mul_f32 v[60:61], v[40:41], v[60:61] op_sel_hi:[0,1]
	v_pk_mul_f32 v[58:59], v[40:41], v[58:59] op_sel_hi:[0,1]
	s_waitcnt lgkmcnt(0)
	v_pk_fma_f32 v[42:43], v[54:55], v[60:61], v[42:43]
	v_pk_fma_f32 v[44:45], v[56:57], v[58:59], v[44:45]
	global_store_dwordx4 v[62:63], v[42:45], off offset:2048
	s_waitcnt vmcnt(15)
	s_nop 1
	v_mov_b32_e32 v58, v254
	v_mov_b32_e32 v59, v255
	s_nop 0
	s_waitcnt vmcnt(16)
	s_nop 1
	v_mov_b32_e32 v42, v220
	v_mov_b32_e32 v43, v221
	v_mov_b32_e32 v44, v222
	v_mov_b32_e32 v45, v223
	ds_read_b128 v[54:57], v76 offset:15360
	s_waitcnt lgkmcnt(0)
	v_lshlrev_b32_e32 v38, 16, v58
	v_and_b32_e32 v39, 0xffff0000, v58
	v_lshlrev_b32_e32 v58, 16, v59
	v_and_b32_e32 v59, 0xffff0000, v59
	v_pk_mul_f32 v[38:39], v[40:41], v[38:39] op_sel_hi:[0,1]
	v_pk_mul_f32 v[58:59], v[40:41], v[58:59] op_sel_hi:[0,1]
	s_waitcnt lgkmcnt(0)
	v_pk_fma_f32 v[42:43], v[54:55], v[38:39], v[42:43]
	v_pk_fma_f32 v[44:45], v[56:57], v[58:59], v[44:45]
	global_store_dwordx4 v[62:63], v[42:45], off offset:3072
	s_cbranch_scc0 .LBB0_4009
